# add hand-written row-pair-packed f32 compute loop for the Gated DeltaNet scan (waves 0-3)
# speedup vs baseline: 1.0382x; 1.0127x over previous
.LBB0_466:
	s_and_b64 vcc, exec, s[0:1]
	s_cbranch_vccz .LBB0_508
	s_bfe_u32 s10, s2, 0x20004
	s_bfe_u32 s21, s2, 0x20002
	s_and_b32 s20, s2, 3
	s_cmp_lt_u32 s2, 64
	s_cselect_b64 s[4:5], -1, 0
	s_cmp_gt_u32 s2, 63
	s_movk_i32 s6, 0x100
	s_cselect_b64 s[0:1], -1, 0
	v_cmp_gt_u32_e32 vcc, s6, v164
	s_and_saveexec_b64 s[6:7], vcc
	s_xor_b64 s[6:7], exec, s[6:7]
	s_cbranch_execz .LBB0_473
	s_setprio 3
	s_lshr_b32 s8, s2, 6
	s_bfe_u32 s9, s2, 0x20004
	s_bfe_u32 s11, s2, 0x20002
	s_and_b32 s14, s2, 3
	s_add_u32 s22, s28, 0xdc00000
	s_addc_u32 s23, s29, 0
	s_cmp_eq_u32 s8, 0
	s_cselect_b32 s22, s22, s26
	s_cselect_b32 s23, s23, s27
	s_mov_b32 s52, 0x8000
	s_mov_b32 s53, 0
	s_mov_b32 s55, 1
	s_lshl_b32 s56, s9, 12
	s_cmp_eq_u32 s8, 0
	s_cbranch_scc1 .Lgc_fwd
	s_mov_b32 s52, 0xffff8000
	s_mov_b32 s53, -1
	s_mov_b32 s55, -1
	s_add_u32 s56, s56, 0xfff
.Lgc_fwd:
	s_lshl_b32 s57, s14, 5
	s_lshl_b32 s58, s11, 7
	s_add_u32 s57, s57, s58
	s_add_u32 s57, s57, 0x200
	v_and_b32_e32 v106, 15, v164
	v_lshrrev_b32_e32 v107, 4, v164
	v_lshrrev_b32_e32 v100, 3, v106
	v_lshlrev_b32_e32 v100, 4, v100
	v_lshl_add_u32 v100, v106, 5, v100
	v_lshlrev_b32_e32 v101, 3, v107
	v_lshlrev_b32_e32 v102, 3, v164
	v_add_u32_e32 v102, 38144, v102
	v_lshlrev_b32_e32 v103, 7, v164
	v_add_u32_e32 v103, 38144, v103
	v_bfe_u32 v116, v164, 1, 3
	v_lshl_or_b32 v103, v116, 4, v103
	v_mov_b32_e32 v117, 0
	v_mul_lo_u32 v118, v107, s55
	v_add_u32_e32 v118, s56, v118
	v_lshlrev_b32_e32 v118, 11, v118
	v_lshl_add_u32 v119, v106, 1, s57
	v_lshl_add_u32 v118, v119, 1, v118
	v_mov_b32_e32 v119, 0
	v_lshl_add_u64 v[104:105], v[118:119], 0, s[22:23]
	v_mov_b32_e32 v2, 0
	v_mov_b32_e32 v3, 0
	v_mov_b32_e32 v4, 0
	v_mov_b32_e32 v5, 0
	v_mov_b32_e32 v6, 0
	v_mov_b32_e32 v7, 0
	v_mov_b32_e32 v8, 0
	v_mov_b32_e32 v9, 0
	v_mov_b32_e32 v10, 0
	v_mov_b32_e32 v11, 0
	v_mov_b32_e32 v12, 0
	v_mov_b32_e32 v13, 0
	v_mov_b32_e32 v14, 0
	v_mov_b32_e32 v15, 0
	v_mov_b32_e32 v16, 0
	v_mov_b32_e32 v17, 0
	s_mov_b32 s16, 0
	s_barrier
.Lgc_loop:
	ds_read_b128 v[18:21], v100 offset:0
	ds_read_b128 v[22:25], v100 offset:16
	ds_read_b128 v[26:29], v100 offset:528
	ds_read_b128 v[30:33], v100 offset:544
	ds_read_b64 v[34:35], v101 offset:33792
	ds_read_b64 v[36:37], v117 offset:37888
	ds_read_b128 v[38:41], v100 offset:1056
	ds_read_b128 v[42:45], v100 offset:1072
	ds_read_b128 v[46:49], v100 offset:1584
	ds_read_b128 v[50:53], v100 offset:1600
	ds_read_b64 v[54:55], v101 offset:33920
	ds_read_b64 v[56:57], v117 offset:37896
	ds_read_b128 v[58:61], v103 offset:32768
	v_xor_b32_e32 v116, 16, v103
	ds_read_b128 v[62:65], v116 offset:32768
	v_xor_b32_e32 v116, 32, v103
	ds_read_b128 v[66:69], v116 offset:32768
	v_xor_b32_e32 v116, 48, v103
	ds_read_b128 v[70:73], v116 offset:32768
	v_xor_b32_e32 v116, 64, v103
	ds_read_b128 v[74:77], v116 offset:32768
	v_xor_b32_e32 v116, 80, v103
	ds_read_b128 v[78:81], v116 offset:32768
	v_xor_b32_e32 v116, 96, v103
	ds_read_b128 v[82:85], v116 offset:32768
	v_xor_b32_e32 v116, 112, v103
	ds_read_b128 v[86:89], v116 offset:32768
	s_waitcnt lgkmcnt(0)
	v_pk_add_f32 v[58:59], v[58:59], v[60:61]
	v_pk_add_f32 v[62:63], v[62:63], v[64:65]
	v_pk_add_f32 v[66:67], v[66:67], v[68:69]
	v_pk_add_f32 v[70:71], v[70:71], v[72:73]
	v_pk_add_f32 v[74:75], v[74:75], v[76:77]
	v_pk_add_f32 v[78:79], v[78:79], v[80:81]
	v_pk_add_f32 v[82:83], v[82:83], v[84:85]
	v_pk_add_f32 v[86:87], v[86:87], v[88:89]
	v_pk_add_f32 v[58:59], v[58:59], v[62:63]
	v_pk_add_f32 v[66:67], v[66:67], v[70:71]
	v_pk_add_f32 v[74:75], v[74:75], v[78:79]
	v_pk_add_f32 v[82:83], v[82:83], v[86:87]
	v_pk_add_f32 v[58:59], v[58:59], v[66:67]
	v_pk_add_f32 v[74:75], v[74:75], v[82:83]
	s_nop 0
	v_pk_add_f32 v[58:59], v[58:59], v[74:75]
	s_nop 0
	v_cvt_pk_bf16_f32 v90, v58, v59
	s_cmp_eq_u32 s16, 0
	s_cselect_b64 s[46:47], 0, -1
	s_cselect_b64 s[50:51], 0, s[52:53]
	s_mov_b64 exec, s[46:47]
	global_store_dword v[104:105], v90, off
	s_mov_b64 exec, -1
	v_lshl_add_u64 v[104:105], v[104:105], 0, s[50:51]
	v_pk_mul_f32 v[94:95], v[18:19], v[2:3] op_sel:[0,0] op_sel_hi:[0,1]
	v_pk_mul_f32 v[96:97], v[18:19], v[4:5] op_sel:[1,0] op_sel_hi:[1,1]
	v_pk_fma_f32 v[94:95], v[20:21], v[6:7], v[94:95] op_sel:[0,0,0] op_sel_hi:[0,1,1]
	v_pk_fma_f32 v[96:97], v[20:21], v[8:9], v[96:97] op_sel:[1,0,0] op_sel_hi:[1,1,1]
	v_pk_fma_f32 v[94:95], v[22:23], v[10:11], v[94:95] op_sel:[0,0,0] op_sel_hi:[0,1,1]
	v_pk_fma_f32 v[96:97], v[22:23], v[12:13], v[96:97] op_sel:[1,0,0] op_sel_hi:[1,1,1]
	v_pk_fma_f32 v[94:95], v[24:25], v[14:15], v[94:95] op_sel:[0,0,0] op_sel_hi:[0,1,1]
	v_pk_fma_f32 v[96:97], v[24:25], v[16:17], v[96:97] op_sel:[1,0,0] op_sel_hi:[1,1,1]
	s_nop 0
	v_pk_add_f32 v[94:95], v[94:95], v[96:97]
	s_nop 1
	v_add_f32_dpp v94, v94, v94 quad_perm:[1,0,3,2] row_mask:0xf bank_mask:0xf
	v_add_f32_dpp v95, v95, v95 quad_perm:[1,0,3,2] row_mask:0xf bank_mask:0xf
	s_nop 0
	v_add_f32_dpp v94, v94, v94 quad_perm:[2,3,0,1] row_mask:0xf bank_mask:0xf
	v_add_f32_dpp v95, v95, v95 quad_perm:[2,3,0,1] row_mask:0xf bank_mask:0xf
	s_nop 0
	v_add_f32_dpp v94, v94, v94 row_half_mirror row_mask:0xf bank_mask:0xf
	v_add_f32_dpp v95, v95, v95 row_half_mirror row_mask:0xf bank_mask:0xf
	s_nop 0
	v_add_f32_dpp v94, v94, v94 row_mirror row_mask:0xf bank_mask:0xf
	v_add_f32_dpp v95, v95, v95 row_mirror row_mask:0xf bank_mask:0xf
	v_pk_fma_f32 v[98:99], v[36:37], v[94:95], v[34:35] op_sel:[1,0,0] op_sel_hi:[1,1,1] neg_lo:[1,0,0] neg_hi:[1,0,0]
	s_nop 0
	v_pk_mul_f32 v[106:107], v[36:37], v[98:99] op_sel:[0,0] op_sel_hi:[0,1]
	ds_read_b128 v[58:61], v100 offset:2112
	ds_read_b128 v[62:65], v100 offset:2128
	ds_read_b128 v[66:69], v100 offset:2640
	ds_read_b128 v[70:73], v100 offset:2656
	ds_read_b64 v[74:75], v101 offset:34048
	ds_read_b64 v[76:77], v117 offset:37904
	v_pk_mul_f32 v[78:79], v[18:19], v[106:107] op_sel:[0,0] op_sel_hi:[0,1]
	v_pk_mul_f32 v[80:81], v[18:19], v[106:107] op_sel:[1,0] op_sel_hi:[1,1]
	v_pk_mul_f32 v[82:83], v[20:21], v[106:107] op_sel:[0,0] op_sel_hi:[0,1]
	v_pk_mul_f32 v[84:85], v[20:21], v[106:107] op_sel:[1,0] op_sel_hi:[1,1]
	v_pk_fma_f32 v[2:3], v[2:3], v[36:37], v[78:79] op_sel:[0,1,0] op_sel_hi:[1,1,1]
	v_pk_fma_f32 v[4:5], v[4:5], v[36:37], v[80:81] op_sel:[0,1,0] op_sel_hi:[1,1,1]
	v_pk_fma_f32 v[6:7], v[6:7], v[36:37], v[82:83] op_sel:[0,1,0] op_sel_hi:[1,1,1]
	v_pk_fma_f32 v[8:9], v[8:9], v[36:37], v[84:85] op_sel:[0,1,0] op_sel_hi:[1,1,1]
	v_pk_mul_f32 v[86:87], v[22:23], v[106:107] op_sel:[0,0] op_sel_hi:[0,1]
	v_pk_mul_f32 v[88:89], v[22:23], v[106:107] op_sel:[1,0] op_sel_hi:[1,1]
	v_pk_mul_f32 v[90:91], v[24:25], v[106:107] op_sel:[0,0] op_sel_hi:[0,1]
	v_pk_mul_f32 v[92:93], v[24:25], v[106:107] op_sel:[1,0] op_sel_hi:[1,1]
	v_pk_fma_f32 v[10:11], v[10:11], v[36:37], v[86:87] op_sel:[0,1,0] op_sel_hi:[1,1,1]
	v_pk_fma_f32 v[12:13], v[12:13], v[36:37], v[88:89] op_sel:[0,1,0] op_sel_hi:[1,1,1]
	v_pk_fma_f32 v[14:15], v[14:15], v[36:37], v[90:91] op_sel:[0,1,0] op_sel_hi:[1,1,1]
	v_pk_fma_f32 v[16:17], v[16:17], v[36:37], v[92:93] op_sel:[0,1,0] op_sel_hi:[1,1,1]
	v_pk_mul_f32 v[94:95], v[38:39], v[2:3] op_sel:[0,0] op_sel_hi:[0,1]
	v_pk_mul_f32 v[96:97], v[38:39], v[4:5] op_sel:[1,0] op_sel_hi:[1,1]
	v_pk_fma_f32 v[94:95], v[40:41], v[6:7], v[94:95] op_sel:[0,0,0] op_sel_hi:[0,1,1]
	v_pk_fma_f32 v[96:97], v[40:41], v[8:9], v[96:97] op_sel:[1,0,0] op_sel_hi:[1,1,1]
	v_pk_fma_f32 v[94:95], v[42:43], v[10:11], v[94:95] op_sel:[0,0,0] op_sel_hi:[0,1,1]
	v_pk_fma_f32 v[96:97], v[42:43], v[12:13], v[96:97] op_sel:[1,0,0] op_sel_hi:[1,1,1]
	v_pk_fma_f32 v[94:95], v[44:45], v[14:15], v[94:95] op_sel:[0,0,0] op_sel_hi:[0,1,1]
	v_pk_fma_f32 v[96:97], v[44:45], v[16:17], v[96:97] op_sel:[1,0,0] op_sel_hi:[1,1,1]
	v_pk_mul_f32 v[108:109], v[26:27], v[2:3] op_sel:[0,0] op_sel_hi:[0,1]
	v_pk_add_f32 v[94:95], v[94:95], v[96:97]
	v_pk_mul_f32 v[110:111], v[26:27], v[4:5] op_sel:[1,0] op_sel_hi:[1,1]
	v_pk_fma_f32 v[108:109], v[28:29], v[6:7], v[108:109] op_sel:[0,0,0] op_sel_hi:[0,1,1]
	v_add_f32_dpp v94, v94, v94 quad_perm:[1,0,3,2] row_mask:0xf bank_mask:0xf
	v_add_f32_dpp v95, v95, v95 quad_perm:[1,0,3,2] row_mask:0xf bank_mask:0xf
	v_pk_fma_f32 v[110:111], v[28:29], v[8:9], v[110:111] op_sel:[1,0,0] op_sel_hi:[1,1,1]
	v_add_f32_dpp v94, v94, v94 quad_perm:[2,3,0,1] row_mask:0xf bank_mask:0xf
	v_add_f32_dpp v95, v95, v95 quad_perm:[2,3,0,1] row_mask:0xf bank_mask:0xf
	v_pk_fma_f32 v[108:109], v[30:31], v[10:11], v[108:109] op_sel:[0,0,0] op_sel_hi:[0,1,1]
	v_add_f32_dpp v94, v94, v94 row_half_mirror row_mask:0xf bank_mask:0xf
	v_add_f32_dpp v95, v95, v95 row_half_mirror row_mask:0xf bank_mask:0xf
	v_pk_fma_f32 v[110:111], v[30:31], v[12:13], v[110:111] op_sel:[1,0,0] op_sel_hi:[1,1,1]
	v_add_f32_dpp v94, v94, v94 row_mirror row_mask:0xf bank_mask:0xf
	v_add_f32_dpp v95, v95, v95 row_mirror row_mask:0xf bank_mask:0xf
	v_pk_fma_f32 v[108:109], v[32:33], v[14:15], v[108:109] op_sel:[0,0,0] op_sel_hi:[0,1,1]
	v_pk_fma_f32 v[110:111], v[32:33], v[16:17], v[110:111] op_sel:[1,0,0] op_sel_hi:[1,1,1]
	s_nop 0
	v_pk_add_f32 v[108:109], v[108:109], v[110:111]
	v_pk_fma_f32 v[98:99], v[56:57], v[94:95], v[54:55] op_sel:[1,0,0] op_sel_hi:[1,1,1] neg_lo:[1,0,0] neg_hi:[1,0,0]
	s_nop 0
	v_pk_mul_f32 v[106:107], v[56:57], v[98:99] op_sel:[0,0] op_sel_hi:[0,1]
	ds_write_b64 v102, v[108:109] offset:0
	ds_read_b128 v[18:21], v100 offset:3168
	ds_read_b128 v[22:25], v100 offset:3184
	ds_read_b128 v[26:29], v100 offset:3696
	ds_read_b128 v[30:33], v100 offset:3712
	ds_read_b64 v[34:35], v101 offset:34176
	ds_read_b64 v[36:37], v117 offset:37912
	v_pk_mul_f32 v[78:79], v[38:39], v[106:107] op_sel:[0,0] op_sel_hi:[0,1]
	v_pk_mul_f32 v[80:81], v[38:39], v[106:107] op_sel:[1,0] op_sel_hi:[1,1]
	v_pk_mul_f32 v[82:83], v[40:41], v[106:107] op_sel:[0,0] op_sel_hi:[0,1]
	v_pk_mul_f32 v[84:85], v[40:41], v[106:107] op_sel:[1,0] op_sel_hi:[1,1]
	v_pk_fma_f32 v[2:3], v[2:3], v[56:57], v[78:79] op_sel:[0,1,0] op_sel_hi:[1,1,1]
	v_pk_fma_f32 v[4:5], v[4:5], v[56:57], v[80:81] op_sel:[0,1,0] op_sel_hi:[1,1,1]
	v_pk_fma_f32 v[6:7], v[6:7], v[56:57], v[82:83] op_sel:[0,1,0] op_sel_hi:[1,1,1]
	v_pk_fma_f32 v[8:9], v[8:9], v[56:57], v[84:85] op_sel:[0,1,0] op_sel_hi:[1,1,1]
	v_pk_mul_f32 v[86:87], v[42:43], v[106:107] op_sel:[0,0] op_sel_hi:[0,1]
	v_pk_mul_f32 v[88:89], v[42:43], v[106:107] op_sel:[1,0] op_sel_hi:[1,1]
	v_pk_mul_f32 v[90:91], v[44:45], v[106:107] op_sel:[0,0] op_sel_hi:[0,1]
	v_pk_mul_f32 v[92:93], v[44:45], v[106:107] op_sel:[1,0] op_sel_hi:[1,1]
	v_pk_fma_f32 v[10:11], v[10:11], v[56:57], v[86:87] op_sel:[0,1,0] op_sel_hi:[1,1,1]
	v_pk_fma_f32 v[12:13], v[12:13], v[56:57], v[88:89] op_sel:[0,1,0] op_sel_hi:[1,1,1]
	v_pk_fma_f32 v[14:15], v[14:15], v[56:57], v[90:91] op_sel:[0,1,0] op_sel_hi:[1,1,1]
	v_pk_fma_f32 v[16:17], v[16:17], v[56:57], v[92:93] op_sel:[0,1,0] op_sel_hi:[1,1,1]
	s_waitcnt lgkmcnt(7)
	v_pk_mul_f32 v[94:95], v[58:59], v[2:3] op_sel:[0,0] op_sel_hi:[0,1]
	v_pk_mul_f32 v[96:97], v[58:59], v[4:5] op_sel:[1,0] op_sel_hi:[1,1]
	v_pk_fma_f32 v[94:95], v[60:61], v[6:7], v[94:95] op_sel:[0,0,0] op_sel_hi:[0,1,1]
	v_pk_fma_f32 v[96:97], v[60:61], v[8:9], v[96:97] op_sel:[1,0,0] op_sel_hi:[1,1,1]
	v_pk_fma_f32 v[94:95], v[62:63], v[10:11], v[94:95] op_sel:[0,0,0] op_sel_hi:[0,1,1]
	v_pk_fma_f32 v[96:97], v[62:63], v[12:13], v[96:97] op_sel:[1,0,0] op_sel_hi:[1,1,1]
	v_pk_fma_f32 v[94:95], v[64:65], v[14:15], v[94:95] op_sel:[0,0,0] op_sel_hi:[0,1,1]
	v_pk_fma_f32 v[96:97], v[64:65], v[16:17], v[96:97] op_sel:[1,0,0] op_sel_hi:[1,1,1]
	v_pk_mul_f32 v[112:113], v[46:47], v[2:3] op_sel:[0,0] op_sel_hi:[0,1]
	v_pk_add_f32 v[94:95], v[94:95], v[96:97]
	v_pk_mul_f32 v[114:115], v[46:47], v[4:5] op_sel:[1,0] op_sel_hi:[1,1]
	v_pk_fma_f32 v[112:113], v[48:49], v[6:7], v[112:113] op_sel:[0,0,0] op_sel_hi:[0,1,1]
	v_add_f32_dpp v94, v94, v94 quad_perm:[1,0,3,2] row_mask:0xf bank_mask:0xf
	v_add_f32_dpp v95, v95, v95 quad_perm:[1,0,3,2] row_mask:0xf bank_mask:0xf
	v_pk_fma_f32 v[114:115], v[48:49], v[8:9], v[114:115] op_sel:[1,0,0] op_sel_hi:[1,1,1]
	v_add_f32_dpp v94, v94, v94 quad_perm:[2,3,0,1] row_mask:0xf bank_mask:0xf
	v_add_f32_dpp v95, v95, v95 quad_perm:[2,3,0,1] row_mask:0xf bank_mask:0xf
	v_pk_fma_f32 v[112:113], v[50:51], v[10:11], v[112:113] op_sel:[0,0,0] op_sel_hi:[0,1,1]
	v_add_f32_dpp v94, v94, v94 row_half_mirror row_mask:0xf bank_mask:0xf
	v_add_f32_dpp v95, v95, v95 row_half_mirror row_mask:0xf bank_mask:0xf
	v_pk_fma_f32 v[114:115], v[50:51], v[12:13], v[114:115] op_sel:[1,0,0] op_sel_hi:[1,1,1]
	v_add_f32_dpp v94, v94, v94 row_mirror row_mask:0xf bank_mask:0xf
	v_add_f32_dpp v95, v95, v95 row_mirror row_mask:0xf bank_mask:0xf
	v_pk_fma_f32 v[112:113], v[52:53], v[14:15], v[112:113] op_sel:[0,0,0] op_sel_hi:[0,1,1]
	v_pk_fma_f32 v[114:115], v[52:53], v[16:17], v[114:115] op_sel:[1,0,0] op_sel_hi:[1,1,1]
	s_nop 0
	v_pk_add_f32 v[112:113], v[112:113], v[114:115]
	v_pk_fma_f32 v[98:99], v[76:77], v[94:95], v[74:75] op_sel:[1,0,0] op_sel_hi:[1,1,1] neg_lo:[1,0,0] neg_hi:[1,0,0]
	s_nop 0
	v_pk_mul_f32 v[106:107], v[76:77], v[98:99] op_sel:[0,0] op_sel_hi:[0,1]
	ds_write_b64 v102, v[112:113] offset:2048
	ds_read_b128 v[38:41], v100 offset:4224
	ds_read_b128 v[42:45], v100 offset:4240
	ds_read_b128 v[46:49], v100 offset:4752
	ds_read_b128 v[50:53], v100 offset:4768
	ds_read_b64 v[54:55], v101 offset:34304
	ds_read_b64 v[56:57], v117 offset:37920
	v_pk_mul_f32 v[78:79], v[58:59], v[106:107] op_sel:[0,0] op_sel_hi:[0,1]
	v_pk_mul_f32 v[80:81], v[58:59], v[106:107] op_sel:[1,0] op_sel_hi:[1,1]
	v_pk_mul_f32 v[82:83], v[60:61], v[106:107] op_sel:[0,0] op_sel_hi:[0,1]
	v_pk_mul_f32 v[84:85], v[60:61], v[106:107] op_sel:[1,0] op_sel_hi:[1,1]
	v_pk_fma_f32 v[2:3], v[2:3], v[76:77], v[78:79] op_sel:[0,1,0] op_sel_hi:[1,1,1]
	v_pk_fma_f32 v[4:5], v[4:5], v[76:77], v[80:81] op_sel:[0,1,0] op_sel_hi:[1,1,1]
	v_pk_fma_f32 v[6:7], v[6:7], v[76:77], v[82:83] op_sel:[0,1,0] op_sel_hi:[1,1,1]
	v_pk_fma_f32 v[8:9], v[8:9], v[76:77], v[84:85] op_sel:[0,1,0] op_sel_hi:[1,1,1]
	v_pk_mul_f32 v[86:87], v[62:63], v[106:107] op_sel:[0,0] op_sel_hi:[0,1]
	v_pk_mul_f32 v[88:89], v[62:63], v[106:107] op_sel:[1,0] op_sel_hi:[1,1]
	v_pk_mul_f32 v[90:91], v[64:65], v[106:107] op_sel:[0,0] op_sel_hi:[0,1]
	v_pk_mul_f32 v[92:93], v[64:65], v[106:107] op_sel:[1,0] op_sel_hi:[1,1]
	v_pk_fma_f32 v[10:11], v[10:11], v[76:77], v[86:87] op_sel:[0,1,0] op_sel_hi:[1,1,1]
	v_pk_fma_f32 v[12:13], v[12:13], v[76:77], v[88:89] op_sel:[0,1,0] op_sel_hi:[1,1,1]
	v_pk_fma_f32 v[14:15], v[14:15], v[76:77], v[90:91] op_sel:[0,1,0] op_sel_hi:[1,1,1]
	v_pk_fma_f32 v[16:17], v[16:17], v[76:77], v[92:93] op_sel:[0,1,0] op_sel_hi:[1,1,1]
	s_waitcnt lgkmcnt(7)
	v_pk_mul_f32 v[94:95], v[18:19], v[2:3] op_sel:[0,0] op_sel_hi:[0,1]
	v_pk_mul_f32 v[96:97], v[18:19], v[4:5] op_sel:[1,0] op_sel_hi:[1,1]
	v_pk_fma_f32 v[94:95], v[20:21], v[6:7], v[94:95] op_sel:[0,0,0] op_sel_hi:[0,1,1]
	v_pk_fma_f32 v[96:97], v[20:21], v[8:9], v[96:97] op_sel:[1,0,0] op_sel_hi:[1,1,1]
	v_pk_fma_f32 v[94:95], v[22:23], v[10:11], v[94:95] op_sel:[0,0,0] op_sel_hi:[0,1,1]
	v_pk_fma_f32 v[96:97], v[22:23], v[12:13], v[96:97] op_sel:[1,0,0] op_sel_hi:[1,1,1]
	v_pk_fma_f32 v[94:95], v[24:25], v[14:15], v[94:95] op_sel:[0,0,0] op_sel_hi:[0,1,1]
	v_pk_fma_f32 v[96:97], v[24:25], v[16:17], v[96:97] op_sel:[1,0,0] op_sel_hi:[1,1,1]
	v_pk_mul_f32 v[108:109], v[66:67], v[2:3] op_sel:[0,0] op_sel_hi:[0,1]
	v_pk_add_f32 v[94:95], v[94:95], v[96:97]
	v_pk_mul_f32 v[110:111], v[66:67], v[4:5] op_sel:[1,0] op_sel_hi:[1,1]
	v_pk_fma_f32 v[108:109], v[68:69], v[6:7], v[108:109] op_sel:[0,0,0] op_sel_hi:[0,1,1]
	v_add_f32_dpp v94, v94, v94 quad_perm:[1,0,3,2] row_mask:0xf bank_mask:0xf
	v_add_f32_dpp v95, v95, v95 quad_perm:[1,0,3,2] row_mask:0xf bank_mask:0xf
	v_pk_fma_f32 v[110:111], v[68:69], v[8:9], v[110:111] op_sel:[1,0,0] op_sel_hi:[1,1,1]
	v_add_f32_dpp v94, v94, v94 quad_perm:[2,3,0,1] row_mask:0xf bank_mask:0xf
	v_add_f32_dpp v95, v95, v95 quad_perm:[2,3,0,1] row_mask:0xf bank_mask:0xf
	v_pk_fma_f32 v[108:109], v[70:71], v[10:11], v[108:109] op_sel:[0,0,0] op_sel_hi:[0,1,1]
	v_add_f32_dpp v94, v94, v94 row_half_mirror row_mask:0xf bank_mask:0xf
	v_add_f32_dpp v95, v95, v95 row_half_mirror row_mask:0xf bank_mask:0xf
	v_pk_fma_f32 v[110:111], v[70:71], v[12:13], v[110:111] op_sel:[1,0,0] op_sel_hi:[1,1,1]
	v_add_f32_dpp v94, v94, v94 row_mirror row_mask:0xf bank_mask:0xf
	v_add_f32_dpp v95, v95, v95 row_mirror row_mask:0xf bank_mask:0xf
	v_pk_fma_f32 v[108:109], v[72:73], v[14:15], v[108:109] op_sel:[0,0,0] op_sel_hi:[0,1,1]
	v_pk_fma_f32 v[110:111], v[72:73], v[16:17], v[110:111] op_sel:[1,0,0] op_sel_hi:[1,1,1]
	s_nop 0
	v_pk_add_f32 v[108:109], v[108:109], v[110:111]
	v_pk_fma_f32 v[98:99], v[36:37], v[94:95], v[34:35] op_sel:[1,0,0] op_sel_hi:[1,1,1] neg_lo:[1,0,0] neg_hi:[1,0,0]
	s_nop 0
	v_pk_mul_f32 v[106:107], v[36:37], v[98:99] op_sel:[0,0] op_sel_hi:[0,1]
	ds_write_b64 v102, v[108:109] offset:4096
	ds_read_b128 v[58:61], v100 offset:5280
	ds_read_b128 v[62:65], v100 offset:5296
	ds_read_b128 v[66:69], v100 offset:5808
	ds_read_b128 v[70:73], v100 offset:5824
	ds_read_b64 v[74:75], v101 offset:34432
	ds_read_b64 v[76:77], v117 offset:37928
	v_pk_mul_f32 v[78:79], v[18:19], v[106:107] op_sel:[0,0] op_sel_hi:[0,1]
	v_pk_mul_f32 v[80:81], v[18:19], v[106:107] op_sel:[1,0] op_sel_hi:[1,1]
	v_pk_mul_f32 v[82:83], v[20:21], v[106:107] op_sel:[0,0] op_sel_hi:[0,1]
	v_pk_mul_f32 v[84:85], v[20:21], v[106:107] op_sel:[1,0] op_sel_hi:[1,1]
	v_pk_fma_f32 v[2:3], v[2:3], v[36:37], v[78:79] op_sel:[0,1,0] op_sel_hi:[1,1,1]
	v_pk_fma_f32 v[4:5], v[4:5], v[36:37], v[80:81] op_sel:[0,1,0] op_sel_hi:[1,1,1]
	v_pk_fma_f32 v[6:7], v[6:7], v[36:37], v[82:83] op_sel:[0,1,0] op_sel_hi:[1,1,1]
	v_pk_fma_f32 v[8:9], v[8:9], v[36:37], v[84:85] op_sel:[0,1,0] op_sel_hi:[1,1,1]
	v_pk_mul_f32 v[86:87], v[22:23], v[106:107] op_sel:[0,0] op_sel_hi:[0,1]
	v_pk_mul_f32 v[88:89], v[22:23], v[106:107] op_sel:[1,0] op_sel_hi:[1,1]
	v_pk_mul_f32 v[90:91], v[24:25], v[106:107] op_sel:[0,0] op_sel_hi:[0,1]
	v_pk_mul_f32 v[92:93], v[24:25], v[106:107] op_sel:[1,0] op_sel_hi:[1,1]
	v_pk_fma_f32 v[10:11], v[10:11], v[36:37], v[86:87] op_sel:[0,1,0] op_sel_hi:[1,1,1]
	v_pk_fma_f32 v[12:13], v[12:13], v[36:37], v[88:89] op_sel:[0,1,0] op_sel_hi:[1,1,1]
	v_pk_fma_f32 v[14:15], v[14:15], v[36:37], v[90:91] op_sel:[0,1,0] op_sel_hi:[1,1,1]
	v_pk_fma_f32 v[16:17], v[16:17], v[36:37], v[92:93] op_sel:[0,1,0] op_sel_hi:[1,1,1]
	s_waitcnt lgkmcnt(7)
	v_pk_mul_f32 v[94:95], v[38:39], v[2:3] op_sel:[0,0] op_sel_hi:[0,1]
	v_pk_mul_f32 v[96:97], v[38:39], v[4:5] op_sel:[1,0] op_sel_hi:[1,1]
	v_pk_fma_f32 v[94:95], v[40:41], v[6:7], v[94:95] op_sel:[0,0,0] op_sel_hi:[0,1,1]
	v_pk_fma_f32 v[96:97], v[40:41], v[8:9], v[96:97] op_sel:[1,0,0] op_sel_hi:[1,1,1]
	v_pk_fma_f32 v[94:95], v[42:43], v[10:11], v[94:95] op_sel:[0,0,0] op_sel_hi:[0,1,1]
	v_pk_fma_f32 v[96:97], v[42:43], v[12:13], v[96:97] op_sel:[1,0,0] op_sel_hi:[1,1,1]
	v_pk_fma_f32 v[94:95], v[44:45], v[14:15], v[94:95] op_sel:[0,0,0] op_sel_hi:[0,1,1]
	v_pk_fma_f32 v[96:97], v[44:45], v[16:17], v[96:97] op_sel:[1,0,0] op_sel_hi:[1,1,1]
	v_pk_mul_f32 v[112:113], v[26:27], v[2:3] op_sel:[0,0] op_sel_hi:[0,1]
	v_pk_add_f32 v[94:95], v[94:95], v[96:97]
	v_pk_mul_f32 v[114:115], v[26:27], v[4:5] op_sel:[1,0] op_sel_hi:[1,1]
	v_pk_fma_f32 v[112:113], v[28:29], v[6:7], v[112:113] op_sel:[0,0,0] op_sel_hi:[0,1,1]
	v_add_f32_dpp v94, v94, v94 quad_perm:[1,0,3,2] row_mask:0xf bank_mask:0xf
	v_add_f32_dpp v95, v95, v95 quad_perm:[1,0,3,2] row_mask:0xf bank_mask:0xf
	v_pk_fma_f32 v[114:115], v[28:29], v[8:9], v[114:115] op_sel:[1,0,0] op_sel_hi:[1,1,1]
	v_add_f32_dpp v94, v94, v94 quad_perm:[2,3,0,1] row_mask:0xf bank_mask:0xf
	v_add_f32_dpp v95, v95, v95 quad_perm:[2,3,0,1] row_mask:0xf bank_mask:0xf
	v_pk_fma_f32 v[112:113], v[30:31], v[10:11], v[112:113] op_sel:[0,0,0] op_sel_hi:[0,1,1]
	v_add_f32_dpp v94, v94, v94 row_half_mirror row_mask:0xf bank_mask:0xf
	v_add_f32_dpp v95, v95, v95 row_half_mirror row_mask:0xf bank_mask:0xf
	v_pk_fma_f32 v[114:115], v[30:31], v[12:13], v[114:115] op_sel:[1,0,0] op_sel_hi:[1,1,1]
	v_add_f32_dpp v94, v94, v94 row_mirror row_mask:0xf bank_mask:0xf
	v_add_f32_dpp v95, v95, v95 row_mirror row_mask:0xf bank_mask:0xf
	v_pk_fma_f32 v[112:113], v[32:33], v[14:15], v[112:113] op_sel:[0,0,0] op_sel_hi:[0,1,1]
	v_pk_fma_f32 v[114:115], v[32:33], v[16:17], v[114:115] op_sel:[1,0,0] op_sel_hi:[1,1,1]
	s_nop 0
	v_pk_add_f32 v[112:113], v[112:113], v[114:115]
	v_pk_fma_f32 v[98:99], v[56:57], v[94:95], v[54:55] op_sel:[1,0,0] op_sel_hi:[1,1,1] neg_lo:[1,0,0] neg_hi:[1,0,0]
	s_nop 0
	v_pk_mul_f32 v[106:107], v[56:57], v[98:99] op_sel:[0,0] op_sel_hi:[0,1]
	ds_write_b64 v102, v[112:113] offset:6144
	ds_read_b128 v[18:21], v100 offset:6336
	ds_read_b128 v[22:25], v100 offset:6352
	ds_read_b128 v[26:29], v100 offset:6864
	ds_read_b128 v[30:33], v100 offset:6880
	ds_read_b64 v[34:35], v101 offset:34560
	ds_read_b64 v[36:37], v117 offset:37936
	v_pk_mul_f32 v[78:79], v[38:39], v[106:107] op_sel:[0,0] op_sel_hi:[0,1]
	v_pk_mul_f32 v[80:81], v[38:39], v[106:107] op_sel:[1,0] op_sel_hi:[1,1]
	v_pk_mul_f32 v[82:83], v[40:41], v[106:107] op_sel:[0,0] op_sel_hi:[0,1]
	v_pk_mul_f32 v[84:85], v[40:41], v[106:107] op_sel:[1,0] op_sel_hi:[1,1]
	v_pk_fma_f32 v[2:3], v[2:3], v[56:57], v[78:79] op_sel:[0,1,0] op_sel_hi:[1,1,1]
	v_pk_fma_f32 v[4:5], v[4:5], v[56:57], v[80:81] op_sel:[0,1,0] op_sel_hi:[1,1,1]
	v_pk_fma_f32 v[6:7], v[6:7], v[56:57], v[82:83] op_sel:[0,1,0] op_sel_hi:[1,1,1]
	v_pk_fma_f32 v[8:9], v[8:9], v[56:57], v[84:85] op_sel:[0,1,0] op_sel_hi:[1,1,1]
	v_pk_mul_f32 v[86:87], v[42:43], v[106:107] op_sel:[0,0] op_sel_hi:[0,1]
	v_pk_mul_f32 v[88:89], v[42:43], v[106:107] op_sel:[1,0] op_sel_hi:[1,1]
	v_pk_mul_f32 v[90:91], v[44:45], v[106:107] op_sel:[0,0] op_sel_hi:[0,1]
	v_pk_mul_f32 v[92:93], v[44:45], v[106:107] op_sel:[1,0] op_sel_hi:[1,1]
	v_pk_fma_f32 v[10:11], v[10:11], v[56:57], v[86:87] op_sel:[0,1,0] op_sel_hi:[1,1,1]
	v_pk_fma_f32 v[12:13], v[12:13], v[56:57], v[88:89] op_sel:[0,1,0] op_sel_hi:[1,1,1]
	v_pk_fma_f32 v[14:15], v[14:15], v[56:57], v[90:91] op_sel:[0,1,0] op_sel_hi:[1,1,1]
	v_pk_fma_f32 v[16:17], v[16:17], v[56:57], v[92:93] op_sel:[0,1,0] op_sel_hi:[1,1,1]
	s_waitcnt lgkmcnt(7)
	v_pk_mul_f32 v[94:95], v[58:59], v[2:3] op_sel:[0,0] op_sel_hi:[0,1]
	v_pk_mul_f32 v[96:97], v[58:59], v[4:5] op_sel:[1,0] op_sel_hi:[1,1]
	v_pk_fma_f32 v[94:95], v[60:61], v[6:7], v[94:95] op_sel:[0,0,0] op_sel_hi:[0,1,1]
	v_pk_fma_f32 v[96:97], v[60:61], v[8:9], v[96:97] op_sel:[1,0,0] op_sel_hi:[1,1,1]
	v_pk_fma_f32 v[94:95], v[62:63], v[10:11], v[94:95] op_sel:[0,0,0] op_sel_hi:[0,1,1]
	v_pk_fma_f32 v[96:97], v[62:63], v[12:13], v[96:97] op_sel:[1,0,0] op_sel_hi:[1,1,1]
	v_pk_fma_f32 v[94:95], v[64:65], v[14:15], v[94:95] op_sel:[0,0,0] op_sel_hi:[0,1,1]
	v_pk_fma_f32 v[96:97], v[64:65], v[16:17], v[96:97] op_sel:[1,0,0] op_sel_hi:[1,1,1]
	v_pk_mul_f32 v[108:109], v[46:47], v[2:3] op_sel:[0,0] op_sel_hi:[0,1]
	v_pk_add_f32 v[94:95], v[94:95], v[96:97]
	v_pk_mul_f32 v[110:111], v[46:47], v[4:5] op_sel:[1,0] op_sel_hi:[1,1]
	v_pk_fma_f32 v[108:109], v[48:49], v[6:7], v[108:109] op_sel:[0,0,0] op_sel_hi:[0,1,1]
	v_add_f32_dpp v94, v94, v94 quad_perm:[1,0,3,2] row_mask:0xf bank_mask:0xf
	v_add_f32_dpp v95, v95, v95 quad_perm:[1,0,3,2] row_mask:0xf bank_mask:0xf
	v_pk_fma_f32 v[110:111], v[48:49], v[8:9], v[110:111] op_sel:[1,0,0] op_sel_hi:[1,1,1]
	v_add_f32_dpp v94, v94, v94 quad_perm:[2,3,0,1] row_mask:0xf bank_mask:0xf
	v_add_f32_dpp v95, v95, v95 quad_perm:[2,3,0,1] row_mask:0xf bank_mask:0xf
	v_pk_fma_f32 v[108:109], v[50:51], v[10:11], v[108:109] op_sel:[0,0,0] op_sel_hi:[0,1,1]
	v_add_f32_dpp v94, v94, v94 row_half_mirror row_mask:0xf bank_mask:0xf
	v_add_f32_dpp v95, v95, v95 row_half_mirror row_mask:0xf bank_mask:0xf
	v_pk_fma_f32 v[110:111], v[50:51], v[12:13], v[110:111] op_sel:[1,0,0] op_sel_hi:[1,1,1]
	v_add_f32_dpp v94, v94, v94 row_mirror row_mask:0xf bank_mask:0xf
	v_add_f32_dpp v95, v95, v95 row_mirror row_mask:0xf bank_mask:0xf
	v_pk_fma_f32 v[108:109], v[52:53], v[14:15], v[108:109] op_sel:[0,0,0] op_sel_hi:[0,1,1]
	v_pk_fma_f32 v[110:111], v[52:53], v[16:17], v[110:111] op_sel:[1,0,0] op_sel_hi:[1,1,1]
	s_nop 0
	v_pk_add_f32 v[108:109], v[108:109], v[110:111]
	v_pk_fma_f32 v[98:99], v[76:77], v[94:95], v[74:75] op_sel:[1,0,0] op_sel_hi:[1,1,1] neg_lo:[1,0,0] neg_hi:[1,0,0]
	s_nop 0
	v_pk_mul_f32 v[106:107], v[76:77], v[98:99] op_sel:[0,0] op_sel_hi:[0,1]
	ds_write_b64 v102, v[108:109] offset:8192
	ds_read_b128 v[38:41], v100 offset:7392
	ds_read_b128 v[42:45], v100 offset:7408
	ds_read_b128 v[46:49], v100 offset:7920
	ds_read_b128 v[50:53], v100 offset:7936
	ds_read_b64 v[54:55], v101 offset:34688
	ds_read_b64 v[56:57], v117 offset:37944
	v_pk_mul_f32 v[78:79], v[58:59], v[106:107] op_sel:[0,0] op_sel_hi:[0,1]
	v_pk_mul_f32 v[80:81], v[58:59], v[106:107] op_sel:[1,0] op_sel_hi:[1,1]
	v_pk_mul_f32 v[82:83], v[60:61], v[106:107] op_sel:[0,0] op_sel_hi:[0,1]
	v_pk_mul_f32 v[84:85], v[60:61], v[106:107] op_sel:[1,0] op_sel_hi:[1,1]
	v_pk_fma_f32 v[2:3], v[2:3], v[76:77], v[78:79] op_sel:[0,1,0] op_sel_hi:[1,1,1]
	v_pk_fma_f32 v[4:5], v[4:5], v[76:77], v[80:81] op_sel:[0,1,0] op_sel_hi:[1,1,1]
	v_pk_fma_f32 v[6:7], v[6:7], v[76:77], v[82:83] op_sel:[0,1,0] op_sel_hi:[1,1,1]
	v_pk_fma_f32 v[8:9], v[8:9], v[76:77], v[84:85] op_sel:[0,1,0] op_sel_hi:[1,1,1]
	v_pk_mul_f32 v[86:87], v[62:63], v[106:107] op_sel:[0,0] op_sel_hi:[0,1]
	v_pk_mul_f32 v[88:89], v[62:63], v[106:107] op_sel:[1,0] op_sel_hi:[1,1]
	v_pk_mul_f32 v[90:91], v[64:65], v[106:107] op_sel:[0,0] op_sel_hi:[0,1]
	v_pk_mul_f32 v[92:93], v[64:65], v[106:107] op_sel:[1,0] op_sel_hi:[1,1]
	v_pk_fma_f32 v[10:11], v[10:11], v[76:77], v[86:87] op_sel:[0,1,0] op_sel_hi:[1,1,1]
	v_pk_fma_f32 v[12:13], v[12:13], v[76:77], v[88:89] op_sel:[0,1,0] op_sel_hi:[1,1,1]
	v_pk_fma_f32 v[14:15], v[14:15], v[76:77], v[90:91] op_sel:[0,1,0] op_sel_hi:[1,1,1]
	v_pk_fma_f32 v[16:17], v[16:17], v[76:77], v[92:93] op_sel:[0,1,0] op_sel_hi:[1,1,1]
	s_waitcnt lgkmcnt(7)
	v_pk_mul_f32 v[94:95], v[18:19], v[2:3] op_sel:[0,0] op_sel_hi:[0,1]
	v_pk_mul_f32 v[96:97], v[18:19], v[4:5] op_sel:[1,0] op_sel_hi:[1,1]
	v_pk_fma_f32 v[94:95], v[20:21], v[6:7], v[94:95] op_sel:[0,0,0] op_sel_hi:[0,1,1]
	v_pk_fma_f32 v[96:97], v[20:21], v[8:9], v[96:97] op_sel:[1,0,0] op_sel_hi:[1,1,1]
	v_pk_fma_f32 v[94:95], v[22:23], v[10:11], v[94:95] op_sel:[0,0,0] op_sel_hi:[0,1,1]
	v_pk_fma_f32 v[96:97], v[22:23], v[12:13], v[96:97] op_sel:[1,0,0] op_sel_hi:[1,1,1]
	v_pk_fma_f32 v[94:95], v[24:25], v[14:15], v[94:95] op_sel:[0,0,0] op_sel_hi:[0,1,1]
	v_pk_fma_f32 v[96:97], v[24:25], v[16:17], v[96:97] op_sel:[1,0,0] op_sel_hi:[1,1,1]
	v_pk_mul_f32 v[112:113], v[66:67], v[2:3] op_sel:[0,0] op_sel_hi:[0,1]
	v_pk_add_f32 v[94:95], v[94:95], v[96:97]
	v_pk_mul_f32 v[114:115], v[66:67], v[4:5] op_sel:[1,0] op_sel_hi:[1,1]
	v_pk_fma_f32 v[112:113], v[68:69], v[6:7], v[112:113] op_sel:[0,0,0] op_sel_hi:[0,1,1]
	v_add_f32_dpp v94, v94, v94 quad_perm:[1,0,3,2] row_mask:0xf bank_mask:0xf
	v_add_f32_dpp v95, v95, v95 quad_perm:[1,0,3,2] row_mask:0xf bank_mask:0xf
	v_pk_fma_f32 v[114:115], v[68:69], v[8:9], v[114:115] op_sel:[1,0,0] op_sel_hi:[1,1,1]
	v_add_f32_dpp v94, v94, v94 quad_perm:[2,3,0,1] row_mask:0xf bank_mask:0xf
	v_add_f32_dpp v95, v95, v95 quad_perm:[2,3,0,1] row_mask:0xf bank_mask:0xf
	v_pk_fma_f32 v[112:113], v[70:71], v[10:11], v[112:113] op_sel:[0,0,0] op_sel_hi:[0,1,1]
	v_add_f32_dpp v94, v94, v94 row_half_mirror row_mask:0xf bank_mask:0xf
	v_add_f32_dpp v95, v95, v95 row_half_mirror row_mask:0xf bank_mask:0xf
	v_pk_fma_f32 v[114:115], v[70:71], v[12:13], v[114:115] op_sel:[1,0,0] op_sel_hi:[1,1,1]
	v_add_f32_dpp v94, v94, v94 row_mirror row_mask:0xf bank_mask:0xf
	v_add_f32_dpp v95, v95, v95 row_mirror row_mask:0xf bank_mask:0xf
	v_pk_fma_f32 v[112:113], v[72:73], v[14:15], v[112:113] op_sel:[0,0,0] op_sel_hi:[0,1,1]
	v_pk_fma_f32 v[114:115], v[72:73], v[16:17], v[114:115] op_sel:[1,0,0] op_sel_hi:[1,1,1]
	s_nop 0
	v_pk_add_f32 v[112:113], v[112:113], v[114:115]
	v_pk_fma_f32 v[98:99], v[36:37], v[94:95], v[34:35] op_sel:[1,0,0] op_sel_hi:[1,1,1] neg_lo:[1,0,0] neg_hi:[1,0,0]
	s_nop 0
	v_pk_mul_f32 v[106:107], v[36:37], v[98:99] op_sel:[0,0] op_sel_hi:[0,1]
	ds_write_b64 v102, v[112:113] offset:10240
	ds_read_b128 v[58:61], v100 offset:8448
	ds_read_b128 v[62:65], v100 offset:8464
	ds_read_b128 v[66:69], v100 offset:8976
	ds_read_b128 v[70:73], v100 offset:8992
	ds_read_b64 v[74:75], v101 offset:34816
	ds_read_b64 v[76:77], v117 offset:37952
	v_pk_mul_f32 v[78:79], v[18:19], v[106:107] op_sel:[0,0] op_sel_hi:[0,1]
	v_pk_mul_f32 v[80:81], v[18:19], v[106:107] op_sel:[1,0] op_sel_hi:[1,1]
	v_pk_mul_f32 v[82:83], v[20:21], v[106:107] op_sel:[0,0] op_sel_hi:[0,1]
	v_pk_mul_f32 v[84:85], v[20:21], v[106:107] op_sel:[1,0] op_sel_hi:[1,1]
	v_pk_fma_f32 v[2:3], v[2:3], v[36:37], v[78:79] op_sel:[0,1,0] op_sel_hi:[1,1,1]
	v_pk_fma_f32 v[4:5], v[4:5], v[36:37], v[80:81] op_sel:[0,1,0] op_sel_hi:[1,1,1]
	v_pk_fma_f32 v[6:7], v[6:7], v[36:37], v[82:83] op_sel:[0,1,0] op_sel_hi:[1,1,1]
	v_pk_fma_f32 v[8:9], v[8:9], v[36:37], v[84:85] op_sel:[0,1,0] op_sel_hi:[1,1,1]
	v_pk_mul_f32 v[86:87], v[22:23], v[106:107] op_sel:[0,0] op_sel_hi:[0,1]
	v_pk_mul_f32 v[88:89], v[22:23], v[106:107] op_sel:[1,0] op_sel_hi:[1,1]
	v_pk_mul_f32 v[90:91], v[24:25], v[106:107] op_sel:[0,0] op_sel_hi:[0,1]
	v_pk_mul_f32 v[92:93], v[24:25], v[106:107] op_sel:[1,0] op_sel_hi:[1,1]
	v_pk_fma_f32 v[10:11], v[10:11], v[36:37], v[86:87] op_sel:[0,1,0] op_sel_hi:[1,1,1]
	v_pk_fma_f32 v[12:13], v[12:13], v[36:37], v[88:89] op_sel:[0,1,0] op_sel_hi:[1,1,1]
	v_pk_fma_f32 v[14:15], v[14:15], v[36:37], v[90:91] op_sel:[0,1,0] op_sel_hi:[1,1,1]
	v_pk_fma_f32 v[16:17], v[16:17], v[36:37], v[92:93] op_sel:[0,1,0] op_sel_hi:[1,1,1]
	s_waitcnt lgkmcnt(7)
	v_pk_mul_f32 v[94:95], v[38:39], v[2:3] op_sel:[0,0] op_sel_hi:[0,1]
	v_pk_mul_f32 v[96:97], v[38:39], v[4:5] op_sel:[1,0] op_sel_hi:[1,1]
	v_pk_fma_f32 v[94:95], v[40:41], v[6:7], v[94:95] op_sel:[0,0,0] op_sel_hi:[0,1,1]
	v_pk_fma_f32 v[96:97], v[40:41], v[8:9], v[96:97] op_sel:[1,0,0] op_sel_hi:[1,1,1]
	v_pk_fma_f32 v[94:95], v[42:43], v[10:11], v[94:95] op_sel:[0,0,0] op_sel_hi:[0,1,1]
	v_pk_fma_f32 v[96:97], v[42:43], v[12:13], v[96:97] op_sel:[1,0,0] op_sel_hi:[1,1,1]
	v_pk_fma_f32 v[94:95], v[44:45], v[14:15], v[94:95] op_sel:[0,0,0] op_sel_hi:[0,1,1]
	v_pk_fma_f32 v[96:97], v[44:45], v[16:17], v[96:97] op_sel:[1,0,0] op_sel_hi:[1,1,1]
	v_pk_mul_f32 v[108:109], v[26:27], v[2:3] op_sel:[0,0] op_sel_hi:[0,1]
	v_pk_add_f32 v[94:95], v[94:95], v[96:97]
	v_pk_mul_f32 v[110:111], v[26:27], v[4:5] op_sel:[1,0] op_sel_hi:[1,1]
	v_pk_fma_f32 v[108:109], v[28:29], v[6:7], v[108:109] op_sel:[0,0,0] op_sel_hi:[0,1,1]
	v_add_f32_dpp v94, v94, v94 quad_perm:[1,0,3,2] row_mask:0xf bank_mask:0xf
	v_add_f32_dpp v95, v95, v95 quad_perm:[1,0,3,2] row_mask:0xf bank_mask:0xf
	v_pk_fma_f32 v[110:111], v[28:29], v[8:9], v[110:111] op_sel:[1,0,0] op_sel_hi:[1,1,1]
	v_add_f32_dpp v94, v94, v94 quad_perm:[2,3,0,1] row_mask:0xf bank_mask:0xf
	v_add_f32_dpp v95, v95, v95 quad_perm:[2,3,0,1] row_mask:0xf bank_mask:0xf
	v_pk_fma_f32 v[108:109], v[30:31], v[10:11], v[108:109] op_sel:[0,0,0] op_sel_hi:[0,1,1]
	v_add_f32_dpp v94, v94, v94 row_half_mirror row_mask:0xf bank_mask:0xf
	v_add_f32_dpp v95, v95, v95 row_half_mirror row_mask:0xf bank_mask:0xf
	v_pk_fma_f32 v[110:111], v[30:31], v[12:13], v[110:111] op_sel:[1,0,0] op_sel_hi:[1,1,1]
	v_add_f32_dpp v94, v94, v94 row_mirror row_mask:0xf bank_mask:0xf
	v_add_f32_dpp v95, v95, v95 row_mirror row_mask:0xf bank_mask:0xf
	v_pk_fma_f32 v[108:109], v[32:33], v[14:15], v[108:109] op_sel:[0,0,0] op_sel_hi:[0,1,1]
	v_pk_fma_f32 v[110:111], v[32:33], v[16:17], v[110:111] op_sel:[1,0,0] op_sel_hi:[1,1,1]
	s_nop 0
	v_pk_add_f32 v[108:109], v[108:109], v[110:111]
	v_pk_fma_f32 v[98:99], v[56:57], v[94:95], v[54:55] op_sel:[1,0,0] op_sel_hi:[1,1,1] neg_lo:[1,0,0] neg_hi:[1,0,0]
	s_nop 0
	v_pk_mul_f32 v[106:107], v[56:57], v[98:99] op_sel:[0,0] op_sel_hi:[0,1]
	ds_write_b64 v102, v[108:109] offset:12288
	ds_read_b128 v[18:21], v100 offset:9504
	ds_read_b128 v[22:25], v100 offset:9520
	ds_read_b128 v[26:29], v100 offset:10032
	ds_read_b128 v[30:33], v100 offset:10048
	ds_read_b64 v[34:35], v101 offset:34944
	ds_read_b64 v[36:37], v117 offset:37960
	v_pk_mul_f32 v[78:79], v[38:39], v[106:107] op_sel:[0,0] op_sel_hi:[0,1]
	v_pk_mul_f32 v[80:81], v[38:39], v[106:107] op_sel:[1,0] op_sel_hi:[1,1]
	v_pk_mul_f32 v[82:83], v[40:41], v[106:107] op_sel:[0,0] op_sel_hi:[0,1]
	v_pk_mul_f32 v[84:85], v[40:41], v[106:107] op_sel:[1,0] op_sel_hi:[1,1]
	v_pk_fma_f32 v[2:3], v[2:3], v[56:57], v[78:79] op_sel:[0,1,0] op_sel_hi:[1,1,1]
	v_pk_fma_f32 v[4:5], v[4:5], v[56:57], v[80:81] op_sel:[0,1,0] op_sel_hi:[1,1,1]
	v_pk_fma_f32 v[6:7], v[6:7], v[56:57], v[82:83] op_sel:[0,1,0] op_sel_hi:[1,1,1]
	v_pk_fma_f32 v[8:9], v[8:9], v[56:57], v[84:85] op_sel:[0,1,0] op_sel_hi:[1,1,1]
	v_pk_mul_f32 v[86:87], v[42:43], v[106:107] op_sel:[0,0] op_sel_hi:[0,1]
	v_pk_mul_f32 v[88:89], v[42:43], v[106:107] op_sel:[1,0] op_sel_hi:[1,1]
	v_pk_mul_f32 v[90:91], v[44:45], v[106:107] op_sel:[0,0] op_sel_hi:[0,1]
	v_pk_mul_f32 v[92:93], v[44:45], v[106:107] op_sel:[1,0] op_sel_hi:[1,1]
	v_pk_fma_f32 v[10:11], v[10:11], v[56:57], v[86:87] op_sel:[0,1,0] op_sel_hi:[1,1,1]
	v_pk_fma_f32 v[12:13], v[12:13], v[56:57], v[88:89] op_sel:[0,1,0] op_sel_hi:[1,1,1]
	v_pk_fma_f32 v[14:15], v[14:15], v[56:57], v[90:91] op_sel:[0,1,0] op_sel_hi:[1,1,1]
	v_pk_fma_f32 v[16:17], v[16:17], v[56:57], v[92:93] op_sel:[0,1,0] op_sel_hi:[1,1,1]
	s_waitcnt lgkmcnt(7)
	v_pk_mul_f32 v[94:95], v[58:59], v[2:3] op_sel:[0,0] op_sel_hi:[0,1]
	v_pk_mul_f32 v[96:97], v[58:59], v[4:5] op_sel:[1,0] op_sel_hi:[1,1]
	v_pk_fma_f32 v[94:95], v[60:61], v[6:7], v[94:95] op_sel:[0,0,0] op_sel_hi:[0,1,1]
	v_pk_fma_f32 v[96:97], v[60:61], v[8:9], v[96:97] op_sel:[1,0,0] op_sel_hi:[1,1,1]
	v_pk_fma_f32 v[94:95], v[62:63], v[10:11], v[94:95] op_sel:[0,0,0] op_sel_hi:[0,1,1]
	v_pk_fma_f32 v[96:97], v[62:63], v[12:13], v[96:97] op_sel:[1,0,0] op_sel_hi:[1,1,1]
	v_pk_fma_f32 v[94:95], v[64:65], v[14:15], v[94:95] op_sel:[0,0,0] op_sel_hi:[0,1,1]
	v_pk_fma_f32 v[96:97], v[64:65], v[16:17], v[96:97] op_sel:[1,0,0] op_sel_hi:[1,1,1]
	v_pk_mul_f32 v[112:113], v[46:47], v[2:3] op_sel:[0,0] op_sel_hi:[0,1]
	v_pk_add_f32 v[94:95], v[94:95], v[96:97]
	v_pk_mul_f32 v[114:115], v[46:47], v[4:5] op_sel:[1,0] op_sel_hi:[1,1]
	v_pk_fma_f32 v[112:113], v[48:49], v[6:7], v[112:113] op_sel:[0,0,0] op_sel_hi:[0,1,1]
	v_add_f32_dpp v94, v94, v94 quad_perm:[1,0,3,2] row_mask:0xf bank_mask:0xf
	v_add_f32_dpp v95, v95, v95 quad_perm:[1,0,3,2] row_mask:0xf bank_mask:0xf
	v_pk_fma_f32 v[114:115], v[48:49], v[8:9], v[114:115] op_sel:[1,0,0] op_sel_hi:[1,1,1]
	v_add_f32_dpp v94, v94, v94 quad_perm:[2,3,0,1] row_mask:0xf bank_mask:0xf
	v_add_f32_dpp v95, v95, v95 quad_perm:[2,3,0,1] row_mask:0xf bank_mask:0xf
	v_pk_fma_f32 v[112:113], v[50:51], v[10:11], v[112:113] op_sel:[0,0,0] op_sel_hi:[0,1,1]
	v_add_f32_dpp v94, v94, v94 row_half_mirror row_mask:0xf bank_mask:0xf
	v_add_f32_dpp v95, v95, v95 row_half_mirror row_mask:0xf bank_mask:0xf
	v_pk_fma_f32 v[114:115], v[50:51], v[12:13], v[114:115] op_sel:[1,0,0] op_sel_hi:[1,1,1]
	v_add_f32_dpp v94, v94, v94 row_mirror row_mask:0xf bank_mask:0xf
	v_add_f32_dpp v95, v95, v95 row_mirror row_mask:0xf bank_mask:0xf
	v_pk_fma_f32 v[112:113], v[52:53], v[14:15], v[112:113] op_sel:[0,0,0] op_sel_hi:[0,1,1]
	v_pk_fma_f32 v[114:115], v[52:53], v[16:17], v[114:115] op_sel:[1,0,0] op_sel_hi:[1,1,1]
	s_nop 0
	v_pk_add_f32 v[112:113], v[112:113], v[114:115]
	v_pk_fma_f32 v[98:99], v[76:77], v[94:95], v[74:75] op_sel:[1,0,0] op_sel_hi:[1,1,1] neg_lo:[1,0,0] neg_hi:[1,0,0]
	s_nop 0
	v_pk_mul_f32 v[106:107], v[76:77], v[98:99] op_sel:[0,0] op_sel_hi:[0,1]
	ds_write_b64 v102, v[112:113] offset:14336
	ds_read_b128 v[38:41], v100 offset:10560
	ds_read_b128 v[42:45], v100 offset:10576
	ds_read_b128 v[46:49], v100 offset:11088
	ds_read_b128 v[50:53], v100 offset:11104
	ds_read_b64 v[54:55], v101 offset:35072
	ds_read_b64 v[56:57], v117 offset:37968
	v_pk_mul_f32 v[78:79], v[58:59], v[106:107] op_sel:[0,0] op_sel_hi:[0,1]
	v_pk_mul_f32 v[80:81], v[58:59], v[106:107] op_sel:[1,0] op_sel_hi:[1,1]
	v_pk_mul_f32 v[82:83], v[60:61], v[106:107] op_sel:[0,0] op_sel_hi:[0,1]
	v_pk_mul_f32 v[84:85], v[60:61], v[106:107] op_sel:[1,0] op_sel_hi:[1,1]
	v_pk_fma_f32 v[2:3], v[2:3], v[76:77], v[78:79] op_sel:[0,1,0] op_sel_hi:[1,1,1]
	v_pk_fma_f32 v[4:5], v[4:5], v[76:77], v[80:81] op_sel:[0,1,0] op_sel_hi:[1,1,1]
	v_pk_fma_f32 v[6:7], v[6:7], v[76:77], v[82:83] op_sel:[0,1,0] op_sel_hi:[1,1,1]
	v_pk_fma_f32 v[8:9], v[8:9], v[76:77], v[84:85] op_sel:[0,1,0] op_sel_hi:[1,1,1]
	v_pk_mul_f32 v[86:87], v[62:63], v[106:107] op_sel:[0,0] op_sel_hi:[0,1]
	v_pk_mul_f32 v[88:89], v[62:63], v[106:107] op_sel:[1,0] op_sel_hi:[1,1]
	v_pk_mul_f32 v[90:91], v[64:65], v[106:107] op_sel:[0,0] op_sel_hi:[0,1]
	v_pk_mul_f32 v[92:93], v[64:65], v[106:107] op_sel:[1,0] op_sel_hi:[1,1]
	v_pk_fma_f32 v[10:11], v[10:11], v[76:77], v[86:87] op_sel:[0,1,0] op_sel_hi:[1,1,1]
	v_pk_fma_f32 v[12:13], v[12:13], v[76:77], v[88:89] op_sel:[0,1,0] op_sel_hi:[1,1,1]
	v_pk_fma_f32 v[14:15], v[14:15], v[76:77], v[90:91] op_sel:[0,1,0] op_sel_hi:[1,1,1]
	v_pk_fma_f32 v[16:17], v[16:17], v[76:77], v[92:93] op_sel:[0,1,0] op_sel_hi:[1,1,1]
	s_waitcnt lgkmcnt(7)
	v_pk_mul_f32 v[94:95], v[18:19], v[2:3] op_sel:[0,0] op_sel_hi:[0,1]
	v_pk_mul_f32 v[96:97], v[18:19], v[4:5] op_sel:[1,0] op_sel_hi:[1,1]
	v_pk_fma_f32 v[94:95], v[20:21], v[6:7], v[94:95] op_sel:[0,0,0] op_sel_hi:[0,1,1]
	v_pk_fma_f32 v[96:97], v[20:21], v[8:9], v[96:97] op_sel:[1,0,0] op_sel_hi:[1,1,1]
	v_pk_fma_f32 v[94:95], v[22:23], v[10:11], v[94:95] op_sel:[0,0,0] op_sel_hi:[0,1,1]
	v_pk_fma_f32 v[96:97], v[22:23], v[12:13], v[96:97] op_sel:[1,0,0] op_sel_hi:[1,1,1]
	v_pk_fma_f32 v[94:95], v[24:25], v[14:15], v[94:95] op_sel:[0,0,0] op_sel_hi:[0,1,1]
	v_pk_fma_f32 v[96:97], v[24:25], v[16:17], v[96:97] op_sel:[1,0,0] op_sel_hi:[1,1,1]
	v_pk_mul_f32 v[108:109], v[66:67], v[2:3] op_sel:[0,0] op_sel_hi:[0,1]
	v_pk_add_f32 v[94:95], v[94:95], v[96:97]
	v_pk_mul_f32 v[110:111], v[66:67], v[4:5] op_sel:[1,0] op_sel_hi:[1,1]
	v_pk_fma_f32 v[108:109], v[68:69], v[6:7], v[108:109] op_sel:[0,0,0] op_sel_hi:[0,1,1]
	v_add_f32_dpp v94, v94, v94 quad_perm:[1,0,3,2] row_mask:0xf bank_mask:0xf
	v_add_f32_dpp v95, v95, v95 quad_perm:[1,0,3,2] row_mask:0xf bank_mask:0xf
	v_pk_fma_f32 v[110:111], v[68:69], v[8:9], v[110:111] op_sel:[1,0,0] op_sel_hi:[1,1,1]
	v_add_f32_dpp v94, v94, v94 quad_perm:[2,3,0,1] row_mask:0xf bank_mask:0xf
	v_add_f32_dpp v95, v95, v95 quad_perm:[2,3,0,1] row_mask:0xf bank_mask:0xf
	v_pk_fma_f32 v[108:109], v[70:71], v[10:11], v[108:109] op_sel:[0,0,0] op_sel_hi:[0,1,1]
	v_add_f32_dpp v94, v94, v94 row_half_mirror row_mask:0xf bank_mask:0xf
	v_add_f32_dpp v95, v95, v95 row_half_mirror row_mask:0xf bank_mask:0xf
	v_pk_fma_f32 v[110:111], v[70:71], v[12:13], v[110:111] op_sel:[1,0,0] op_sel_hi:[1,1,1]
	v_add_f32_dpp v94, v94, v94 row_mirror row_mask:0xf bank_mask:0xf
	v_add_f32_dpp v95, v95, v95 row_mirror row_mask:0xf bank_mask:0xf
	v_pk_fma_f32 v[108:109], v[72:73], v[14:15], v[108:109] op_sel:[0,0,0] op_sel_hi:[0,1,1]
	v_pk_fma_f32 v[110:111], v[72:73], v[16:17], v[110:111] op_sel:[1,0,0] op_sel_hi:[1,1,1]
	s_nop 0
	v_pk_add_f32 v[108:109], v[108:109], v[110:111]
	v_pk_fma_f32 v[98:99], v[36:37], v[94:95], v[34:35] op_sel:[1,0,0] op_sel_hi:[1,1,1] neg_lo:[1,0,0] neg_hi:[1,0,0]
	s_nop 0
	v_pk_mul_f32 v[106:107], v[36:37], v[98:99] op_sel:[0,0] op_sel_hi:[0,1]
	ds_write_b64 v102, v[108:109] offset:16384
	ds_read_b128 v[58:61], v100 offset:11616
	ds_read_b128 v[62:65], v100 offset:11632
	ds_read_b128 v[66:69], v100 offset:12144
	ds_read_b128 v[70:73], v100 offset:12160
	ds_read_b64 v[74:75], v101 offset:35200
	ds_read_b64 v[76:77], v117 offset:37976
	v_pk_mul_f32 v[78:79], v[18:19], v[106:107] op_sel:[0,0] op_sel_hi:[0,1]
	v_pk_mul_f32 v[80:81], v[18:19], v[106:107] op_sel:[1,0] op_sel_hi:[1,1]
	v_pk_mul_f32 v[82:83], v[20:21], v[106:107] op_sel:[0,0] op_sel_hi:[0,1]
	v_pk_mul_f32 v[84:85], v[20:21], v[106:107] op_sel:[1,0] op_sel_hi:[1,1]
	v_pk_fma_f32 v[2:3], v[2:3], v[36:37], v[78:79] op_sel:[0,1,0] op_sel_hi:[1,1,1]
	v_pk_fma_f32 v[4:5], v[4:5], v[36:37], v[80:81] op_sel:[0,1,0] op_sel_hi:[1,1,1]
	v_pk_fma_f32 v[6:7], v[6:7], v[36:37], v[82:83] op_sel:[0,1,0] op_sel_hi:[1,1,1]
	v_pk_fma_f32 v[8:9], v[8:9], v[36:37], v[84:85] op_sel:[0,1,0] op_sel_hi:[1,1,1]
	v_pk_mul_f32 v[86:87], v[22:23], v[106:107] op_sel:[0,0] op_sel_hi:[0,1]
	v_pk_mul_f32 v[88:89], v[22:23], v[106:107] op_sel:[1,0] op_sel_hi:[1,1]
	v_pk_mul_f32 v[90:91], v[24:25], v[106:107] op_sel:[0,0] op_sel_hi:[0,1]
	v_pk_mul_f32 v[92:93], v[24:25], v[106:107] op_sel:[1,0] op_sel_hi:[1,1]
	v_pk_fma_f32 v[10:11], v[10:11], v[36:37], v[86:87] op_sel:[0,1,0] op_sel_hi:[1,1,1]
	v_pk_fma_f32 v[12:13], v[12:13], v[36:37], v[88:89] op_sel:[0,1,0] op_sel_hi:[1,1,1]
	v_pk_fma_f32 v[14:15], v[14:15], v[36:37], v[90:91] op_sel:[0,1,0] op_sel_hi:[1,1,1]
	v_pk_fma_f32 v[16:17], v[16:17], v[36:37], v[92:93] op_sel:[0,1,0] op_sel_hi:[1,1,1]
	s_waitcnt lgkmcnt(7)
	v_pk_mul_f32 v[94:95], v[38:39], v[2:3] op_sel:[0,0] op_sel_hi:[0,1]
	v_pk_mul_f32 v[96:97], v[38:39], v[4:5] op_sel:[1,0] op_sel_hi:[1,1]
	v_pk_fma_f32 v[94:95], v[40:41], v[6:7], v[94:95] op_sel:[0,0,0] op_sel_hi:[0,1,1]
	v_pk_fma_f32 v[96:97], v[40:41], v[8:9], v[96:97] op_sel:[1,0,0] op_sel_hi:[1,1,1]
	v_pk_fma_f32 v[94:95], v[42:43], v[10:11], v[94:95] op_sel:[0,0,0] op_sel_hi:[0,1,1]
	v_pk_fma_f32 v[96:97], v[42:43], v[12:13], v[96:97] op_sel:[1,0,0] op_sel_hi:[1,1,1]
	v_pk_fma_f32 v[94:95], v[44:45], v[14:15], v[94:95] op_sel:[0,0,0] op_sel_hi:[0,1,1]
	v_pk_fma_f32 v[96:97], v[44:45], v[16:17], v[96:97] op_sel:[1,0,0] op_sel_hi:[1,1,1]
	v_pk_mul_f32 v[112:113], v[26:27], v[2:3] op_sel:[0,0] op_sel_hi:[0,1]
	v_pk_add_f32 v[94:95], v[94:95], v[96:97]
	v_pk_mul_f32 v[114:115], v[26:27], v[4:5] op_sel:[1,0] op_sel_hi:[1,1]
	v_pk_fma_f32 v[112:113], v[28:29], v[6:7], v[112:113] op_sel:[0,0,0] op_sel_hi:[0,1,1]
	v_add_f32_dpp v94, v94, v94 quad_perm:[1,0,3,2] row_mask:0xf bank_mask:0xf
	v_add_f32_dpp v95, v95, v95 quad_perm:[1,0,3,2] row_mask:0xf bank_mask:0xf
	v_pk_fma_f32 v[114:115], v[28:29], v[8:9], v[114:115] op_sel:[1,0,0] op_sel_hi:[1,1,1]
	v_add_f32_dpp v94, v94, v94 quad_perm:[2,3,0,1] row_mask:0xf bank_mask:0xf
	v_add_f32_dpp v95, v95, v95 quad_perm:[2,3,0,1] row_mask:0xf bank_mask:0xf
	v_pk_fma_f32 v[112:113], v[30:31], v[10:11], v[112:113] op_sel:[0,0,0] op_sel_hi:[0,1,1]
	v_add_f32_dpp v94, v94, v94 row_half_mirror row_mask:0xf bank_mask:0xf
	v_add_f32_dpp v95, v95, v95 row_half_mirror row_mask:0xf bank_mask:0xf
	v_pk_fma_f32 v[114:115], v[30:31], v[12:13], v[114:115] op_sel:[1,0,0] op_sel_hi:[1,1,1]
	v_add_f32_dpp v94, v94, v94 row_mirror row_mask:0xf bank_mask:0xf
	v_add_f32_dpp v95, v95, v95 row_mirror row_mask:0xf bank_mask:0xf
	v_pk_fma_f32 v[112:113], v[32:33], v[14:15], v[112:113] op_sel:[0,0,0] op_sel_hi:[0,1,1]
	v_pk_fma_f32 v[114:115], v[32:33], v[16:17], v[114:115] op_sel:[1,0,0] op_sel_hi:[1,1,1]
	s_nop 0
	v_pk_add_f32 v[112:113], v[112:113], v[114:115]
	v_pk_fma_f32 v[98:99], v[56:57], v[94:95], v[54:55] op_sel:[1,0,0] op_sel_hi:[1,1,1] neg_lo:[1,0,0] neg_hi:[1,0,0]
	s_nop 0
	v_pk_mul_f32 v[106:107], v[56:57], v[98:99] op_sel:[0,0] op_sel_hi:[0,1]
	ds_write_b64 v102, v[112:113] offset:18432
	ds_read_b128 v[18:21], v100 offset:12672
	ds_read_b128 v[22:25], v100 offset:12688
	ds_read_b128 v[26:29], v100 offset:13200
	ds_read_b128 v[30:33], v100 offset:13216
	ds_read_b64 v[34:35], v101 offset:35328
	ds_read_b64 v[36:37], v117 offset:37984
	v_pk_mul_f32 v[78:79], v[38:39], v[106:107] op_sel:[0,0] op_sel_hi:[0,1]
	v_pk_mul_f32 v[80:81], v[38:39], v[106:107] op_sel:[1,0] op_sel_hi:[1,1]
	v_pk_mul_f32 v[82:83], v[40:41], v[106:107] op_sel:[0,0] op_sel_hi:[0,1]
	v_pk_mul_f32 v[84:85], v[40:41], v[106:107] op_sel:[1,0] op_sel_hi:[1,1]
	v_pk_fma_f32 v[2:3], v[2:3], v[56:57], v[78:79] op_sel:[0,1,0] op_sel_hi:[1,1,1]
	v_pk_fma_f32 v[4:5], v[4:5], v[56:57], v[80:81] op_sel:[0,1,0] op_sel_hi:[1,1,1]
	v_pk_fma_f32 v[6:7], v[6:7], v[56:57], v[82:83] op_sel:[0,1,0] op_sel_hi:[1,1,1]
	v_pk_fma_f32 v[8:9], v[8:9], v[56:57], v[84:85] op_sel:[0,1,0] op_sel_hi:[1,1,1]
	v_pk_mul_f32 v[86:87], v[42:43], v[106:107] op_sel:[0,0] op_sel_hi:[0,1]
	v_pk_mul_f32 v[88:89], v[42:43], v[106:107] op_sel:[1,0] op_sel_hi:[1,1]
	v_pk_mul_f32 v[90:91], v[44:45], v[106:107] op_sel:[0,0] op_sel_hi:[0,1]
	v_pk_mul_f32 v[92:93], v[44:45], v[106:107] op_sel:[1,0] op_sel_hi:[1,1]
	v_pk_fma_f32 v[10:11], v[10:11], v[56:57], v[86:87] op_sel:[0,1,0] op_sel_hi:[1,1,1]
	v_pk_fma_f32 v[12:13], v[12:13], v[56:57], v[88:89] op_sel:[0,1,0] op_sel_hi:[1,1,1]
	v_pk_fma_f32 v[14:15], v[14:15], v[56:57], v[90:91] op_sel:[0,1,0] op_sel_hi:[1,1,1]
	v_pk_fma_f32 v[16:17], v[16:17], v[56:57], v[92:93] op_sel:[0,1,0] op_sel_hi:[1,1,1]
	s_waitcnt lgkmcnt(7)
	v_pk_mul_f32 v[94:95], v[58:59], v[2:3] op_sel:[0,0] op_sel_hi:[0,1]
	v_pk_mul_f32 v[96:97], v[58:59], v[4:5] op_sel:[1,0] op_sel_hi:[1,1]
	v_pk_fma_f32 v[94:95], v[60:61], v[6:7], v[94:95] op_sel:[0,0,0] op_sel_hi:[0,1,1]
	v_pk_fma_f32 v[96:97], v[60:61], v[8:9], v[96:97] op_sel:[1,0,0] op_sel_hi:[1,1,1]
	v_pk_fma_f32 v[94:95], v[62:63], v[10:11], v[94:95] op_sel:[0,0,0] op_sel_hi:[0,1,1]
	v_pk_fma_f32 v[96:97], v[62:63], v[12:13], v[96:97] op_sel:[1,0,0] op_sel_hi:[1,1,1]
	v_pk_fma_f32 v[94:95], v[64:65], v[14:15], v[94:95] op_sel:[0,0,0] op_sel_hi:[0,1,1]
	v_pk_fma_f32 v[96:97], v[64:65], v[16:17], v[96:97] op_sel:[1,0,0] op_sel_hi:[1,1,1]
	v_pk_mul_f32 v[108:109], v[46:47], v[2:3] op_sel:[0,0] op_sel_hi:[0,1]
	v_pk_add_f32 v[94:95], v[94:95], v[96:97]
	v_pk_mul_f32 v[110:111], v[46:47], v[4:5] op_sel:[1,0] op_sel_hi:[1,1]
	v_pk_fma_f32 v[108:109], v[48:49], v[6:7], v[108:109] op_sel:[0,0,0] op_sel_hi:[0,1,1]
	v_add_f32_dpp v94, v94, v94 quad_perm:[1,0,3,2] row_mask:0xf bank_mask:0xf
	v_add_f32_dpp v95, v95, v95 quad_perm:[1,0,3,2] row_mask:0xf bank_mask:0xf
	v_pk_fma_f32 v[110:111], v[48:49], v[8:9], v[110:111] op_sel:[1,0,0] op_sel_hi:[1,1,1]
	v_add_f32_dpp v94, v94, v94 quad_perm:[2,3,0,1] row_mask:0xf bank_mask:0xf
	v_add_f32_dpp v95, v95, v95 quad_perm:[2,3,0,1] row_mask:0xf bank_mask:0xf
	v_pk_fma_f32 v[108:109], v[50:51], v[10:11], v[108:109] op_sel:[0,0,0] op_sel_hi:[0,1,1]
	v_add_f32_dpp v94, v94, v94 row_half_mirror row_mask:0xf bank_mask:0xf
	v_add_f32_dpp v95, v95, v95 row_half_mirror row_mask:0xf bank_mask:0xf
	v_pk_fma_f32 v[110:111], v[50:51], v[12:13], v[110:111] op_sel:[1,0,0] op_sel_hi:[1,1,1]
	v_add_f32_dpp v94, v94, v94 row_mirror row_mask:0xf bank_mask:0xf
	v_add_f32_dpp v95, v95, v95 row_mirror row_mask:0xf bank_mask:0xf
	v_pk_fma_f32 v[108:109], v[52:53], v[14:15], v[108:109] op_sel:[0,0,0] op_sel_hi:[0,1,1]
	v_pk_fma_f32 v[110:111], v[52:53], v[16:17], v[110:111] op_sel:[1,0,0] op_sel_hi:[1,1,1]
	s_nop 0
	v_pk_add_f32 v[108:109], v[108:109], v[110:111]
	v_pk_fma_f32 v[98:99], v[76:77], v[94:95], v[74:75] op_sel:[1,0,0] op_sel_hi:[1,1,1] neg_lo:[1,0,0] neg_hi:[1,0,0]
	s_nop 0
	v_pk_mul_f32 v[106:107], v[76:77], v[98:99] op_sel:[0,0] op_sel_hi:[0,1]
	ds_write_b64 v102, v[108:109] offset:20480
	ds_read_b128 v[38:41], v100 offset:13728
	ds_read_b128 v[42:45], v100 offset:13744
	ds_read_b128 v[46:49], v100 offset:14256
	ds_read_b128 v[50:53], v100 offset:14272
	ds_read_b64 v[54:55], v101 offset:35456
	ds_read_b64 v[56:57], v117 offset:37992
	v_pk_mul_f32 v[78:79], v[58:59], v[106:107] op_sel:[0,0] op_sel_hi:[0,1]
	v_pk_mul_f32 v[80:81], v[58:59], v[106:107] op_sel:[1,0] op_sel_hi:[1,1]
	v_pk_mul_f32 v[82:83], v[60:61], v[106:107] op_sel:[0,0] op_sel_hi:[0,1]
	v_pk_mul_f32 v[84:85], v[60:61], v[106:107] op_sel:[1,0] op_sel_hi:[1,1]
	v_pk_fma_f32 v[2:3], v[2:3], v[76:77], v[78:79] op_sel:[0,1,0] op_sel_hi:[1,1,1]
	v_pk_fma_f32 v[4:5], v[4:5], v[76:77], v[80:81] op_sel:[0,1,0] op_sel_hi:[1,1,1]
	v_pk_fma_f32 v[6:7], v[6:7], v[76:77], v[82:83] op_sel:[0,1,0] op_sel_hi:[1,1,1]
	v_pk_fma_f32 v[8:9], v[8:9], v[76:77], v[84:85] op_sel:[0,1,0] op_sel_hi:[1,1,1]
	v_pk_mul_f32 v[86:87], v[62:63], v[106:107] op_sel:[0,0] op_sel_hi:[0,1]
	v_pk_mul_f32 v[88:89], v[62:63], v[106:107] op_sel:[1,0] op_sel_hi:[1,1]
	v_pk_mul_f32 v[90:91], v[64:65], v[106:107] op_sel:[0,0] op_sel_hi:[0,1]
	v_pk_mul_f32 v[92:93], v[64:65], v[106:107] op_sel:[1,0] op_sel_hi:[1,1]
	v_pk_fma_f32 v[10:11], v[10:11], v[76:77], v[86:87] op_sel:[0,1,0] op_sel_hi:[1,1,1]
	v_pk_fma_f32 v[12:13], v[12:13], v[76:77], v[88:89] op_sel:[0,1,0] op_sel_hi:[1,1,1]
	v_pk_fma_f32 v[14:15], v[14:15], v[76:77], v[90:91] op_sel:[0,1,0] op_sel_hi:[1,1,1]
	v_pk_fma_f32 v[16:17], v[16:17], v[76:77], v[92:93] op_sel:[0,1,0] op_sel_hi:[1,1,1]
	s_waitcnt lgkmcnt(7)
	v_pk_mul_f32 v[94:95], v[18:19], v[2:3] op_sel:[0,0] op_sel_hi:[0,1]
	v_pk_mul_f32 v[96:97], v[18:19], v[4:5] op_sel:[1,0] op_sel_hi:[1,1]
	v_pk_fma_f32 v[94:95], v[20:21], v[6:7], v[94:95] op_sel:[0,0,0] op_sel_hi:[0,1,1]
	v_pk_fma_f32 v[96:97], v[20:21], v[8:9], v[96:97] op_sel:[1,0,0] op_sel_hi:[1,1,1]
	v_pk_fma_f32 v[94:95], v[22:23], v[10:11], v[94:95] op_sel:[0,0,0] op_sel_hi:[0,1,1]
	v_pk_fma_f32 v[96:97], v[22:23], v[12:13], v[96:97] op_sel:[1,0,0] op_sel_hi:[1,1,1]
	v_pk_fma_f32 v[94:95], v[24:25], v[14:15], v[94:95] op_sel:[0,0,0] op_sel_hi:[0,1,1]
	v_pk_fma_f32 v[96:97], v[24:25], v[16:17], v[96:97] op_sel:[1,0,0] op_sel_hi:[1,1,1]
	v_pk_mul_f32 v[112:113], v[66:67], v[2:3] op_sel:[0,0] op_sel_hi:[0,1]
	v_pk_add_f32 v[94:95], v[94:95], v[96:97]
	v_pk_mul_f32 v[114:115], v[66:67], v[4:5] op_sel:[1,0] op_sel_hi:[1,1]
	v_pk_fma_f32 v[112:113], v[68:69], v[6:7], v[112:113] op_sel:[0,0,0] op_sel_hi:[0,1,1]
	v_add_f32_dpp v94, v94, v94 quad_perm:[1,0,3,2] row_mask:0xf bank_mask:0xf
	v_add_f32_dpp v95, v95, v95 quad_perm:[1,0,3,2] row_mask:0xf bank_mask:0xf
	v_pk_fma_f32 v[114:115], v[68:69], v[8:9], v[114:115] op_sel:[1,0,0] op_sel_hi:[1,1,1]
	v_add_f32_dpp v94, v94, v94 quad_perm:[2,3,0,1] row_mask:0xf bank_mask:0xf
	v_add_f32_dpp v95, v95, v95 quad_perm:[2,3,0,1] row_mask:0xf bank_mask:0xf
	v_pk_fma_f32 v[112:113], v[70:71], v[10:11], v[112:113] op_sel:[0,0,0] op_sel_hi:[0,1,1]
	v_add_f32_dpp v94, v94, v94 row_half_mirror row_mask:0xf bank_mask:0xf
	v_add_f32_dpp v95, v95, v95 row_half_mirror row_mask:0xf bank_mask:0xf
	v_pk_fma_f32 v[114:115], v[70:71], v[12:13], v[114:115] op_sel:[1,0,0] op_sel_hi:[1,1,1]
	v_add_f32_dpp v94, v94, v94 row_mirror row_mask:0xf bank_mask:0xf
	v_add_f32_dpp v95, v95, v95 row_mirror row_mask:0xf bank_mask:0xf
	v_pk_fma_f32 v[112:113], v[72:73], v[14:15], v[112:113] op_sel:[0,0,0] op_sel_hi:[0,1,1]
	v_pk_fma_f32 v[114:115], v[72:73], v[16:17], v[114:115] op_sel:[1,0,0] op_sel_hi:[1,1,1]
	s_nop 0
	v_pk_add_f32 v[112:113], v[112:113], v[114:115]
	v_pk_fma_f32 v[98:99], v[36:37], v[94:95], v[34:35] op_sel:[1,0,0] op_sel_hi:[1,1,1] neg_lo:[1,0,0] neg_hi:[1,0,0]
	s_nop 0
	v_pk_mul_f32 v[106:107], v[36:37], v[98:99] op_sel:[0,0] op_sel_hi:[0,1]
	ds_write_b64 v102, v[112:113] offset:22528
	ds_read_b128 v[58:61], v100 offset:14784
	ds_read_b128 v[62:65], v100 offset:14800
	ds_read_b128 v[66:69], v100 offset:15312
	ds_read_b128 v[70:73], v100 offset:15328
	ds_read_b64 v[74:75], v101 offset:35584
	ds_read_b64 v[76:77], v117 offset:38000
	v_pk_mul_f32 v[78:79], v[18:19], v[106:107] op_sel:[0,0] op_sel_hi:[0,1]
	v_pk_mul_f32 v[80:81], v[18:19], v[106:107] op_sel:[1,0] op_sel_hi:[1,1]
	v_pk_mul_f32 v[82:83], v[20:21], v[106:107] op_sel:[0,0] op_sel_hi:[0,1]
	v_pk_mul_f32 v[84:85], v[20:21], v[106:107] op_sel:[1,0] op_sel_hi:[1,1]
	v_pk_fma_f32 v[2:3], v[2:3], v[36:37], v[78:79] op_sel:[0,1,0] op_sel_hi:[1,1,1]
	v_pk_fma_f32 v[4:5], v[4:5], v[36:37], v[80:81] op_sel:[0,1,0] op_sel_hi:[1,1,1]
	v_pk_fma_f32 v[6:7], v[6:7], v[36:37], v[82:83] op_sel:[0,1,0] op_sel_hi:[1,1,1]
	v_pk_fma_f32 v[8:9], v[8:9], v[36:37], v[84:85] op_sel:[0,1,0] op_sel_hi:[1,1,1]
	v_pk_mul_f32 v[86:87], v[22:23], v[106:107] op_sel:[0,0] op_sel_hi:[0,1]
	v_pk_mul_f32 v[88:89], v[22:23], v[106:107] op_sel:[1,0] op_sel_hi:[1,1]
	v_pk_mul_f32 v[90:91], v[24:25], v[106:107] op_sel:[0,0] op_sel_hi:[0,1]
	v_pk_mul_f32 v[92:93], v[24:25], v[106:107] op_sel:[1,0] op_sel_hi:[1,1]
	v_pk_fma_f32 v[10:11], v[10:11], v[36:37], v[86:87] op_sel:[0,1,0] op_sel_hi:[1,1,1]
	v_pk_fma_f32 v[12:13], v[12:13], v[36:37], v[88:89] op_sel:[0,1,0] op_sel_hi:[1,1,1]
	v_pk_fma_f32 v[14:15], v[14:15], v[36:37], v[90:91] op_sel:[0,1,0] op_sel_hi:[1,1,1]
	v_pk_fma_f32 v[16:17], v[16:17], v[36:37], v[92:93] op_sel:[0,1,0] op_sel_hi:[1,1,1]
	s_waitcnt lgkmcnt(7)
	v_pk_mul_f32 v[94:95], v[38:39], v[2:3] op_sel:[0,0] op_sel_hi:[0,1]
	v_pk_mul_f32 v[96:97], v[38:39], v[4:5] op_sel:[1,0] op_sel_hi:[1,1]
	v_pk_fma_f32 v[94:95], v[40:41], v[6:7], v[94:95] op_sel:[0,0,0] op_sel_hi:[0,1,1]
	v_pk_fma_f32 v[96:97], v[40:41], v[8:9], v[96:97] op_sel:[1,0,0] op_sel_hi:[1,1,1]
	v_pk_fma_f32 v[94:95], v[42:43], v[10:11], v[94:95] op_sel:[0,0,0] op_sel_hi:[0,1,1]
	v_pk_fma_f32 v[96:97], v[42:43], v[12:13], v[96:97] op_sel:[1,0,0] op_sel_hi:[1,1,1]
	v_pk_fma_f32 v[94:95], v[44:45], v[14:15], v[94:95] op_sel:[0,0,0] op_sel_hi:[0,1,1]
	v_pk_fma_f32 v[96:97], v[44:45], v[16:17], v[96:97] op_sel:[1,0,0] op_sel_hi:[1,1,1]
	v_pk_mul_f32 v[108:109], v[26:27], v[2:3] op_sel:[0,0] op_sel_hi:[0,1]
	v_pk_add_f32 v[94:95], v[94:95], v[96:97]
	v_pk_mul_f32 v[110:111], v[26:27], v[4:5] op_sel:[1,0] op_sel_hi:[1,1]
	v_pk_fma_f32 v[108:109], v[28:29], v[6:7], v[108:109] op_sel:[0,0,0] op_sel_hi:[0,1,1]
	v_add_f32_dpp v94, v94, v94 quad_perm:[1,0,3,2] row_mask:0xf bank_mask:0xf
	v_add_f32_dpp v95, v95, v95 quad_perm:[1,0,3,2] row_mask:0xf bank_mask:0xf
	v_pk_fma_f32 v[110:111], v[28:29], v[8:9], v[110:111] op_sel:[1,0,0] op_sel_hi:[1,1,1]
	v_add_f32_dpp v94, v94, v94 quad_perm:[2,3,0,1] row_mask:0xf bank_mask:0xf
	v_add_f32_dpp v95, v95, v95 quad_perm:[2,3,0,1] row_mask:0xf bank_mask:0xf
	v_pk_fma_f32 v[108:109], v[30:31], v[10:11], v[108:109] op_sel:[0,0,0] op_sel_hi:[0,1,1]
	v_add_f32_dpp v94, v94, v94 row_half_mirror row_mask:0xf bank_mask:0xf
	v_add_f32_dpp v95, v95, v95 row_half_mirror row_mask:0xf bank_mask:0xf
	v_pk_fma_f32 v[110:111], v[30:31], v[12:13], v[110:111] op_sel:[1,0,0] op_sel_hi:[1,1,1]
	v_add_f32_dpp v94, v94, v94 row_mirror row_mask:0xf bank_mask:0xf
	v_add_f32_dpp v95, v95, v95 row_mirror row_mask:0xf bank_mask:0xf
	v_pk_fma_f32 v[108:109], v[32:33], v[14:15], v[108:109] op_sel:[0,0,0] op_sel_hi:[0,1,1]
	v_pk_fma_f32 v[110:111], v[32:33], v[16:17], v[110:111] op_sel:[1,0,0] op_sel_hi:[1,1,1]
	s_nop 0
	v_pk_add_f32 v[108:109], v[108:109], v[110:111]
	v_pk_fma_f32 v[98:99], v[56:57], v[94:95], v[54:55] op_sel:[1,0,0] op_sel_hi:[1,1,1] neg_lo:[1,0,0] neg_hi:[1,0,0]
	s_nop 0
	v_pk_mul_f32 v[106:107], v[56:57], v[98:99] op_sel:[0,0] op_sel_hi:[0,1]
	ds_write_b64 v102, v[108:109] offset:24576
	ds_read_b128 v[18:21], v100 offset:15840
	ds_read_b128 v[22:25], v100 offset:15856
	ds_read_b128 v[26:29], v100 offset:16368
	ds_read_b128 v[30:33], v100 offset:16384
	ds_read_b64 v[34:35], v101 offset:35712
	ds_read_b64 v[36:37], v117 offset:38008
	v_pk_mul_f32 v[78:79], v[38:39], v[106:107] op_sel:[0,0] op_sel_hi:[0,1]
	v_pk_mul_f32 v[80:81], v[38:39], v[106:107] op_sel:[1,0] op_sel_hi:[1,1]
	v_pk_mul_f32 v[82:83], v[40:41], v[106:107] op_sel:[0,0] op_sel_hi:[0,1]
	v_pk_mul_f32 v[84:85], v[40:41], v[106:107] op_sel:[1,0] op_sel_hi:[1,1]
	v_pk_fma_f32 v[2:3], v[2:3], v[56:57], v[78:79] op_sel:[0,1,0] op_sel_hi:[1,1,1]
	v_pk_fma_f32 v[4:5], v[4:5], v[56:57], v[80:81] op_sel:[0,1,0] op_sel_hi:[1,1,1]
	v_pk_fma_f32 v[6:7], v[6:7], v[56:57], v[82:83] op_sel:[0,1,0] op_sel_hi:[1,1,1]
	v_pk_fma_f32 v[8:9], v[8:9], v[56:57], v[84:85] op_sel:[0,1,0] op_sel_hi:[1,1,1]
	v_pk_mul_f32 v[86:87], v[42:43], v[106:107] op_sel:[0,0] op_sel_hi:[0,1]
	v_pk_mul_f32 v[88:89], v[42:43], v[106:107] op_sel:[1,0] op_sel_hi:[1,1]
	v_pk_mul_f32 v[90:91], v[44:45], v[106:107] op_sel:[0,0] op_sel_hi:[0,1]
	v_pk_mul_f32 v[92:93], v[44:45], v[106:107] op_sel:[1,0] op_sel_hi:[1,1]
	v_pk_fma_f32 v[10:11], v[10:11], v[56:57], v[86:87] op_sel:[0,1,0] op_sel_hi:[1,1,1]
	v_pk_fma_f32 v[12:13], v[12:13], v[56:57], v[88:89] op_sel:[0,1,0] op_sel_hi:[1,1,1]
	v_pk_fma_f32 v[14:15], v[14:15], v[56:57], v[90:91] op_sel:[0,1,0] op_sel_hi:[1,1,1]
	v_pk_fma_f32 v[16:17], v[16:17], v[56:57], v[92:93] op_sel:[0,1,0] op_sel_hi:[1,1,1]
	s_waitcnt lgkmcnt(7)
	v_pk_mul_f32 v[94:95], v[58:59], v[2:3] op_sel:[0,0] op_sel_hi:[0,1]
	v_pk_mul_f32 v[96:97], v[58:59], v[4:5] op_sel:[1,0] op_sel_hi:[1,1]
	v_pk_fma_f32 v[94:95], v[60:61], v[6:7], v[94:95] op_sel:[0,0,0] op_sel_hi:[0,1,1]
	v_pk_fma_f32 v[96:97], v[60:61], v[8:9], v[96:97] op_sel:[1,0,0] op_sel_hi:[1,1,1]
	v_pk_fma_f32 v[94:95], v[62:63], v[10:11], v[94:95] op_sel:[0,0,0] op_sel_hi:[0,1,1]
	v_pk_fma_f32 v[96:97], v[62:63], v[12:13], v[96:97] op_sel:[1,0,0] op_sel_hi:[1,1,1]
	v_pk_fma_f32 v[94:95], v[64:65], v[14:15], v[94:95] op_sel:[0,0,0] op_sel_hi:[0,1,1]
	v_pk_fma_f32 v[96:97], v[64:65], v[16:17], v[96:97] op_sel:[1,0,0] op_sel_hi:[1,1,1]
	v_pk_mul_f32 v[112:113], v[46:47], v[2:3] op_sel:[0,0] op_sel_hi:[0,1]
	v_pk_add_f32 v[94:95], v[94:95], v[96:97]
	v_pk_mul_f32 v[114:115], v[46:47], v[4:5] op_sel:[1,0] op_sel_hi:[1,1]
	v_pk_fma_f32 v[112:113], v[48:49], v[6:7], v[112:113] op_sel:[0,0,0] op_sel_hi:[0,1,1]
	v_add_f32_dpp v94, v94, v94 quad_perm:[1,0,3,2] row_mask:0xf bank_mask:0xf
	v_add_f32_dpp v95, v95, v95 quad_perm:[1,0,3,2] row_mask:0xf bank_mask:0xf
	v_pk_fma_f32 v[114:115], v[48:49], v[8:9], v[114:115] op_sel:[1,0,0] op_sel_hi:[1,1,1]
	v_add_f32_dpp v94, v94, v94 quad_perm:[2,3,0,1] row_mask:0xf bank_mask:0xf
	v_add_f32_dpp v95, v95, v95 quad_perm:[2,3,0,1] row_mask:0xf bank_mask:0xf
	v_pk_fma_f32 v[112:113], v[50:51], v[10:11], v[112:113] op_sel:[0,0,0] op_sel_hi:[0,1,1]
	v_add_f32_dpp v94, v94, v94 row_half_mirror row_mask:0xf bank_mask:0xf
	v_add_f32_dpp v95, v95, v95 row_half_mirror row_mask:0xf bank_mask:0xf
	v_pk_fma_f32 v[114:115], v[50:51], v[12:13], v[114:115] op_sel:[1,0,0] op_sel_hi:[1,1,1]
	v_add_f32_dpp v94, v94, v94 row_mirror row_mask:0xf bank_mask:0xf
	v_add_f32_dpp v95, v95, v95 row_mirror row_mask:0xf bank_mask:0xf
	v_pk_fma_f32 v[112:113], v[52:53], v[14:15], v[112:113] op_sel:[0,0,0] op_sel_hi:[0,1,1]
	v_pk_fma_f32 v[114:115], v[52:53], v[16:17], v[114:115] op_sel:[1,0,0] op_sel_hi:[1,1,1]
	s_nop 0
	v_pk_add_f32 v[112:113], v[112:113], v[114:115]
	v_pk_fma_f32 v[98:99], v[76:77], v[94:95], v[74:75] op_sel:[1,0,0] op_sel_hi:[1,1,1] neg_lo:[1,0,0] neg_hi:[1,0,0]
	s_nop 0
	v_pk_mul_f32 v[106:107], v[76:77], v[98:99] op_sel:[0,0] op_sel_hi:[0,1]
	ds_write_b64 v102, v[112:113] offset:26624
	v_pk_mul_f32 v[78:79], v[58:59], v[106:107] op_sel:[0,0] op_sel_hi:[0,1]
	v_pk_mul_f32 v[80:81], v[58:59], v[106:107] op_sel:[1,0] op_sel_hi:[1,1]
	v_pk_mul_f32 v[82:83], v[60:61], v[106:107] op_sel:[0,0] op_sel_hi:[0,1]
	v_pk_mul_f32 v[84:85], v[60:61], v[106:107] op_sel:[1,0] op_sel_hi:[1,1]
	v_pk_fma_f32 v[2:3], v[2:3], v[76:77], v[78:79] op_sel:[0,1,0] op_sel_hi:[1,1,1]
	v_pk_fma_f32 v[4:5], v[4:5], v[76:77], v[80:81] op_sel:[0,1,0] op_sel_hi:[1,1,1]
	v_pk_fma_f32 v[6:7], v[6:7], v[76:77], v[82:83] op_sel:[0,1,0] op_sel_hi:[1,1,1]
	v_pk_fma_f32 v[8:9], v[8:9], v[76:77], v[84:85] op_sel:[0,1,0] op_sel_hi:[1,1,1]
	v_pk_mul_f32 v[86:87], v[62:63], v[106:107] op_sel:[0,0] op_sel_hi:[0,1]
	v_pk_mul_f32 v[88:89], v[62:63], v[106:107] op_sel:[1,0] op_sel_hi:[1,1]
	v_pk_mul_f32 v[90:91], v[64:65], v[106:107] op_sel:[0,0] op_sel_hi:[0,1]
	v_pk_mul_f32 v[92:93], v[64:65], v[106:107] op_sel:[1,0] op_sel_hi:[1,1]
	v_pk_fma_f32 v[10:11], v[10:11], v[76:77], v[86:87] op_sel:[0,1,0] op_sel_hi:[1,1,1]
	v_pk_fma_f32 v[12:13], v[12:13], v[76:77], v[88:89] op_sel:[0,1,0] op_sel_hi:[1,1,1]
	v_pk_fma_f32 v[14:15], v[14:15], v[76:77], v[90:91] op_sel:[0,1,0] op_sel_hi:[1,1,1]
	v_pk_fma_f32 v[16:17], v[16:17], v[76:77], v[92:93] op_sel:[0,1,0] op_sel_hi:[1,1,1]
	s_waitcnt lgkmcnt(1)
	v_pk_mul_f32 v[94:95], v[18:19], v[2:3] op_sel:[0,0] op_sel_hi:[0,1]
	v_pk_mul_f32 v[96:97], v[18:19], v[4:5] op_sel:[1,0] op_sel_hi:[1,1]
	v_pk_fma_f32 v[94:95], v[20:21], v[6:7], v[94:95] op_sel:[0,0,0] op_sel_hi:[0,1,1]
	v_pk_fma_f32 v[96:97], v[20:21], v[8:9], v[96:97] op_sel:[1,0,0] op_sel_hi:[1,1,1]
	v_pk_fma_f32 v[94:95], v[22:23], v[10:11], v[94:95] op_sel:[0,0,0] op_sel_hi:[0,1,1]
	v_pk_fma_f32 v[96:97], v[22:23], v[12:13], v[96:97] op_sel:[1,0,0] op_sel_hi:[1,1,1]
	v_pk_fma_f32 v[94:95], v[24:25], v[14:15], v[94:95] op_sel:[0,0,0] op_sel_hi:[0,1,1]
	v_pk_fma_f32 v[96:97], v[24:25], v[16:17], v[96:97] op_sel:[1,0,0] op_sel_hi:[1,1,1]
	v_pk_mul_f32 v[108:109], v[66:67], v[2:3] op_sel:[0,0] op_sel_hi:[0,1]
	v_pk_add_f32 v[94:95], v[94:95], v[96:97]
	v_pk_mul_f32 v[110:111], v[66:67], v[4:5] op_sel:[1,0] op_sel_hi:[1,1]
	v_pk_fma_f32 v[108:109], v[68:69], v[6:7], v[108:109] op_sel:[0,0,0] op_sel_hi:[0,1,1]
	v_add_f32_dpp v94, v94, v94 quad_perm:[1,0,3,2] row_mask:0xf bank_mask:0xf
	v_add_f32_dpp v95, v95, v95 quad_perm:[1,0,3,2] row_mask:0xf bank_mask:0xf
	v_pk_fma_f32 v[110:111], v[68:69], v[8:9], v[110:111] op_sel:[1,0,0] op_sel_hi:[1,1,1]
	v_add_f32_dpp v94, v94, v94 quad_perm:[2,3,0,1] row_mask:0xf bank_mask:0xf
	v_add_f32_dpp v95, v95, v95 quad_perm:[2,3,0,1] row_mask:0xf bank_mask:0xf
	v_pk_fma_f32 v[108:109], v[70:71], v[10:11], v[108:109] op_sel:[0,0,0] op_sel_hi:[0,1,1]
	v_add_f32_dpp v94, v94, v94 row_half_mirror row_mask:0xf bank_mask:0xf
	v_add_f32_dpp v95, v95, v95 row_half_mirror row_mask:0xf bank_mask:0xf
	v_pk_fma_f32 v[110:111], v[70:71], v[12:13], v[110:111] op_sel:[1,0,0] op_sel_hi:[1,1,1]
	v_add_f32_dpp v94, v94, v94 row_mirror row_mask:0xf bank_mask:0xf
	v_add_f32_dpp v95, v95, v95 row_mirror row_mask:0xf bank_mask:0xf
	v_pk_fma_f32 v[108:109], v[72:73], v[14:15], v[108:109] op_sel:[0,0,0] op_sel_hi:[0,1,1]
	v_pk_fma_f32 v[110:111], v[72:73], v[16:17], v[110:111] op_sel:[1,0,0] op_sel_hi:[1,1,1]
	s_nop 0
	v_pk_add_f32 v[108:109], v[108:109], v[110:111]
	v_pk_fma_f32 v[98:99], v[36:37], v[94:95], v[34:35] op_sel:[1,0,0] op_sel_hi:[1,1,1] neg_lo:[1,0,0] neg_hi:[1,0,0]
	s_nop 0
	v_pk_mul_f32 v[106:107], v[36:37], v[98:99] op_sel:[0,0] op_sel_hi:[0,1]
	ds_write_b64 v102, v[108:109] offset:28672
	v_pk_mul_f32 v[78:79], v[18:19], v[106:107] op_sel:[0,0] op_sel_hi:[0,1]
	v_pk_mul_f32 v[80:81], v[18:19], v[106:107] op_sel:[1,0] op_sel_hi:[1,1]
	v_pk_mul_f32 v[82:83], v[20:21], v[106:107] op_sel:[0,0] op_sel_hi:[0,1]
	v_pk_mul_f32 v[84:85], v[20:21], v[106:107] op_sel:[1,0] op_sel_hi:[1,1]
	v_pk_fma_f32 v[2:3], v[2:3], v[36:37], v[78:79] op_sel:[0,1,0] op_sel_hi:[1,1,1]
	v_pk_fma_f32 v[4:5], v[4:5], v[36:37], v[80:81] op_sel:[0,1,0] op_sel_hi:[1,1,1]
	v_pk_fma_f32 v[6:7], v[6:7], v[36:37], v[82:83] op_sel:[0,1,0] op_sel_hi:[1,1,1]
	v_pk_fma_f32 v[8:9], v[8:9], v[36:37], v[84:85] op_sel:[0,1,0] op_sel_hi:[1,1,1]
	v_pk_mul_f32 v[86:87], v[22:23], v[106:107] op_sel:[0,0] op_sel_hi:[0,1]
	v_pk_mul_f32 v[88:89], v[22:23], v[106:107] op_sel:[1,0] op_sel_hi:[1,1]
	v_pk_mul_f32 v[90:91], v[24:25], v[106:107] op_sel:[0,0] op_sel_hi:[0,1]
	v_pk_mul_f32 v[92:93], v[24:25], v[106:107] op_sel:[1,0] op_sel_hi:[1,1]
	v_pk_fma_f32 v[10:11], v[10:11], v[36:37], v[86:87] op_sel:[0,1,0] op_sel_hi:[1,1,1]
	v_pk_fma_f32 v[12:13], v[12:13], v[36:37], v[88:89] op_sel:[0,1,0] op_sel_hi:[1,1,1]
	v_pk_fma_f32 v[14:15], v[14:15], v[36:37], v[90:91] op_sel:[0,1,0] op_sel_hi:[1,1,1]
	v_pk_fma_f32 v[16:17], v[16:17], v[36:37], v[92:93] op_sel:[0,1,0] op_sel_hi:[1,1,1]
	v_pk_mul_f32 v[112:113], v[26:27], v[2:3] op_sel:[0,0] op_sel_hi:[0,1]
	v_pk_mul_f32 v[114:115], v[26:27], v[4:5] op_sel:[1,0] op_sel_hi:[1,1]
	v_pk_fma_f32 v[112:113], v[28:29], v[6:7], v[112:113] op_sel:[0,0,0] op_sel_hi:[0,1,1]
	v_pk_fma_f32 v[114:115], v[28:29], v[8:9], v[114:115] op_sel:[1,0,0] op_sel_hi:[1,1,1]
	v_pk_fma_f32 v[112:113], v[30:31], v[10:11], v[112:113] op_sel:[0,0,0] op_sel_hi:[0,1,1]
	v_pk_fma_f32 v[114:115], v[30:31], v[12:13], v[114:115] op_sel:[1,0,0] op_sel_hi:[1,1,1]
	v_pk_fma_f32 v[112:113], v[32:33], v[14:15], v[112:113] op_sel:[0,0,0] op_sel_hi:[0,1,1]
	v_pk_fma_f32 v[114:115], v[32:33], v[16:17], v[114:115] op_sel:[1,0,0] op_sel_hi:[1,1,1]
	s_nop 0
	v_pk_add_f32 v[112:113], v[112:113], v[114:115]
	s_nop 0
	ds_write_b64 v102, v[112:113] offset:30720
	s_waitcnt lgkmcnt(0)
	s_barrier
	ds_read_b128 v[18:21], v100 offset:16896
	ds_read_b128 v[22:25], v100 offset:16912
	ds_read_b128 v[26:29], v100 offset:17424
	ds_read_b128 v[30:33], v100 offset:17440
	ds_read_b64 v[34:35], v101 offset:35840
	ds_read_b64 v[36:37], v117 offset:38016
	ds_read_b128 v[38:41], v100 offset:17952
	ds_read_b128 v[42:45], v100 offset:17968
	ds_read_b128 v[46:49], v100 offset:18480
	ds_read_b128 v[50:53], v100 offset:18496
	ds_read_b64 v[54:55], v101 offset:35968
	ds_read_b64 v[56:57], v117 offset:38024
	ds_read_b128 v[58:61], v103 offset:0
	v_xor_b32_e32 v116, 16, v103
	ds_read_b128 v[62:65], v116 offset:0
	v_xor_b32_e32 v116, 32, v103
	ds_read_b128 v[66:69], v116 offset:0
	v_xor_b32_e32 v116, 48, v103
	ds_read_b128 v[70:73], v116 offset:0
	v_xor_b32_e32 v116, 64, v103
	ds_read_b128 v[74:77], v116 offset:0
	v_xor_b32_e32 v116, 80, v103
	ds_read_b128 v[78:81], v116 offset:0
	v_xor_b32_e32 v116, 96, v103
	ds_read_b128 v[82:85], v116 offset:0
	v_xor_b32_e32 v116, 112, v103
	ds_read_b128 v[86:89], v116 offset:0
	s_waitcnt lgkmcnt(0)
	v_pk_add_f32 v[58:59], v[58:59], v[60:61]
	v_pk_add_f32 v[62:63], v[62:63], v[64:65]
	v_pk_add_f32 v[66:67], v[66:67], v[68:69]
	v_pk_add_f32 v[70:71], v[70:71], v[72:73]
	v_pk_add_f32 v[74:75], v[74:75], v[76:77]
	v_pk_add_f32 v[78:79], v[78:79], v[80:81]
	v_pk_add_f32 v[82:83], v[82:83], v[84:85]
	v_pk_add_f32 v[86:87], v[86:87], v[88:89]
	v_pk_add_f32 v[58:59], v[58:59], v[62:63]
	v_pk_add_f32 v[66:67], v[66:67], v[70:71]
	v_pk_add_f32 v[74:75], v[74:75], v[78:79]
	v_pk_add_f32 v[82:83], v[82:83], v[86:87]
	v_pk_add_f32 v[58:59], v[58:59], v[66:67]
	v_pk_add_f32 v[74:75], v[74:75], v[82:83]
	s_nop 0
	v_pk_add_f32 v[58:59], v[58:59], v[74:75]
	s_nop 0
	v_cvt_pk_bf16_f32 v90, v58, v59
	global_store_dword v[104:105], v90, off
	v_lshl_add_u64 v[104:105], v[104:105], 0, s[52:53]
	v_pk_mul_f32 v[94:95], v[18:19], v[2:3] op_sel:[0,0] op_sel_hi:[0,1]
	v_pk_mul_f32 v[96:97], v[18:19], v[4:5] op_sel:[1,0] op_sel_hi:[1,1]
	v_pk_fma_f32 v[94:95], v[20:21], v[6:7], v[94:95] op_sel:[0,0,0] op_sel_hi:[0,1,1]
	v_pk_fma_f32 v[96:97], v[20:21], v[8:9], v[96:97] op_sel:[1,0,0] op_sel_hi:[1,1,1]
	v_pk_fma_f32 v[94:95], v[22:23], v[10:11], v[94:95] op_sel:[0,0,0] op_sel_hi:[0,1,1]
	v_pk_fma_f32 v[96:97], v[22:23], v[12:13], v[96:97] op_sel:[1,0,0] op_sel_hi:[1,1,1]
	v_pk_fma_f32 v[94:95], v[24:25], v[14:15], v[94:95] op_sel:[0,0,0] op_sel_hi:[0,1,1]
	v_pk_fma_f32 v[96:97], v[24:25], v[16:17], v[96:97] op_sel:[1,0,0] op_sel_hi:[1,1,1]
	s_nop 0
	v_pk_add_f32 v[94:95], v[94:95], v[96:97]
	s_nop 1
	v_add_f32_dpp v94, v94, v94 quad_perm:[1,0,3,2] row_mask:0xf bank_mask:0xf
	v_add_f32_dpp v95, v95, v95 quad_perm:[1,0,3,2] row_mask:0xf bank_mask:0xf
	s_nop 0
	v_add_f32_dpp v94, v94, v94 quad_perm:[2,3,0,1] row_mask:0xf bank_mask:0xf
	v_add_f32_dpp v95, v95, v95 quad_perm:[2,3,0,1] row_mask:0xf bank_mask:0xf
	s_nop 0
	v_add_f32_dpp v94, v94, v94 row_half_mirror row_mask:0xf bank_mask:0xf
	v_add_f32_dpp v95, v95, v95 row_half_mirror row_mask:0xf bank_mask:0xf
	s_nop 0
	v_add_f32_dpp v94, v94, v94 row_mirror row_mask:0xf bank_mask:0xf
	v_add_f32_dpp v95, v95, v95 row_mirror row_mask:0xf bank_mask:0xf
	v_pk_fma_f32 v[98:99], v[36:37], v[94:95], v[34:35] op_sel:[1,0,0] op_sel_hi:[1,1,1] neg_lo:[1,0,0] neg_hi:[1,0,0]
	s_nop 0
	v_pk_mul_f32 v[106:107], v[36:37], v[98:99] op_sel:[0,0] op_sel_hi:[0,1]
	ds_read_b128 v[58:61], v100 offset:19008
	ds_read_b128 v[62:65], v100 offset:19024
	ds_read_b128 v[66:69], v100 offset:19536
	ds_read_b128 v[70:73], v100 offset:19552
	ds_read_b64 v[74:75], v101 offset:36096
	ds_read_b64 v[76:77], v117 offset:38032
	v_pk_mul_f32 v[78:79], v[18:19], v[106:107] op_sel:[0,0] op_sel_hi:[0,1]
	v_pk_mul_f32 v[80:81], v[18:19], v[106:107] op_sel:[1,0] op_sel_hi:[1,1]
	v_pk_mul_f32 v[82:83], v[20:21], v[106:107] op_sel:[0,0] op_sel_hi:[0,1]
	v_pk_mul_f32 v[84:85], v[20:21], v[106:107] op_sel:[1,0] op_sel_hi:[1,1]
	v_pk_fma_f32 v[2:3], v[2:3], v[36:37], v[78:79] op_sel:[0,1,0] op_sel_hi:[1,1,1]
	v_pk_fma_f32 v[4:5], v[4:5], v[36:37], v[80:81] op_sel:[0,1,0] op_sel_hi:[1,1,1]
	v_pk_fma_f32 v[6:7], v[6:7], v[36:37], v[82:83] op_sel:[0,1,0] op_sel_hi:[1,1,1]
	v_pk_fma_f32 v[8:9], v[8:9], v[36:37], v[84:85] op_sel:[0,1,0] op_sel_hi:[1,1,1]
	v_pk_mul_f32 v[86:87], v[22:23], v[106:107] op_sel:[0,0] op_sel_hi:[0,1]
	v_pk_mul_f32 v[88:89], v[22:23], v[106:107] op_sel:[1,0] op_sel_hi:[1,1]
	v_pk_mul_f32 v[90:91], v[24:25], v[106:107] op_sel:[0,0] op_sel_hi:[0,1]
	v_pk_mul_f32 v[92:93], v[24:25], v[106:107] op_sel:[1,0] op_sel_hi:[1,1]
	v_pk_fma_f32 v[10:11], v[10:11], v[36:37], v[86:87] op_sel:[0,1,0] op_sel_hi:[1,1,1]
	v_pk_fma_f32 v[12:13], v[12:13], v[36:37], v[88:89] op_sel:[0,1,0] op_sel_hi:[1,1,1]
	v_pk_fma_f32 v[14:15], v[14:15], v[36:37], v[90:91] op_sel:[0,1,0] op_sel_hi:[1,1,1]
	v_pk_fma_f32 v[16:17], v[16:17], v[36:37], v[92:93] op_sel:[0,1,0] op_sel_hi:[1,1,1]
	v_pk_mul_f32 v[94:95], v[38:39], v[2:3] op_sel:[0,0] op_sel_hi:[0,1]
	v_pk_mul_f32 v[96:97], v[38:39], v[4:5] op_sel:[1,0] op_sel_hi:[1,1]
	v_pk_fma_f32 v[94:95], v[40:41], v[6:7], v[94:95] op_sel:[0,0,0] op_sel_hi:[0,1,1]
	v_pk_fma_f32 v[96:97], v[40:41], v[8:9], v[96:97] op_sel:[1,0,0] op_sel_hi:[1,1,1]
	v_pk_fma_f32 v[94:95], v[42:43], v[10:11], v[94:95] op_sel:[0,0,0] op_sel_hi:[0,1,1]
	v_pk_fma_f32 v[96:97], v[42:43], v[12:13], v[96:97] op_sel:[1,0,0] op_sel_hi:[1,1,1]
	v_pk_fma_f32 v[94:95], v[44:45], v[14:15], v[94:95] op_sel:[0,0,0] op_sel_hi:[0,1,1]
	v_pk_fma_f32 v[96:97], v[44:45], v[16:17], v[96:97] op_sel:[1,0,0] op_sel_hi:[1,1,1]
	v_pk_mul_f32 v[108:109], v[26:27], v[2:3] op_sel:[0,0] op_sel_hi:[0,1]
	v_pk_add_f32 v[94:95], v[94:95], v[96:97]
	v_pk_mul_f32 v[110:111], v[26:27], v[4:5] op_sel:[1,0] op_sel_hi:[1,1]
	v_pk_fma_f32 v[108:109], v[28:29], v[6:7], v[108:109] op_sel:[0,0,0] op_sel_hi:[0,1,1]
	v_add_f32_dpp v94, v94, v94 quad_perm:[1,0,3,2] row_mask:0xf bank_mask:0xf
	v_add_f32_dpp v95, v95, v95 quad_perm:[1,0,3,2] row_mask:0xf bank_mask:0xf
	v_pk_fma_f32 v[110:111], v[28:29], v[8:9], v[110:111] op_sel:[1,0,0] op_sel_hi:[1,1,1]
	v_add_f32_dpp v94, v94, v94 quad_perm:[2,3,0,1] row_mask:0xf bank_mask:0xf
	v_add_f32_dpp v95, v95, v95 quad_perm:[2,3,0,1] row_mask:0xf bank_mask:0xf
	v_pk_fma_f32 v[108:109], v[30:31], v[10:11], v[108:109] op_sel:[0,0,0] op_sel_hi:[0,1,1]
	v_add_f32_dpp v94, v94, v94 row_half_mirror row_mask:0xf bank_mask:0xf
	v_add_f32_dpp v95, v95, v95 row_half_mirror row_mask:0xf bank_mask:0xf
	v_pk_fma_f32 v[110:111], v[30:31], v[12:13], v[110:111] op_sel:[1,0,0] op_sel_hi:[1,1,1]
	v_add_f32_dpp v94, v94, v94 row_mirror row_mask:0xf bank_mask:0xf
	v_add_f32_dpp v95, v95, v95 row_mirror row_mask:0xf bank_mask:0xf
	v_pk_fma_f32 v[108:109], v[32:33], v[14:15], v[108:109] op_sel:[0,0,0] op_sel_hi:[0,1,1]
	v_pk_fma_f32 v[110:111], v[32:33], v[16:17], v[110:111] op_sel:[1,0,0] op_sel_hi:[1,1,1]
	s_nop 0
	v_pk_add_f32 v[108:109], v[108:109], v[110:111]
	v_pk_fma_f32 v[98:99], v[56:57], v[94:95], v[54:55] op_sel:[1,0,0] op_sel_hi:[1,1,1] neg_lo:[1,0,0] neg_hi:[1,0,0]
	s_nop 0
	v_pk_mul_f32 v[106:107], v[56:57], v[98:99] op_sel:[0,0] op_sel_hi:[0,1]
	ds_write_b64 v102, v[108:109] offset:32768
	ds_read_b128 v[18:21], v100 offset:20064
	ds_read_b128 v[22:25], v100 offset:20080
	ds_read_b128 v[26:29], v100 offset:20592
	ds_read_b128 v[30:33], v100 offset:20608
	ds_read_b64 v[34:35], v101 offset:36224
	ds_read_b64 v[36:37], v117 offset:38040
	v_pk_mul_f32 v[78:79], v[38:39], v[106:107] op_sel:[0,0] op_sel_hi:[0,1]
	v_pk_mul_f32 v[80:81], v[38:39], v[106:107] op_sel:[1,0] op_sel_hi:[1,1]
	v_pk_mul_f32 v[82:83], v[40:41], v[106:107] op_sel:[0,0] op_sel_hi:[0,1]
	v_pk_mul_f32 v[84:85], v[40:41], v[106:107] op_sel:[1,0] op_sel_hi:[1,1]
	v_pk_fma_f32 v[2:3], v[2:3], v[56:57], v[78:79] op_sel:[0,1,0] op_sel_hi:[1,1,1]
	v_pk_fma_f32 v[4:5], v[4:5], v[56:57], v[80:81] op_sel:[0,1,0] op_sel_hi:[1,1,1]
	v_pk_fma_f32 v[6:7], v[6:7], v[56:57], v[82:83] op_sel:[0,1,0] op_sel_hi:[1,1,1]
	v_pk_fma_f32 v[8:9], v[8:9], v[56:57], v[84:85] op_sel:[0,1,0] op_sel_hi:[1,1,1]
	v_pk_mul_f32 v[86:87], v[42:43], v[106:107] op_sel:[0,0] op_sel_hi:[0,1]
	v_pk_mul_f32 v[88:89], v[42:43], v[106:107] op_sel:[1,0] op_sel_hi:[1,1]
	v_pk_mul_f32 v[90:91], v[44:45], v[106:107] op_sel:[0,0] op_sel_hi:[0,1]
	v_pk_mul_f32 v[92:93], v[44:45], v[106:107] op_sel:[1,0] op_sel_hi:[1,1]
	v_pk_fma_f32 v[10:11], v[10:11], v[56:57], v[86:87] op_sel:[0,1,0] op_sel_hi:[1,1,1]
	v_pk_fma_f32 v[12:13], v[12:13], v[56:57], v[88:89] op_sel:[0,1,0] op_sel_hi:[1,1,1]
	v_pk_fma_f32 v[14:15], v[14:15], v[56:57], v[90:91] op_sel:[0,1,0] op_sel_hi:[1,1,1]
	v_pk_fma_f32 v[16:17], v[16:17], v[56:57], v[92:93] op_sel:[0,1,0] op_sel_hi:[1,1,1]
	s_waitcnt lgkmcnt(7)
	v_pk_mul_f32 v[94:95], v[58:59], v[2:3] op_sel:[0,0] op_sel_hi:[0,1]
	v_pk_mul_f32 v[96:97], v[58:59], v[4:5] op_sel:[1,0] op_sel_hi:[1,1]
	v_pk_fma_f32 v[94:95], v[60:61], v[6:7], v[94:95] op_sel:[0,0,0] op_sel_hi:[0,1,1]
	v_pk_fma_f32 v[96:97], v[60:61], v[8:9], v[96:97] op_sel:[1,0,0] op_sel_hi:[1,1,1]
	v_pk_fma_f32 v[94:95], v[62:63], v[10:11], v[94:95] op_sel:[0,0,0] op_sel_hi:[0,1,1]
	v_pk_fma_f32 v[96:97], v[62:63], v[12:13], v[96:97] op_sel:[1,0,0] op_sel_hi:[1,1,1]
	v_pk_fma_f32 v[94:95], v[64:65], v[14:15], v[94:95] op_sel:[0,0,0] op_sel_hi:[0,1,1]
	v_pk_fma_f32 v[96:97], v[64:65], v[16:17], v[96:97] op_sel:[1,0,0] op_sel_hi:[1,1,1]
	v_pk_mul_f32 v[112:113], v[46:47], v[2:3] op_sel:[0,0] op_sel_hi:[0,1]
	v_pk_add_f32 v[94:95], v[94:95], v[96:97]
	v_pk_mul_f32 v[114:115], v[46:47], v[4:5] op_sel:[1,0] op_sel_hi:[1,1]
	v_pk_fma_f32 v[112:113], v[48:49], v[6:7], v[112:113] op_sel:[0,0,0] op_sel_hi:[0,1,1]
	v_add_f32_dpp v94, v94, v94 quad_perm:[1,0,3,2] row_mask:0xf bank_mask:0xf
	v_add_f32_dpp v95, v95, v95 quad_perm:[1,0,3,2] row_mask:0xf bank_mask:0xf
	v_pk_fma_f32 v[114:115], v[48:49], v[8:9], v[114:115] op_sel:[1,0,0] op_sel_hi:[1,1,1]
	v_add_f32_dpp v94, v94, v94 quad_perm:[2,3,0,1] row_mask:0xf bank_mask:0xf
	v_add_f32_dpp v95, v95, v95 quad_perm:[2,3,0,1] row_mask:0xf bank_mask:0xf
	v_pk_fma_f32 v[112:113], v[50:51], v[10:11], v[112:113] op_sel:[0,0,0] op_sel_hi:[0,1,1]
	v_add_f32_dpp v94, v94, v94 row_half_mirror row_mask:0xf bank_mask:0xf
	v_add_f32_dpp v95, v95, v95 row_half_mirror row_mask:0xf bank_mask:0xf
	v_pk_fma_f32 v[114:115], v[50:51], v[12:13], v[114:115] op_sel:[1,0,0] op_sel_hi:[1,1,1]
	v_add_f32_dpp v94, v94, v94 row_mirror row_mask:0xf bank_mask:0xf
	v_add_f32_dpp v95, v95, v95 row_mirror row_mask:0xf bank_mask:0xf
	v_pk_fma_f32 v[112:113], v[52:53], v[14:15], v[112:113] op_sel:[0,0,0] op_sel_hi:[0,1,1]
	v_pk_fma_f32 v[114:115], v[52:53], v[16:17], v[114:115] op_sel:[1,0,0] op_sel_hi:[1,1,1]
	s_nop 0
	v_pk_add_f32 v[112:113], v[112:113], v[114:115]
	v_pk_fma_f32 v[98:99], v[76:77], v[94:95], v[74:75] op_sel:[1,0,0] op_sel_hi:[1,1,1] neg_lo:[1,0,0] neg_hi:[1,0,0]
	s_nop 0
	v_pk_mul_f32 v[106:107], v[76:77], v[98:99] op_sel:[0,0] op_sel_hi:[0,1]
	ds_write_b64 v102, v[112:113] offset:34816
	ds_read_b128 v[38:41], v100 offset:21120
	ds_read_b128 v[42:45], v100 offset:21136
	ds_read_b128 v[46:49], v100 offset:21648
	ds_read_b128 v[50:53], v100 offset:21664
	ds_read_b64 v[54:55], v101 offset:36352
	ds_read_b64 v[56:57], v117 offset:38048
	v_pk_mul_f32 v[78:79], v[58:59], v[106:107] op_sel:[0,0] op_sel_hi:[0,1]
	v_pk_mul_f32 v[80:81], v[58:59], v[106:107] op_sel:[1,0] op_sel_hi:[1,1]
	v_pk_mul_f32 v[82:83], v[60:61], v[106:107] op_sel:[0,0] op_sel_hi:[0,1]
	v_pk_mul_f32 v[84:85], v[60:61], v[106:107] op_sel:[1,0] op_sel_hi:[1,1]
	v_pk_fma_f32 v[2:3], v[2:3], v[76:77], v[78:79] op_sel:[0,1,0] op_sel_hi:[1,1,1]
	v_pk_fma_f32 v[4:5], v[4:5], v[76:77], v[80:81] op_sel:[0,1,0] op_sel_hi:[1,1,1]
	v_pk_fma_f32 v[6:7], v[6:7], v[76:77], v[82:83] op_sel:[0,1,0] op_sel_hi:[1,1,1]
	v_pk_fma_f32 v[8:9], v[8:9], v[76:77], v[84:85] op_sel:[0,1,0] op_sel_hi:[1,1,1]
	v_pk_mul_f32 v[86:87], v[62:63], v[106:107] op_sel:[0,0] op_sel_hi:[0,1]
	v_pk_mul_f32 v[88:89], v[62:63], v[106:107] op_sel:[1,0] op_sel_hi:[1,1]
	v_pk_mul_f32 v[90:91], v[64:65], v[106:107] op_sel:[0,0] op_sel_hi:[0,1]
	v_pk_mul_f32 v[92:93], v[64:65], v[106:107] op_sel:[1,0] op_sel_hi:[1,1]
	v_pk_fma_f32 v[10:11], v[10:11], v[76:77], v[86:87] op_sel:[0,1,0] op_sel_hi:[1,1,1]
	v_pk_fma_f32 v[12:13], v[12:13], v[76:77], v[88:89] op_sel:[0,1,0] op_sel_hi:[1,1,1]
	v_pk_fma_f32 v[14:15], v[14:15], v[76:77], v[90:91] op_sel:[0,1,0] op_sel_hi:[1,1,1]
	v_pk_fma_f32 v[16:17], v[16:17], v[76:77], v[92:93] op_sel:[0,1,0] op_sel_hi:[1,1,1]
	s_waitcnt lgkmcnt(7)
	v_pk_mul_f32 v[94:95], v[18:19], v[2:3] op_sel:[0,0] op_sel_hi:[0,1]
	v_pk_mul_f32 v[96:97], v[18:19], v[4:5] op_sel:[1,0] op_sel_hi:[1,1]
	v_pk_fma_f32 v[94:95], v[20:21], v[6:7], v[94:95] op_sel:[0,0,0] op_sel_hi:[0,1,1]
	v_pk_fma_f32 v[96:97], v[20:21], v[8:9], v[96:97] op_sel:[1,0,0] op_sel_hi:[1,1,1]
	v_pk_fma_f32 v[94:95], v[22:23], v[10:11], v[94:95] op_sel:[0,0,0] op_sel_hi:[0,1,1]
	v_pk_fma_f32 v[96:97], v[22:23], v[12:13], v[96:97] op_sel:[1,0,0] op_sel_hi:[1,1,1]
	v_pk_fma_f32 v[94:95], v[24:25], v[14:15], v[94:95] op_sel:[0,0,0] op_sel_hi:[0,1,1]
	v_pk_fma_f32 v[96:97], v[24:25], v[16:17], v[96:97] op_sel:[1,0,0] op_sel_hi:[1,1,1]
	v_pk_mul_f32 v[108:109], v[66:67], v[2:3] op_sel:[0,0] op_sel_hi:[0,1]
	v_pk_add_f32 v[94:95], v[94:95], v[96:97]
	v_pk_mul_f32 v[110:111], v[66:67], v[4:5] op_sel:[1,0] op_sel_hi:[1,1]
	v_pk_fma_f32 v[108:109], v[68:69], v[6:7], v[108:109] op_sel:[0,0,0] op_sel_hi:[0,1,1]
	v_add_f32_dpp v94, v94, v94 quad_perm:[1,0,3,2] row_mask:0xf bank_mask:0xf
	v_add_f32_dpp v95, v95, v95 quad_perm:[1,0,3,2] row_mask:0xf bank_mask:0xf
	v_pk_fma_f32 v[110:111], v[68:69], v[8:9], v[110:111] op_sel:[1,0,0] op_sel_hi:[1,1,1]
	v_add_f32_dpp v94, v94, v94 quad_perm:[2,3,0,1] row_mask:0xf bank_mask:0xf
	v_add_f32_dpp v95, v95, v95 quad_perm:[2,3,0,1] row_mask:0xf bank_mask:0xf
	v_pk_fma_f32 v[108:109], v[70:71], v[10:11], v[108:109] op_sel:[0,0,0] op_sel_hi:[0,1,1]
	v_add_f32_dpp v94, v94, v94 row_half_mirror row_mask:0xf bank_mask:0xf
	v_add_f32_dpp v95, v95, v95 row_half_mirror row_mask:0xf bank_mask:0xf
	v_pk_fma_f32 v[110:111], v[70:71], v[12:13], v[110:111] op_sel:[1,0,0] op_sel_hi:[1,1,1]
	v_add_f32_dpp v94, v94, v94 row_mirror row_mask:0xf bank_mask:0xf
	v_add_f32_dpp v95, v95, v95 row_mirror row_mask:0xf bank_mask:0xf
	v_pk_fma_f32 v[108:109], v[72:73], v[14:15], v[108:109] op_sel:[0,0,0] op_sel_hi:[0,1,1]
	v_pk_fma_f32 v[110:111], v[72:73], v[16:17], v[110:111] op_sel:[1,0,0] op_sel_hi:[1,1,1]
	s_nop 0
	v_pk_add_f32 v[108:109], v[108:109], v[110:111]
	v_pk_fma_f32 v[98:99], v[36:37], v[94:95], v[34:35] op_sel:[1,0,0] op_sel_hi:[1,1,1] neg_lo:[1,0,0] neg_hi:[1,0,0]
	s_nop 0
	v_pk_mul_f32 v[106:107], v[36:37], v[98:99] op_sel:[0,0] op_sel_hi:[0,1]
	ds_write_b64 v102, v[108:109] offset:36864
	ds_read_b128 v[58:61], v100 offset:22176
	ds_read_b128 v[62:65], v100 offset:22192
	ds_read_b128 v[66:69], v100 offset:22704
	ds_read_b128 v[70:73], v100 offset:22720
	ds_read_b64 v[74:75], v101 offset:36480
	ds_read_b64 v[76:77], v117 offset:38056
	v_pk_mul_f32 v[78:79], v[18:19], v[106:107] op_sel:[0,0] op_sel_hi:[0,1]
	v_pk_mul_f32 v[80:81], v[18:19], v[106:107] op_sel:[1,0] op_sel_hi:[1,1]
	v_pk_mul_f32 v[82:83], v[20:21], v[106:107] op_sel:[0,0] op_sel_hi:[0,1]
	v_pk_mul_f32 v[84:85], v[20:21], v[106:107] op_sel:[1,0] op_sel_hi:[1,1]
	v_pk_fma_f32 v[2:3], v[2:3], v[36:37], v[78:79] op_sel:[0,1,0] op_sel_hi:[1,1,1]
	v_pk_fma_f32 v[4:5], v[4:5], v[36:37], v[80:81] op_sel:[0,1,0] op_sel_hi:[1,1,1]
	v_pk_fma_f32 v[6:7], v[6:7], v[36:37], v[82:83] op_sel:[0,1,0] op_sel_hi:[1,1,1]
	v_pk_fma_f32 v[8:9], v[8:9], v[36:37], v[84:85] op_sel:[0,1,0] op_sel_hi:[1,1,1]
	v_pk_mul_f32 v[86:87], v[22:23], v[106:107] op_sel:[0,0] op_sel_hi:[0,1]
	v_pk_mul_f32 v[88:89], v[22:23], v[106:107] op_sel:[1,0] op_sel_hi:[1,1]
	v_pk_mul_f32 v[90:91], v[24:25], v[106:107] op_sel:[0,0] op_sel_hi:[0,1]
	v_pk_mul_f32 v[92:93], v[24:25], v[106:107] op_sel:[1,0] op_sel_hi:[1,1]
	v_pk_fma_f32 v[10:11], v[10:11], v[36:37], v[86:87] op_sel:[0,1,0] op_sel_hi:[1,1,1]
	v_pk_fma_f32 v[12:13], v[12:13], v[36:37], v[88:89] op_sel:[0,1,0] op_sel_hi:[1,1,1]
	v_pk_fma_f32 v[14:15], v[14:15], v[36:37], v[90:91] op_sel:[0,1,0] op_sel_hi:[1,1,1]
	v_pk_fma_f32 v[16:17], v[16:17], v[36:37], v[92:93] op_sel:[0,1,0] op_sel_hi:[1,1,1]
	s_waitcnt lgkmcnt(7)
	v_pk_mul_f32 v[94:95], v[38:39], v[2:3] op_sel:[0,0] op_sel_hi:[0,1]
	v_pk_mul_f32 v[96:97], v[38:39], v[4:5] op_sel:[1,0] op_sel_hi:[1,1]
	v_pk_fma_f32 v[94:95], v[40:41], v[6:7], v[94:95] op_sel:[0,0,0] op_sel_hi:[0,1,1]
	v_pk_fma_f32 v[96:97], v[40:41], v[8:9], v[96:97] op_sel:[1,0,0] op_sel_hi:[1,1,1]
	v_pk_fma_f32 v[94:95], v[42:43], v[10:11], v[94:95] op_sel:[0,0,0] op_sel_hi:[0,1,1]
	v_pk_fma_f32 v[96:97], v[42:43], v[12:13], v[96:97] op_sel:[1,0,0] op_sel_hi:[1,1,1]
	v_pk_fma_f32 v[94:95], v[44:45], v[14:15], v[94:95] op_sel:[0,0,0] op_sel_hi:[0,1,1]
	v_pk_fma_f32 v[96:97], v[44:45], v[16:17], v[96:97] op_sel:[1,0,0] op_sel_hi:[1,1,1]
	v_pk_mul_f32 v[112:113], v[26:27], v[2:3] op_sel:[0,0] op_sel_hi:[0,1]
	v_pk_add_f32 v[94:95], v[94:95], v[96:97]
	v_pk_mul_f32 v[114:115], v[26:27], v[4:5] op_sel:[1,0] op_sel_hi:[1,1]
	v_pk_fma_f32 v[112:113], v[28:29], v[6:7], v[112:113] op_sel:[0,0,0] op_sel_hi:[0,1,1]
	v_add_f32_dpp v94, v94, v94 quad_perm:[1,0,3,2] row_mask:0xf bank_mask:0xf
	v_add_f32_dpp v95, v95, v95 quad_perm:[1,0,3,2] row_mask:0xf bank_mask:0xf
	v_pk_fma_f32 v[114:115], v[28:29], v[8:9], v[114:115] op_sel:[1,0,0] op_sel_hi:[1,1,1]
	v_add_f32_dpp v94, v94, v94 quad_perm:[2,3,0,1] row_mask:0xf bank_mask:0xf
	v_add_f32_dpp v95, v95, v95 quad_perm:[2,3,0,1] row_mask:0xf bank_mask:0xf
	v_pk_fma_f32 v[112:113], v[30:31], v[10:11], v[112:113] op_sel:[0,0,0] op_sel_hi:[0,1,1]
	v_add_f32_dpp v94, v94, v94 row_half_mirror row_mask:0xf bank_mask:0xf
	v_add_f32_dpp v95, v95, v95 row_half_mirror row_mask:0xf bank_mask:0xf
	v_pk_fma_f32 v[114:115], v[30:31], v[12:13], v[114:115] op_sel:[1,0,0] op_sel_hi:[1,1,1]
	v_add_f32_dpp v94, v94, v94 row_mirror row_mask:0xf bank_mask:0xf
	v_add_f32_dpp v95, v95, v95 row_mirror row_mask:0xf bank_mask:0xf
	v_pk_fma_f32 v[112:113], v[32:33], v[14:15], v[112:113] op_sel:[0,0,0] op_sel_hi:[0,1,1]
	v_pk_fma_f32 v[114:115], v[32:33], v[16:17], v[114:115] op_sel:[1,0,0] op_sel_hi:[1,1,1]
	s_nop 0
	v_pk_add_f32 v[112:113], v[112:113], v[114:115]
	v_pk_fma_f32 v[98:99], v[56:57], v[94:95], v[54:55] op_sel:[1,0,0] op_sel_hi:[1,1,1] neg_lo:[1,0,0] neg_hi:[1,0,0]
	s_nop 0
	v_pk_mul_f32 v[106:107], v[56:57], v[98:99] op_sel:[0,0] op_sel_hi:[0,1]
	ds_write_b64 v102, v[112:113] offset:38912
	ds_read_b128 v[18:21], v100 offset:23232
	ds_read_b128 v[22:25], v100 offset:23248
	ds_read_b128 v[26:29], v100 offset:23760
	ds_read_b128 v[30:33], v100 offset:23776
	ds_read_b64 v[34:35], v101 offset:36608
	ds_read_b64 v[36:37], v117 offset:38064
	v_pk_mul_f32 v[78:79], v[38:39], v[106:107] op_sel:[0,0] op_sel_hi:[0,1]
	v_pk_mul_f32 v[80:81], v[38:39], v[106:107] op_sel:[1,0] op_sel_hi:[1,1]
	v_pk_mul_f32 v[82:83], v[40:41], v[106:107] op_sel:[0,0] op_sel_hi:[0,1]
	v_pk_mul_f32 v[84:85], v[40:41], v[106:107] op_sel:[1,0] op_sel_hi:[1,1]
	v_pk_fma_f32 v[2:3], v[2:3], v[56:57], v[78:79] op_sel:[0,1,0] op_sel_hi:[1,1,1]
	v_pk_fma_f32 v[4:5], v[4:5], v[56:57], v[80:81] op_sel:[0,1,0] op_sel_hi:[1,1,1]
	v_pk_fma_f32 v[6:7], v[6:7], v[56:57], v[82:83] op_sel:[0,1,0] op_sel_hi:[1,1,1]
	v_pk_fma_f32 v[8:9], v[8:9], v[56:57], v[84:85] op_sel:[0,1,0] op_sel_hi:[1,1,1]
	v_pk_mul_f32 v[86:87], v[42:43], v[106:107] op_sel:[0,0] op_sel_hi:[0,1]
	v_pk_mul_f32 v[88:89], v[42:43], v[106:107] op_sel:[1,0] op_sel_hi:[1,1]
	v_pk_mul_f32 v[90:91], v[44:45], v[106:107] op_sel:[0,0] op_sel_hi:[0,1]
	v_pk_mul_f32 v[92:93], v[44:45], v[106:107] op_sel:[1,0] op_sel_hi:[1,1]
	v_pk_fma_f32 v[10:11], v[10:11], v[56:57], v[86:87] op_sel:[0,1,0] op_sel_hi:[1,1,1]
	v_pk_fma_f32 v[12:13], v[12:13], v[56:57], v[88:89] op_sel:[0,1,0] op_sel_hi:[1,1,1]
	v_pk_fma_f32 v[14:15], v[14:15], v[56:57], v[90:91] op_sel:[0,1,0] op_sel_hi:[1,1,1]
	v_pk_fma_f32 v[16:17], v[16:17], v[56:57], v[92:93] op_sel:[0,1,0] op_sel_hi:[1,1,1]
	s_waitcnt lgkmcnt(7)
	v_pk_mul_f32 v[94:95], v[58:59], v[2:3] op_sel:[0,0] op_sel_hi:[0,1]
	v_pk_mul_f32 v[96:97], v[58:59], v[4:5] op_sel:[1,0] op_sel_hi:[1,1]
	v_pk_fma_f32 v[94:95], v[60:61], v[6:7], v[94:95] op_sel:[0,0,0] op_sel_hi:[0,1,1]
	v_pk_fma_f32 v[96:97], v[60:61], v[8:9], v[96:97] op_sel:[1,0,0] op_sel_hi:[1,1,1]
	v_pk_fma_f32 v[94:95], v[62:63], v[10:11], v[94:95] op_sel:[0,0,0] op_sel_hi:[0,1,1]
	v_pk_fma_f32 v[96:97], v[62:63], v[12:13], v[96:97] op_sel:[1,0,0] op_sel_hi:[1,1,1]
	v_pk_fma_f32 v[94:95], v[64:65], v[14:15], v[94:95] op_sel:[0,0,0] op_sel_hi:[0,1,1]
	v_pk_fma_f32 v[96:97], v[64:65], v[16:17], v[96:97] op_sel:[1,0,0] op_sel_hi:[1,1,1]
	v_pk_mul_f32 v[108:109], v[46:47], v[2:3] op_sel:[0,0] op_sel_hi:[0,1]
	v_pk_add_f32 v[94:95], v[94:95], v[96:97]
	v_pk_mul_f32 v[110:111], v[46:47], v[4:5] op_sel:[1,0] op_sel_hi:[1,1]
	v_pk_fma_f32 v[108:109], v[48:49], v[6:7], v[108:109] op_sel:[0,0,0] op_sel_hi:[0,1,1]
	v_add_f32_dpp v94, v94, v94 quad_perm:[1,0,3,2] row_mask:0xf bank_mask:0xf
	v_add_f32_dpp v95, v95, v95 quad_perm:[1,0,3,2] row_mask:0xf bank_mask:0xf
	v_pk_fma_f32 v[110:111], v[48:49], v[8:9], v[110:111] op_sel:[1,0,0] op_sel_hi:[1,1,1]
	v_add_f32_dpp v94, v94, v94 quad_perm:[2,3,0,1] row_mask:0xf bank_mask:0xf
	v_add_f32_dpp v95, v95, v95 quad_perm:[2,3,0,1] row_mask:0xf bank_mask:0xf
	v_pk_fma_f32 v[108:109], v[50:51], v[10:11], v[108:109] op_sel:[0,0,0] op_sel_hi:[0,1,1]
	v_add_f32_dpp v94, v94, v94 row_half_mirror row_mask:0xf bank_mask:0xf
	v_add_f32_dpp v95, v95, v95 row_half_mirror row_mask:0xf bank_mask:0xf
	v_pk_fma_f32 v[110:111], v[50:51], v[12:13], v[110:111] op_sel:[1,0,0] op_sel_hi:[1,1,1]
	v_add_f32_dpp v94, v94, v94 row_mirror row_mask:0xf bank_mask:0xf
	v_add_f32_dpp v95, v95, v95 row_mirror row_mask:0xf bank_mask:0xf
	v_pk_fma_f32 v[108:109], v[52:53], v[14:15], v[108:109] op_sel:[0,0,0] op_sel_hi:[0,1,1]
	v_pk_fma_f32 v[110:111], v[52:53], v[16:17], v[110:111] op_sel:[1,0,0] op_sel_hi:[1,1,1]
	s_nop 0
	v_pk_add_f32 v[108:109], v[108:109], v[110:111]
	v_pk_fma_f32 v[98:99], v[76:77], v[94:95], v[74:75] op_sel:[1,0,0] op_sel_hi:[1,1,1] neg_lo:[1,0,0] neg_hi:[1,0,0]
	s_nop 0
	v_pk_mul_f32 v[106:107], v[76:77], v[98:99] op_sel:[0,0] op_sel_hi:[0,1]
	ds_write_b64 v102, v[108:109] offset:40960
	ds_read_b128 v[38:41], v100 offset:24288
	ds_read_b128 v[42:45], v100 offset:24304
	ds_read_b128 v[46:49], v100 offset:24816
	ds_read_b128 v[50:53], v100 offset:24832
	ds_read_b64 v[54:55], v101 offset:36736
	ds_read_b64 v[56:57], v117 offset:38072
	v_pk_mul_f32 v[78:79], v[58:59], v[106:107] op_sel:[0,0] op_sel_hi:[0,1]
	v_pk_mul_f32 v[80:81], v[58:59], v[106:107] op_sel:[1,0] op_sel_hi:[1,1]
	v_pk_mul_f32 v[82:83], v[60:61], v[106:107] op_sel:[0,0] op_sel_hi:[0,1]
	v_pk_mul_f32 v[84:85], v[60:61], v[106:107] op_sel:[1,0] op_sel_hi:[1,1]
	v_pk_fma_f32 v[2:3], v[2:3], v[76:77], v[78:79] op_sel:[0,1,0] op_sel_hi:[1,1,1]
	v_pk_fma_f32 v[4:5], v[4:5], v[76:77], v[80:81] op_sel:[0,1,0] op_sel_hi:[1,1,1]
	v_pk_fma_f32 v[6:7], v[6:7], v[76:77], v[82:83] op_sel:[0,1,0] op_sel_hi:[1,1,1]
	v_pk_fma_f32 v[8:9], v[8:9], v[76:77], v[84:85] op_sel:[0,1,0] op_sel_hi:[1,1,1]
	v_pk_mul_f32 v[86:87], v[62:63], v[106:107] op_sel:[0,0] op_sel_hi:[0,1]
	v_pk_mul_f32 v[88:89], v[62:63], v[106:107] op_sel:[1,0] op_sel_hi:[1,1]
	v_pk_mul_f32 v[90:91], v[64:65], v[106:107] op_sel:[0,0] op_sel_hi:[0,1]
	v_pk_mul_f32 v[92:93], v[64:65], v[106:107] op_sel:[1,0] op_sel_hi:[1,1]
	v_pk_fma_f32 v[10:11], v[10:11], v[76:77], v[86:87] op_sel:[0,1,0] op_sel_hi:[1,1,1]
	v_pk_fma_f32 v[12:13], v[12:13], v[76:77], v[88:89] op_sel:[0,1,0] op_sel_hi:[1,1,1]
	v_pk_fma_f32 v[14:15], v[14:15], v[76:77], v[90:91] op_sel:[0,1,0] op_sel_hi:[1,1,1]
	v_pk_fma_f32 v[16:17], v[16:17], v[76:77], v[92:93] op_sel:[0,1,0] op_sel_hi:[1,1,1]
	s_waitcnt lgkmcnt(7)
	v_pk_mul_f32 v[94:95], v[18:19], v[2:3] op_sel:[0,0] op_sel_hi:[0,1]
	v_pk_mul_f32 v[96:97], v[18:19], v[4:5] op_sel:[1,0] op_sel_hi:[1,1]
	v_pk_fma_f32 v[94:95], v[20:21], v[6:7], v[94:95] op_sel:[0,0,0] op_sel_hi:[0,1,1]
	v_pk_fma_f32 v[96:97], v[20:21], v[8:9], v[96:97] op_sel:[1,0,0] op_sel_hi:[1,1,1]
	v_pk_fma_f32 v[94:95], v[22:23], v[10:11], v[94:95] op_sel:[0,0,0] op_sel_hi:[0,1,1]
	v_pk_fma_f32 v[96:97], v[22:23], v[12:13], v[96:97] op_sel:[1,0,0] op_sel_hi:[1,1,1]
	v_pk_fma_f32 v[94:95], v[24:25], v[14:15], v[94:95] op_sel:[0,0,0] op_sel_hi:[0,1,1]
	v_pk_fma_f32 v[96:97], v[24:25], v[16:17], v[96:97] op_sel:[1,0,0] op_sel_hi:[1,1,1]
	v_pk_mul_f32 v[112:113], v[66:67], v[2:3] op_sel:[0,0] op_sel_hi:[0,1]
	v_pk_add_f32 v[94:95], v[94:95], v[96:97]
	v_pk_mul_f32 v[114:115], v[66:67], v[4:5] op_sel:[1,0] op_sel_hi:[1,1]
	v_pk_fma_f32 v[112:113], v[68:69], v[6:7], v[112:113] op_sel:[0,0,0] op_sel_hi:[0,1,1]
	v_add_f32_dpp v94, v94, v94 quad_perm:[1,0,3,2] row_mask:0xf bank_mask:0xf
	v_add_f32_dpp v95, v95, v95 quad_perm:[1,0,3,2] row_mask:0xf bank_mask:0xf
	v_pk_fma_f32 v[114:115], v[68:69], v[8:9], v[114:115] op_sel:[1,0,0] op_sel_hi:[1,1,1]
	v_add_f32_dpp v94, v94, v94 quad_perm:[2,3,0,1] row_mask:0xf bank_mask:0xf
	v_add_f32_dpp v95, v95, v95 quad_perm:[2,3,0,1] row_mask:0xf bank_mask:0xf
	v_pk_fma_f32 v[112:113], v[70:71], v[10:11], v[112:113] op_sel:[0,0,0] op_sel_hi:[0,1,1]
	v_add_f32_dpp v94, v94, v94 row_half_mirror row_mask:0xf bank_mask:0xf
	v_add_f32_dpp v95, v95, v95 row_half_mirror row_mask:0xf bank_mask:0xf
	v_pk_fma_f32 v[114:115], v[70:71], v[12:13], v[114:115] op_sel:[1,0,0] op_sel_hi:[1,1,1]
	v_add_f32_dpp v94, v94, v94 row_mirror row_mask:0xf bank_mask:0xf
	v_add_f32_dpp v95, v95, v95 row_mirror row_mask:0xf bank_mask:0xf
	v_pk_fma_f32 v[112:113], v[72:73], v[14:15], v[112:113] op_sel:[0,0,0] op_sel_hi:[0,1,1]
	v_pk_fma_f32 v[114:115], v[72:73], v[16:17], v[114:115] op_sel:[1,0,0] op_sel_hi:[1,1,1]
	s_nop 0
	v_pk_add_f32 v[112:113], v[112:113], v[114:115]
	v_pk_fma_f32 v[98:99], v[36:37], v[94:95], v[34:35] op_sel:[1,0,0] op_sel_hi:[1,1,1] neg_lo:[1,0,0] neg_hi:[1,0,0]
	s_nop 0
	v_pk_mul_f32 v[106:107], v[36:37], v[98:99] op_sel:[0,0] op_sel_hi:[0,1]
	ds_write_b64 v102, v[112:113] offset:43008
	ds_read_b128 v[58:61], v100 offset:25344
	ds_read_b128 v[62:65], v100 offset:25360
	ds_read_b128 v[66:69], v100 offset:25872
	ds_read_b128 v[70:73], v100 offset:25888
	ds_read_b64 v[74:75], v101 offset:36864
	ds_read_b64 v[76:77], v117 offset:38080
	v_pk_mul_f32 v[78:79], v[18:19], v[106:107] op_sel:[0,0] op_sel_hi:[0,1]
	v_pk_mul_f32 v[80:81], v[18:19], v[106:107] op_sel:[1,0] op_sel_hi:[1,1]
	v_pk_mul_f32 v[82:83], v[20:21], v[106:107] op_sel:[0,0] op_sel_hi:[0,1]
	v_pk_mul_f32 v[84:85], v[20:21], v[106:107] op_sel:[1,0] op_sel_hi:[1,1]
	v_pk_fma_f32 v[2:3], v[2:3], v[36:37], v[78:79] op_sel:[0,1,0] op_sel_hi:[1,1,1]
	v_pk_fma_f32 v[4:5], v[4:5], v[36:37], v[80:81] op_sel:[0,1,0] op_sel_hi:[1,1,1]
	v_pk_fma_f32 v[6:7], v[6:7], v[36:37], v[82:83] op_sel:[0,1,0] op_sel_hi:[1,1,1]
	v_pk_fma_f32 v[8:9], v[8:9], v[36:37], v[84:85] op_sel:[0,1,0] op_sel_hi:[1,1,1]
	v_pk_mul_f32 v[86:87], v[22:23], v[106:107] op_sel:[0,0] op_sel_hi:[0,1]
	v_pk_mul_f32 v[88:89], v[22:23], v[106:107] op_sel:[1,0] op_sel_hi:[1,1]
	v_pk_mul_f32 v[90:91], v[24:25], v[106:107] op_sel:[0,0] op_sel_hi:[0,1]
	v_pk_mul_f32 v[92:93], v[24:25], v[106:107] op_sel:[1,0] op_sel_hi:[1,1]
	v_pk_fma_f32 v[10:11], v[10:11], v[36:37], v[86:87] op_sel:[0,1,0] op_sel_hi:[1,1,1]
	v_pk_fma_f32 v[12:13], v[12:13], v[36:37], v[88:89] op_sel:[0,1,0] op_sel_hi:[1,1,1]
	v_pk_fma_f32 v[14:15], v[14:15], v[36:37], v[90:91] op_sel:[0,1,0] op_sel_hi:[1,1,1]
	v_pk_fma_f32 v[16:17], v[16:17], v[36:37], v[92:93] op_sel:[0,1,0] op_sel_hi:[1,1,1]
	s_waitcnt lgkmcnt(7)
	v_pk_mul_f32 v[94:95], v[38:39], v[2:3] op_sel:[0,0] op_sel_hi:[0,1]
	v_pk_mul_f32 v[96:97], v[38:39], v[4:5] op_sel:[1,0] op_sel_hi:[1,1]
	v_pk_fma_f32 v[94:95], v[40:41], v[6:7], v[94:95] op_sel:[0,0,0] op_sel_hi:[0,1,1]
	v_pk_fma_f32 v[96:97], v[40:41], v[8:9], v[96:97] op_sel:[1,0,0] op_sel_hi:[1,1,1]
	v_pk_fma_f32 v[94:95], v[42:43], v[10:11], v[94:95] op_sel:[0,0,0] op_sel_hi:[0,1,1]
	v_pk_fma_f32 v[96:97], v[42:43], v[12:13], v[96:97] op_sel:[1,0,0] op_sel_hi:[1,1,1]
	v_pk_fma_f32 v[94:95], v[44:45], v[14:15], v[94:95] op_sel:[0,0,0] op_sel_hi:[0,1,1]
	v_pk_fma_f32 v[96:97], v[44:45], v[16:17], v[96:97] op_sel:[1,0,0] op_sel_hi:[1,1,1]
	v_pk_mul_f32 v[108:109], v[26:27], v[2:3] op_sel:[0,0] op_sel_hi:[0,1]
	v_pk_add_f32 v[94:95], v[94:95], v[96:97]
	v_pk_mul_f32 v[110:111], v[26:27], v[4:5] op_sel:[1,0] op_sel_hi:[1,1]
	v_pk_fma_f32 v[108:109], v[28:29], v[6:7], v[108:109] op_sel:[0,0,0] op_sel_hi:[0,1,1]
	v_add_f32_dpp v94, v94, v94 quad_perm:[1,0,3,2] row_mask:0xf bank_mask:0xf
	v_add_f32_dpp v95, v95, v95 quad_perm:[1,0,3,2] row_mask:0xf bank_mask:0xf
	v_pk_fma_f32 v[110:111], v[28:29], v[8:9], v[110:111] op_sel:[1,0,0] op_sel_hi:[1,1,1]
	v_add_f32_dpp v94, v94, v94 quad_perm:[2,3,0,1] row_mask:0xf bank_mask:0xf
	v_add_f32_dpp v95, v95, v95 quad_perm:[2,3,0,1] row_mask:0xf bank_mask:0xf
	v_pk_fma_f32 v[108:109], v[30:31], v[10:11], v[108:109] op_sel:[0,0,0] op_sel_hi:[0,1,1]
	v_add_f32_dpp v94, v94, v94 row_half_mirror row_mask:0xf bank_mask:0xf
	v_add_f32_dpp v95, v95, v95 row_half_mirror row_mask:0xf bank_mask:0xf
	v_pk_fma_f32 v[110:111], v[30:31], v[12:13], v[110:111] op_sel:[1,0,0] op_sel_hi:[1,1,1]
	v_add_f32_dpp v94, v94, v94 row_mirror row_mask:0xf bank_mask:0xf
	v_add_f32_dpp v95, v95, v95 row_mirror row_mask:0xf bank_mask:0xf
	v_pk_fma_f32 v[108:109], v[32:33], v[14:15], v[108:109] op_sel:[0,0,0] op_sel_hi:[0,1,1]
	v_pk_fma_f32 v[110:111], v[32:33], v[16:17], v[110:111] op_sel:[1,0,0] op_sel_hi:[1,1,1]
	s_nop 0
	v_pk_add_f32 v[108:109], v[108:109], v[110:111]
	v_pk_fma_f32 v[98:99], v[56:57], v[94:95], v[54:55] op_sel:[1,0,0] op_sel_hi:[1,1,1] neg_lo:[1,0,0] neg_hi:[1,0,0]
	s_nop 0
	v_pk_mul_f32 v[106:107], v[56:57], v[98:99] op_sel:[0,0] op_sel_hi:[0,1]
	ds_write_b64 v102, v[108:109] offset:45056
	ds_read_b128 v[18:21], v100 offset:26400
	ds_read_b128 v[22:25], v100 offset:26416
	ds_read_b128 v[26:29], v100 offset:26928
	ds_read_b128 v[30:33], v100 offset:26944
	ds_read_b64 v[34:35], v101 offset:36992
	ds_read_b64 v[36:37], v117 offset:38088
	v_pk_mul_f32 v[78:79], v[38:39], v[106:107] op_sel:[0,0] op_sel_hi:[0,1]
	v_pk_mul_f32 v[80:81], v[38:39], v[106:107] op_sel:[1,0] op_sel_hi:[1,1]
	v_pk_mul_f32 v[82:83], v[40:41], v[106:107] op_sel:[0,0] op_sel_hi:[0,1]
	v_pk_mul_f32 v[84:85], v[40:41], v[106:107] op_sel:[1,0] op_sel_hi:[1,1]
	v_pk_fma_f32 v[2:3], v[2:3], v[56:57], v[78:79] op_sel:[0,1,0] op_sel_hi:[1,1,1]
	v_pk_fma_f32 v[4:5], v[4:5], v[56:57], v[80:81] op_sel:[0,1,0] op_sel_hi:[1,1,1]
	v_pk_fma_f32 v[6:7], v[6:7], v[56:57], v[82:83] op_sel:[0,1,0] op_sel_hi:[1,1,1]
	v_pk_fma_f32 v[8:9], v[8:9], v[56:57], v[84:85] op_sel:[0,1,0] op_sel_hi:[1,1,1]
	v_pk_mul_f32 v[86:87], v[42:43], v[106:107] op_sel:[0,0] op_sel_hi:[0,1]
	v_pk_mul_f32 v[88:89], v[42:43], v[106:107] op_sel:[1,0] op_sel_hi:[1,1]
	v_pk_mul_f32 v[90:91], v[44:45], v[106:107] op_sel:[0,0] op_sel_hi:[0,1]
	v_pk_mul_f32 v[92:93], v[44:45], v[106:107] op_sel:[1,0] op_sel_hi:[1,1]
	v_pk_fma_f32 v[10:11], v[10:11], v[56:57], v[86:87] op_sel:[0,1,0] op_sel_hi:[1,1,1]
	v_pk_fma_f32 v[12:13], v[12:13], v[56:57], v[88:89] op_sel:[0,1,0] op_sel_hi:[1,1,1]
	v_pk_fma_f32 v[14:15], v[14:15], v[56:57], v[90:91] op_sel:[0,1,0] op_sel_hi:[1,1,1]
	v_pk_fma_f32 v[16:17], v[16:17], v[56:57], v[92:93] op_sel:[0,1,0] op_sel_hi:[1,1,1]
	s_waitcnt lgkmcnt(7)
	v_pk_mul_f32 v[94:95], v[58:59], v[2:3] op_sel:[0,0] op_sel_hi:[0,1]
	v_pk_mul_f32 v[96:97], v[58:59], v[4:5] op_sel:[1,0] op_sel_hi:[1,1]
	v_pk_fma_f32 v[94:95], v[60:61], v[6:7], v[94:95] op_sel:[0,0,0] op_sel_hi:[0,1,1]
	v_pk_fma_f32 v[96:97], v[60:61], v[8:9], v[96:97] op_sel:[1,0,0] op_sel_hi:[1,1,1]
	v_pk_fma_f32 v[94:95], v[62:63], v[10:11], v[94:95] op_sel:[0,0,0] op_sel_hi:[0,1,1]
	v_pk_fma_f32 v[96:97], v[62:63], v[12:13], v[96:97] op_sel:[1,0,0] op_sel_hi:[1,1,1]
	v_pk_fma_f32 v[94:95], v[64:65], v[14:15], v[94:95] op_sel:[0,0,0] op_sel_hi:[0,1,1]
	v_pk_fma_f32 v[96:97], v[64:65], v[16:17], v[96:97] op_sel:[1,0,0] op_sel_hi:[1,1,1]
	v_pk_mul_f32 v[112:113], v[46:47], v[2:3] op_sel:[0,0] op_sel_hi:[0,1]
	v_pk_add_f32 v[94:95], v[94:95], v[96:97]
	v_pk_mul_f32 v[114:115], v[46:47], v[4:5] op_sel:[1,0] op_sel_hi:[1,1]
	v_pk_fma_f32 v[112:113], v[48:49], v[6:7], v[112:113] op_sel:[0,0,0] op_sel_hi:[0,1,1]
	v_add_f32_dpp v94, v94, v94 quad_perm:[1,0,3,2] row_mask:0xf bank_mask:0xf
	v_add_f32_dpp v95, v95, v95 quad_perm:[1,0,3,2] row_mask:0xf bank_mask:0xf
	v_pk_fma_f32 v[114:115], v[48:49], v[8:9], v[114:115] op_sel:[1,0,0] op_sel_hi:[1,1,1]
	v_add_f32_dpp v94, v94, v94 quad_perm:[2,3,0,1] row_mask:0xf bank_mask:0xf
	v_add_f32_dpp v95, v95, v95 quad_perm:[2,3,0,1] row_mask:0xf bank_mask:0xf
	v_pk_fma_f32 v[112:113], v[50:51], v[10:11], v[112:113] op_sel:[0,0,0] op_sel_hi:[0,1,1]
	v_add_f32_dpp v94, v94, v94 row_half_mirror row_mask:0xf bank_mask:0xf
	v_add_f32_dpp v95, v95, v95 row_half_mirror row_mask:0xf bank_mask:0xf
	v_pk_fma_f32 v[114:115], v[50:51], v[12:13], v[114:115] op_sel:[1,0,0] op_sel_hi:[1,1,1]
	v_add_f32_dpp v94, v94, v94 row_mirror row_mask:0xf bank_mask:0xf
	v_add_f32_dpp v95, v95, v95 row_mirror row_mask:0xf bank_mask:0xf
	v_pk_fma_f32 v[112:113], v[52:53], v[14:15], v[112:113] op_sel:[0,0,0] op_sel_hi:[0,1,1]
	v_pk_fma_f32 v[114:115], v[52:53], v[16:17], v[114:115] op_sel:[1,0,0] op_sel_hi:[1,1,1]
	s_nop 0
	v_pk_add_f32 v[112:113], v[112:113], v[114:115]
	v_pk_fma_f32 v[98:99], v[76:77], v[94:95], v[74:75] op_sel:[1,0,0] op_sel_hi:[1,1,1] neg_lo:[1,0,0] neg_hi:[1,0,0]
	s_nop 0
	v_pk_mul_f32 v[106:107], v[76:77], v[98:99] op_sel:[0,0] op_sel_hi:[0,1]
	ds_write_b64 v102, v[112:113] offset:47104
	ds_read_b128 v[38:41], v100 offset:27456
	ds_read_b128 v[42:45], v100 offset:27472
	ds_read_b128 v[46:49], v100 offset:27984
	ds_read_b128 v[50:53], v100 offset:28000
	ds_read_b64 v[54:55], v101 offset:37120
	ds_read_b64 v[56:57], v117 offset:38096
	v_pk_mul_f32 v[78:79], v[58:59], v[106:107] op_sel:[0,0] op_sel_hi:[0,1]
	v_pk_mul_f32 v[80:81], v[58:59], v[106:107] op_sel:[1,0] op_sel_hi:[1,1]
	v_pk_mul_f32 v[82:83], v[60:61], v[106:107] op_sel:[0,0] op_sel_hi:[0,1]
	v_pk_mul_f32 v[84:85], v[60:61], v[106:107] op_sel:[1,0] op_sel_hi:[1,1]
	v_pk_fma_f32 v[2:3], v[2:3], v[76:77], v[78:79] op_sel:[0,1,0] op_sel_hi:[1,1,1]
	v_pk_fma_f32 v[4:5], v[4:5], v[76:77], v[80:81] op_sel:[0,1,0] op_sel_hi:[1,1,1]
	v_pk_fma_f32 v[6:7], v[6:7], v[76:77], v[82:83] op_sel:[0,1,0] op_sel_hi:[1,1,1]
	v_pk_fma_f32 v[8:9], v[8:9], v[76:77], v[84:85] op_sel:[0,1,0] op_sel_hi:[1,1,1]
	v_pk_mul_f32 v[86:87], v[62:63], v[106:107] op_sel:[0,0] op_sel_hi:[0,1]
	v_pk_mul_f32 v[88:89], v[62:63], v[106:107] op_sel:[1,0] op_sel_hi:[1,1]
	v_pk_mul_f32 v[90:91], v[64:65], v[106:107] op_sel:[0,0] op_sel_hi:[0,1]
	v_pk_mul_f32 v[92:93], v[64:65], v[106:107] op_sel:[1,0] op_sel_hi:[1,1]
	v_pk_fma_f32 v[10:11], v[10:11], v[76:77], v[86:87] op_sel:[0,1,0] op_sel_hi:[1,1,1]
	v_pk_fma_f32 v[12:13], v[12:13], v[76:77], v[88:89] op_sel:[0,1,0] op_sel_hi:[1,1,1]
	v_pk_fma_f32 v[14:15], v[14:15], v[76:77], v[90:91] op_sel:[0,1,0] op_sel_hi:[1,1,1]
	v_pk_fma_f32 v[16:17], v[16:17], v[76:77], v[92:93] op_sel:[0,1,0] op_sel_hi:[1,1,1]
	s_waitcnt lgkmcnt(7)
	v_pk_mul_f32 v[94:95], v[18:19], v[2:3] op_sel:[0,0] op_sel_hi:[0,1]
	v_pk_mul_f32 v[96:97], v[18:19], v[4:5] op_sel:[1,0] op_sel_hi:[1,1]
	v_pk_fma_f32 v[94:95], v[20:21], v[6:7], v[94:95] op_sel:[0,0,0] op_sel_hi:[0,1,1]
	v_pk_fma_f32 v[96:97], v[20:21], v[8:9], v[96:97] op_sel:[1,0,0] op_sel_hi:[1,1,1]
	v_pk_fma_f32 v[94:95], v[22:23], v[10:11], v[94:95] op_sel:[0,0,0] op_sel_hi:[0,1,1]
	v_pk_fma_f32 v[96:97], v[22:23], v[12:13], v[96:97] op_sel:[1,0,0] op_sel_hi:[1,1,1]
	v_pk_fma_f32 v[94:95], v[24:25], v[14:15], v[94:95] op_sel:[0,0,0] op_sel_hi:[0,1,1]
	v_pk_fma_f32 v[96:97], v[24:25], v[16:17], v[96:97] op_sel:[1,0,0] op_sel_hi:[1,1,1]
	v_pk_mul_f32 v[108:109], v[66:67], v[2:3] op_sel:[0,0] op_sel_hi:[0,1]
	v_pk_add_f32 v[94:95], v[94:95], v[96:97]
	v_pk_mul_f32 v[110:111], v[66:67], v[4:5] op_sel:[1,0] op_sel_hi:[1,1]
	v_pk_fma_f32 v[108:109], v[68:69], v[6:7], v[108:109] op_sel:[0,0,0] op_sel_hi:[0,1,1]
	v_add_f32_dpp v94, v94, v94 quad_perm:[1,0,3,2] row_mask:0xf bank_mask:0xf
	v_add_f32_dpp v95, v95, v95 quad_perm:[1,0,3,2] row_mask:0xf bank_mask:0xf
	v_pk_fma_f32 v[110:111], v[68:69], v[8:9], v[110:111] op_sel:[1,0,0] op_sel_hi:[1,1,1]
	v_add_f32_dpp v94, v94, v94 quad_perm:[2,3,0,1] row_mask:0xf bank_mask:0xf
	v_add_f32_dpp v95, v95, v95 quad_perm:[2,3,0,1] row_mask:0xf bank_mask:0xf
	v_pk_fma_f32 v[108:109], v[70:71], v[10:11], v[108:109] op_sel:[0,0,0] op_sel_hi:[0,1,1]
	v_add_f32_dpp v94, v94, v94 row_half_mirror row_mask:0xf bank_mask:0xf
	v_add_f32_dpp v95, v95, v95 row_half_mirror row_mask:0xf bank_mask:0xf
	v_pk_fma_f32 v[110:111], v[70:71], v[12:13], v[110:111] op_sel:[1,0,0] op_sel_hi:[1,1,1]
	v_add_f32_dpp v94, v94, v94 row_mirror row_mask:0xf bank_mask:0xf
	v_add_f32_dpp v95, v95, v95 row_mirror row_mask:0xf bank_mask:0xf
	v_pk_fma_f32 v[108:109], v[72:73], v[14:15], v[108:109] op_sel:[0,0,0] op_sel_hi:[0,1,1]
	v_pk_fma_f32 v[110:111], v[72:73], v[16:17], v[110:111] op_sel:[1,0,0] op_sel_hi:[1,1,1]
	s_nop 0
	v_pk_add_f32 v[108:109], v[108:109], v[110:111]
	v_pk_fma_f32 v[98:99], v[36:37], v[94:95], v[34:35] op_sel:[1,0,0] op_sel_hi:[1,1,1] neg_lo:[1,0,0] neg_hi:[1,0,0]
	s_nop 0
	v_pk_mul_f32 v[106:107], v[36:37], v[98:99] op_sel:[0,0] op_sel_hi:[0,1]
	ds_write_b64 v102, v[108:109] offset:49152
	ds_read_b128 v[58:61], v100 offset:28512
	ds_read_b128 v[62:65], v100 offset:28528
	ds_read_b128 v[66:69], v100 offset:29040
	ds_read_b128 v[70:73], v100 offset:29056
	ds_read_b64 v[74:75], v101 offset:37248
	ds_read_b64 v[76:77], v117 offset:38104
	v_pk_mul_f32 v[78:79], v[18:19], v[106:107] op_sel:[0,0] op_sel_hi:[0,1]
	v_pk_mul_f32 v[80:81], v[18:19], v[106:107] op_sel:[1,0] op_sel_hi:[1,1]
	v_pk_mul_f32 v[82:83], v[20:21], v[106:107] op_sel:[0,0] op_sel_hi:[0,1]
	v_pk_mul_f32 v[84:85], v[20:21], v[106:107] op_sel:[1,0] op_sel_hi:[1,1]
	v_pk_fma_f32 v[2:3], v[2:3], v[36:37], v[78:79] op_sel:[0,1,0] op_sel_hi:[1,1,1]
	v_pk_fma_f32 v[4:5], v[4:5], v[36:37], v[80:81] op_sel:[0,1,0] op_sel_hi:[1,1,1]
	v_pk_fma_f32 v[6:7], v[6:7], v[36:37], v[82:83] op_sel:[0,1,0] op_sel_hi:[1,1,1]
	v_pk_fma_f32 v[8:9], v[8:9], v[36:37], v[84:85] op_sel:[0,1,0] op_sel_hi:[1,1,1]
	v_pk_mul_f32 v[86:87], v[22:23], v[106:107] op_sel:[0,0] op_sel_hi:[0,1]
	v_pk_mul_f32 v[88:89], v[22:23], v[106:107] op_sel:[1,0] op_sel_hi:[1,1]
	v_pk_mul_f32 v[90:91], v[24:25], v[106:107] op_sel:[0,0] op_sel_hi:[0,1]
	v_pk_mul_f32 v[92:93], v[24:25], v[106:107] op_sel:[1,0] op_sel_hi:[1,1]
	v_pk_fma_f32 v[10:11], v[10:11], v[36:37], v[86:87] op_sel:[0,1,0] op_sel_hi:[1,1,1]
	v_pk_fma_f32 v[12:13], v[12:13], v[36:37], v[88:89] op_sel:[0,1,0] op_sel_hi:[1,1,1]
	v_pk_fma_f32 v[14:15], v[14:15], v[36:37], v[90:91] op_sel:[0,1,0] op_sel_hi:[1,1,1]
	v_pk_fma_f32 v[16:17], v[16:17], v[36:37], v[92:93] op_sel:[0,1,0] op_sel_hi:[1,1,1]
	s_waitcnt lgkmcnt(7)
	v_pk_mul_f32 v[94:95], v[38:39], v[2:3] op_sel:[0,0] op_sel_hi:[0,1]
	v_pk_mul_f32 v[96:97], v[38:39], v[4:5] op_sel:[1,0] op_sel_hi:[1,1]
	v_pk_fma_f32 v[94:95], v[40:41], v[6:7], v[94:95] op_sel:[0,0,0] op_sel_hi:[0,1,1]
	v_pk_fma_f32 v[96:97], v[40:41], v[8:9], v[96:97] op_sel:[1,0,0] op_sel_hi:[1,1,1]
	v_pk_fma_f32 v[94:95], v[42:43], v[10:11], v[94:95] op_sel:[0,0,0] op_sel_hi:[0,1,1]
	v_pk_fma_f32 v[96:97], v[42:43], v[12:13], v[96:97] op_sel:[1,0,0] op_sel_hi:[1,1,1]
	v_pk_fma_f32 v[94:95], v[44:45], v[14:15], v[94:95] op_sel:[0,0,0] op_sel_hi:[0,1,1]
	v_pk_fma_f32 v[96:97], v[44:45], v[16:17], v[96:97] op_sel:[1,0,0] op_sel_hi:[1,1,1]
	v_pk_mul_f32 v[112:113], v[26:27], v[2:3] op_sel:[0,0] op_sel_hi:[0,1]
	v_pk_add_f32 v[94:95], v[94:95], v[96:97]
	v_pk_mul_f32 v[114:115], v[26:27], v[4:5] op_sel:[1,0] op_sel_hi:[1,1]
	v_pk_fma_f32 v[112:113], v[28:29], v[6:7], v[112:113] op_sel:[0,0,0] op_sel_hi:[0,1,1]
	v_add_f32_dpp v94, v94, v94 quad_perm:[1,0,3,2] row_mask:0xf bank_mask:0xf
	v_add_f32_dpp v95, v95, v95 quad_perm:[1,0,3,2] row_mask:0xf bank_mask:0xf
	v_pk_fma_f32 v[114:115], v[28:29], v[8:9], v[114:115] op_sel:[1,0,0] op_sel_hi:[1,1,1]
	v_add_f32_dpp v94, v94, v94 quad_perm:[2,3,0,1] row_mask:0xf bank_mask:0xf
	v_add_f32_dpp v95, v95, v95 quad_perm:[2,3,0,1] row_mask:0xf bank_mask:0xf
	v_pk_fma_f32 v[112:113], v[30:31], v[10:11], v[112:113] op_sel:[0,0,0] op_sel_hi:[0,1,1]
	v_add_f32_dpp v94, v94, v94 row_half_mirror row_mask:0xf bank_mask:0xf
	v_add_f32_dpp v95, v95, v95 row_half_mirror row_mask:0xf bank_mask:0xf
	v_pk_fma_f32 v[114:115], v[30:31], v[12:13], v[114:115] op_sel:[1,0,0] op_sel_hi:[1,1,1]
	v_add_f32_dpp v94, v94, v94 row_mirror row_mask:0xf bank_mask:0xf
	v_add_f32_dpp v95, v95, v95 row_mirror row_mask:0xf bank_mask:0xf
	v_pk_fma_f32 v[112:113], v[32:33], v[14:15], v[112:113] op_sel:[0,0,0] op_sel_hi:[0,1,1]
	v_pk_fma_f32 v[114:115], v[32:33], v[16:17], v[114:115] op_sel:[1,0,0] op_sel_hi:[1,1,1]
	s_nop 0
	v_pk_add_f32 v[112:113], v[112:113], v[114:115]
	v_pk_fma_f32 v[98:99], v[56:57], v[94:95], v[54:55] op_sel:[1,0,0] op_sel_hi:[1,1,1] neg_lo:[1,0,0] neg_hi:[1,0,0]
	s_nop 0
	v_pk_mul_f32 v[106:107], v[56:57], v[98:99] op_sel:[0,0] op_sel_hi:[0,1]
	ds_write_b64 v102, v[112:113] offset:51200
	ds_read_b128 v[18:21], v100 offset:29568
	ds_read_b128 v[22:25], v100 offset:29584
	ds_read_b128 v[26:29], v100 offset:30096
	ds_read_b128 v[30:33], v100 offset:30112
	ds_read_b64 v[34:35], v101 offset:37376
	ds_read_b64 v[36:37], v117 offset:38112
	v_pk_mul_f32 v[78:79], v[38:39], v[106:107] op_sel:[0,0] op_sel_hi:[0,1]
	v_pk_mul_f32 v[80:81], v[38:39], v[106:107] op_sel:[1,0] op_sel_hi:[1,1]
	v_pk_mul_f32 v[82:83], v[40:41], v[106:107] op_sel:[0,0] op_sel_hi:[0,1]
	v_pk_mul_f32 v[84:85], v[40:41], v[106:107] op_sel:[1,0] op_sel_hi:[1,1]
	v_pk_fma_f32 v[2:3], v[2:3], v[56:57], v[78:79] op_sel:[0,1,0] op_sel_hi:[1,1,1]
	v_pk_fma_f32 v[4:5], v[4:5], v[56:57], v[80:81] op_sel:[0,1,0] op_sel_hi:[1,1,1]
	v_pk_fma_f32 v[6:7], v[6:7], v[56:57], v[82:83] op_sel:[0,1,0] op_sel_hi:[1,1,1]
	v_pk_fma_f32 v[8:9], v[8:9], v[56:57], v[84:85] op_sel:[0,1,0] op_sel_hi:[1,1,1]
	v_pk_mul_f32 v[86:87], v[42:43], v[106:107] op_sel:[0,0] op_sel_hi:[0,1]
	v_pk_mul_f32 v[88:89], v[42:43], v[106:107] op_sel:[1,0] op_sel_hi:[1,1]
	v_pk_mul_f32 v[90:91], v[44:45], v[106:107] op_sel:[0,0] op_sel_hi:[0,1]
	v_pk_mul_f32 v[92:93], v[44:45], v[106:107] op_sel:[1,0] op_sel_hi:[1,1]
	v_pk_fma_f32 v[10:11], v[10:11], v[56:57], v[86:87] op_sel:[0,1,0] op_sel_hi:[1,1,1]
	v_pk_fma_f32 v[12:13], v[12:13], v[56:57], v[88:89] op_sel:[0,1,0] op_sel_hi:[1,1,1]
	v_pk_fma_f32 v[14:15], v[14:15], v[56:57], v[90:91] op_sel:[0,1,0] op_sel_hi:[1,1,1]
	v_pk_fma_f32 v[16:17], v[16:17], v[56:57], v[92:93] op_sel:[0,1,0] op_sel_hi:[1,1,1]
	s_waitcnt lgkmcnt(7)
	v_pk_mul_f32 v[94:95], v[58:59], v[2:3] op_sel:[0,0] op_sel_hi:[0,1]
	v_pk_mul_f32 v[96:97], v[58:59], v[4:5] op_sel:[1,0] op_sel_hi:[1,1]
	v_pk_fma_f32 v[94:95], v[60:61], v[6:7], v[94:95] op_sel:[0,0,0] op_sel_hi:[0,1,1]
	v_pk_fma_f32 v[96:97], v[60:61], v[8:9], v[96:97] op_sel:[1,0,0] op_sel_hi:[1,1,1]
	v_pk_fma_f32 v[94:95], v[62:63], v[10:11], v[94:95] op_sel:[0,0,0] op_sel_hi:[0,1,1]
	v_pk_fma_f32 v[96:97], v[62:63], v[12:13], v[96:97] op_sel:[1,0,0] op_sel_hi:[1,1,1]
	v_pk_fma_f32 v[94:95], v[64:65], v[14:15], v[94:95] op_sel:[0,0,0] op_sel_hi:[0,1,1]
	v_pk_fma_f32 v[96:97], v[64:65], v[16:17], v[96:97] op_sel:[1,0,0] op_sel_hi:[1,1,1]
	v_pk_mul_f32 v[108:109], v[46:47], v[2:3] op_sel:[0,0] op_sel_hi:[0,1]
	v_pk_add_f32 v[94:95], v[94:95], v[96:97]
	v_pk_mul_f32 v[110:111], v[46:47], v[4:5] op_sel:[1,0] op_sel_hi:[1,1]
	v_pk_fma_f32 v[108:109], v[48:49], v[6:7], v[108:109] op_sel:[0,0,0] op_sel_hi:[0,1,1]
	v_add_f32_dpp v94, v94, v94 quad_perm:[1,0,3,2] row_mask:0xf bank_mask:0xf
	v_add_f32_dpp v95, v95, v95 quad_perm:[1,0,3,2] row_mask:0xf bank_mask:0xf
	v_pk_fma_f32 v[110:111], v[48:49], v[8:9], v[110:111] op_sel:[1,0,0] op_sel_hi:[1,1,1]
	v_add_f32_dpp v94, v94, v94 quad_perm:[2,3,0,1] row_mask:0xf bank_mask:0xf
	v_add_f32_dpp v95, v95, v95 quad_perm:[2,3,0,1] row_mask:0xf bank_mask:0xf
	v_pk_fma_f32 v[108:109], v[50:51], v[10:11], v[108:109] op_sel:[0,0,0] op_sel_hi:[0,1,1]
	v_add_f32_dpp v94, v94, v94 row_half_mirror row_mask:0xf bank_mask:0xf
	v_add_f32_dpp v95, v95, v95 row_half_mirror row_mask:0xf bank_mask:0xf
	v_pk_fma_f32 v[110:111], v[50:51], v[12:13], v[110:111] op_sel:[1,0,0] op_sel_hi:[1,1,1]
	v_add_f32_dpp v94, v94, v94 row_mirror row_mask:0xf bank_mask:0xf
	v_add_f32_dpp v95, v95, v95 row_mirror row_mask:0xf bank_mask:0xf
	v_pk_fma_f32 v[108:109], v[52:53], v[14:15], v[108:109] op_sel:[0,0,0] op_sel_hi:[0,1,1]
	v_pk_fma_f32 v[110:111], v[52:53], v[16:17], v[110:111] op_sel:[1,0,0] op_sel_hi:[1,1,1]
	s_nop 0
	v_pk_add_f32 v[108:109], v[108:109], v[110:111]
	v_pk_fma_f32 v[98:99], v[76:77], v[94:95], v[74:75] op_sel:[1,0,0] op_sel_hi:[1,1,1] neg_lo:[1,0,0] neg_hi:[1,0,0]
	s_nop 0
	v_pk_mul_f32 v[106:107], v[76:77], v[98:99] op_sel:[0,0] op_sel_hi:[0,1]
	ds_write_b64 v102, v[108:109] offset:53248
	ds_read_b128 v[38:41], v100 offset:30624
	ds_read_b128 v[42:45], v100 offset:30640
	ds_read_b128 v[46:49], v100 offset:31152
	ds_read_b128 v[50:53], v100 offset:31168
	ds_read_b64 v[54:55], v101 offset:37504
	ds_read_b64 v[56:57], v117 offset:38120
	v_pk_mul_f32 v[78:79], v[58:59], v[106:107] op_sel:[0,0] op_sel_hi:[0,1]
	v_pk_mul_f32 v[80:81], v[58:59], v[106:107] op_sel:[1,0] op_sel_hi:[1,1]
	v_pk_mul_f32 v[82:83], v[60:61], v[106:107] op_sel:[0,0] op_sel_hi:[0,1]
	v_pk_mul_f32 v[84:85], v[60:61], v[106:107] op_sel:[1,0] op_sel_hi:[1,1]
	v_pk_fma_f32 v[2:3], v[2:3], v[76:77], v[78:79] op_sel:[0,1,0] op_sel_hi:[1,1,1]
	v_pk_fma_f32 v[4:5], v[4:5], v[76:77], v[80:81] op_sel:[0,1,0] op_sel_hi:[1,1,1]
	v_pk_fma_f32 v[6:7], v[6:7], v[76:77], v[82:83] op_sel:[0,1,0] op_sel_hi:[1,1,1]
	v_pk_fma_f32 v[8:9], v[8:9], v[76:77], v[84:85] op_sel:[0,1,0] op_sel_hi:[1,1,1]
	v_pk_mul_f32 v[86:87], v[62:63], v[106:107] op_sel:[0,0] op_sel_hi:[0,1]
	v_pk_mul_f32 v[88:89], v[62:63], v[106:107] op_sel:[1,0] op_sel_hi:[1,1]
	v_pk_mul_f32 v[90:91], v[64:65], v[106:107] op_sel:[0,0] op_sel_hi:[0,1]
	v_pk_mul_f32 v[92:93], v[64:65], v[106:107] op_sel:[1,0] op_sel_hi:[1,1]
	v_pk_fma_f32 v[10:11], v[10:11], v[76:77], v[86:87] op_sel:[0,1,0] op_sel_hi:[1,1,1]
	v_pk_fma_f32 v[12:13], v[12:13], v[76:77], v[88:89] op_sel:[0,1,0] op_sel_hi:[1,1,1]
	v_pk_fma_f32 v[14:15], v[14:15], v[76:77], v[90:91] op_sel:[0,1,0] op_sel_hi:[1,1,1]
	v_pk_fma_f32 v[16:17], v[16:17], v[76:77], v[92:93] op_sel:[0,1,0] op_sel_hi:[1,1,1]
	s_waitcnt lgkmcnt(7)
	v_pk_mul_f32 v[94:95], v[18:19], v[2:3] op_sel:[0,0] op_sel_hi:[0,1]
	v_pk_mul_f32 v[96:97], v[18:19], v[4:5] op_sel:[1,0] op_sel_hi:[1,1]
	v_pk_fma_f32 v[94:95], v[20:21], v[6:7], v[94:95] op_sel:[0,0,0] op_sel_hi:[0,1,1]
	v_pk_fma_f32 v[96:97], v[20:21], v[8:9], v[96:97] op_sel:[1,0,0] op_sel_hi:[1,1,1]
	v_pk_fma_f32 v[94:95], v[22:23], v[10:11], v[94:95] op_sel:[0,0,0] op_sel_hi:[0,1,1]
	v_pk_fma_f32 v[96:97], v[22:23], v[12:13], v[96:97] op_sel:[1,0,0] op_sel_hi:[1,1,1]
	v_pk_fma_f32 v[94:95], v[24:25], v[14:15], v[94:95] op_sel:[0,0,0] op_sel_hi:[0,1,1]
	v_pk_fma_f32 v[96:97], v[24:25], v[16:17], v[96:97] op_sel:[1,0,0] op_sel_hi:[1,1,1]
	v_pk_mul_f32 v[112:113], v[66:67], v[2:3] op_sel:[0,0] op_sel_hi:[0,1]
	v_pk_add_f32 v[94:95], v[94:95], v[96:97]
	v_pk_mul_f32 v[114:115], v[66:67], v[4:5] op_sel:[1,0] op_sel_hi:[1,1]
	v_pk_fma_f32 v[112:113], v[68:69], v[6:7], v[112:113] op_sel:[0,0,0] op_sel_hi:[0,1,1]
	v_add_f32_dpp v94, v94, v94 quad_perm:[1,0,3,2] row_mask:0xf bank_mask:0xf
	v_add_f32_dpp v95, v95, v95 quad_perm:[1,0,3,2] row_mask:0xf bank_mask:0xf
	v_pk_fma_f32 v[114:115], v[68:69], v[8:9], v[114:115] op_sel:[1,0,0] op_sel_hi:[1,1,1]
	v_add_f32_dpp v94, v94, v94 quad_perm:[2,3,0,1] row_mask:0xf bank_mask:0xf
	v_add_f32_dpp v95, v95, v95 quad_perm:[2,3,0,1] row_mask:0xf bank_mask:0xf
	v_pk_fma_f32 v[112:113], v[70:71], v[10:11], v[112:113] op_sel:[0,0,0] op_sel_hi:[0,1,1]
	v_add_f32_dpp v94, v94, v94 row_half_mirror row_mask:0xf bank_mask:0xf
	v_add_f32_dpp v95, v95, v95 row_half_mirror row_mask:0xf bank_mask:0xf
	v_pk_fma_f32 v[114:115], v[70:71], v[12:13], v[114:115] op_sel:[1,0,0] op_sel_hi:[1,1,1]
	v_add_f32_dpp v94, v94, v94 row_mirror row_mask:0xf bank_mask:0xf
	v_add_f32_dpp v95, v95, v95 row_mirror row_mask:0xf bank_mask:0xf
	v_pk_fma_f32 v[112:113], v[72:73], v[14:15], v[112:113] op_sel:[0,0,0] op_sel_hi:[0,1,1]
	v_pk_fma_f32 v[114:115], v[72:73], v[16:17], v[114:115] op_sel:[1,0,0] op_sel_hi:[1,1,1]
	s_nop 0
	v_pk_add_f32 v[112:113], v[112:113], v[114:115]
	v_pk_fma_f32 v[98:99], v[36:37], v[94:95], v[34:35] op_sel:[1,0,0] op_sel_hi:[1,1,1] neg_lo:[1,0,0] neg_hi:[1,0,0]
	s_nop 0
	v_pk_mul_f32 v[106:107], v[36:37], v[98:99] op_sel:[0,0] op_sel_hi:[0,1]
	ds_write_b64 v102, v[112:113] offset:55296
	ds_read_b128 v[58:61], v100 offset:31680
	ds_read_b128 v[62:65], v100 offset:31696
	ds_read_b128 v[66:69], v100 offset:32208
	ds_read_b128 v[70:73], v100 offset:32224
	ds_read_b64 v[74:75], v101 offset:37632
	ds_read_b64 v[76:77], v117 offset:38128
	v_pk_mul_f32 v[78:79], v[18:19], v[106:107] op_sel:[0,0] op_sel_hi:[0,1]
	v_pk_mul_f32 v[80:81], v[18:19], v[106:107] op_sel:[1,0] op_sel_hi:[1,1]
	v_pk_mul_f32 v[82:83], v[20:21], v[106:107] op_sel:[0,0] op_sel_hi:[0,1]
	v_pk_mul_f32 v[84:85], v[20:21], v[106:107] op_sel:[1,0] op_sel_hi:[1,1]
	v_pk_fma_f32 v[2:3], v[2:3], v[36:37], v[78:79] op_sel:[0,1,0] op_sel_hi:[1,1,1]
	v_pk_fma_f32 v[4:5], v[4:5], v[36:37], v[80:81] op_sel:[0,1,0] op_sel_hi:[1,1,1]
	v_pk_fma_f32 v[6:7], v[6:7], v[36:37], v[82:83] op_sel:[0,1,0] op_sel_hi:[1,1,1]
	v_pk_fma_f32 v[8:9], v[8:9], v[36:37], v[84:85] op_sel:[0,1,0] op_sel_hi:[1,1,1]
	v_pk_mul_f32 v[86:87], v[22:23], v[106:107] op_sel:[0,0] op_sel_hi:[0,1]
	v_pk_mul_f32 v[88:89], v[22:23], v[106:107] op_sel:[1,0] op_sel_hi:[1,1]
	v_pk_mul_f32 v[90:91], v[24:25], v[106:107] op_sel:[0,0] op_sel_hi:[0,1]
	v_pk_mul_f32 v[92:93], v[24:25], v[106:107] op_sel:[1,0] op_sel_hi:[1,1]
	v_pk_fma_f32 v[10:11], v[10:11], v[36:37], v[86:87] op_sel:[0,1,0] op_sel_hi:[1,1,1]
	v_pk_fma_f32 v[12:13], v[12:13], v[36:37], v[88:89] op_sel:[0,1,0] op_sel_hi:[1,1,1]
	v_pk_fma_f32 v[14:15], v[14:15], v[36:37], v[90:91] op_sel:[0,1,0] op_sel_hi:[1,1,1]
	v_pk_fma_f32 v[16:17], v[16:17], v[36:37], v[92:93] op_sel:[0,1,0] op_sel_hi:[1,1,1]
	s_waitcnt lgkmcnt(7)
	v_pk_mul_f32 v[94:95], v[38:39], v[2:3] op_sel:[0,0] op_sel_hi:[0,1]
	v_pk_mul_f32 v[96:97], v[38:39], v[4:5] op_sel:[1,0] op_sel_hi:[1,1]
	v_pk_fma_f32 v[94:95], v[40:41], v[6:7], v[94:95] op_sel:[0,0,0] op_sel_hi:[0,1,1]
	v_pk_fma_f32 v[96:97], v[40:41], v[8:9], v[96:97] op_sel:[1,0,0] op_sel_hi:[1,1,1]
	v_pk_fma_f32 v[94:95], v[42:43], v[10:11], v[94:95] op_sel:[0,0,0] op_sel_hi:[0,1,1]
	v_pk_fma_f32 v[96:97], v[42:43], v[12:13], v[96:97] op_sel:[1,0,0] op_sel_hi:[1,1,1]
	v_pk_fma_f32 v[94:95], v[44:45], v[14:15], v[94:95] op_sel:[0,0,0] op_sel_hi:[0,1,1]
	v_pk_fma_f32 v[96:97], v[44:45], v[16:17], v[96:97] op_sel:[1,0,0] op_sel_hi:[1,1,1]
	v_pk_mul_f32 v[108:109], v[26:27], v[2:3] op_sel:[0,0] op_sel_hi:[0,1]
	v_pk_add_f32 v[94:95], v[94:95], v[96:97]
	v_pk_mul_f32 v[110:111], v[26:27], v[4:5] op_sel:[1,0] op_sel_hi:[1,1]
	v_pk_fma_f32 v[108:109], v[28:29], v[6:7], v[108:109] op_sel:[0,0,0] op_sel_hi:[0,1,1]
	v_add_f32_dpp v94, v94, v94 quad_perm:[1,0,3,2] row_mask:0xf bank_mask:0xf
	v_add_f32_dpp v95, v95, v95 quad_perm:[1,0,3,2] row_mask:0xf bank_mask:0xf
	v_pk_fma_f32 v[110:111], v[28:29], v[8:9], v[110:111] op_sel:[1,0,0] op_sel_hi:[1,1,1]
	v_add_f32_dpp v94, v94, v94 quad_perm:[2,3,0,1] row_mask:0xf bank_mask:0xf
	v_add_f32_dpp v95, v95, v95 quad_perm:[2,3,0,1] row_mask:0xf bank_mask:0xf
	v_pk_fma_f32 v[108:109], v[30:31], v[10:11], v[108:109] op_sel:[0,0,0] op_sel_hi:[0,1,1]
	v_add_f32_dpp v94, v94, v94 row_half_mirror row_mask:0xf bank_mask:0xf
	v_add_f32_dpp v95, v95, v95 row_half_mirror row_mask:0xf bank_mask:0xf
	v_pk_fma_f32 v[110:111], v[30:31], v[12:13], v[110:111] op_sel:[1,0,0] op_sel_hi:[1,1,1]
	v_add_f32_dpp v94, v94, v94 row_mirror row_mask:0xf bank_mask:0xf
	v_add_f32_dpp v95, v95, v95 row_mirror row_mask:0xf bank_mask:0xf
	v_pk_fma_f32 v[108:109], v[32:33], v[14:15], v[108:109] op_sel:[0,0,0] op_sel_hi:[0,1,1]
	v_pk_fma_f32 v[110:111], v[32:33], v[16:17], v[110:111] op_sel:[1,0,0] op_sel_hi:[1,1,1]
	s_nop 0
	v_pk_add_f32 v[108:109], v[108:109], v[110:111]
	v_pk_fma_f32 v[98:99], v[56:57], v[94:95], v[54:55] op_sel:[1,0,0] op_sel_hi:[1,1,1] neg_lo:[1,0,0] neg_hi:[1,0,0]
	s_nop 0
	v_pk_mul_f32 v[106:107], v[56:57], v[98:99] op_sel:[0,0] op_sel_hi:[0,1]
	ds_write_b64 v102, v[108:109] offset:57344
	ds_read_b128 v[18:21], v100 offset:32736
	ds_read_b128 v[22:25], v100 offset:32752
	ds_read_b128 v[26:29], v100 offset:33264
	ds_read_b128 v[30:33], v100 offset:33280
	ds_read_b64 v[34:35], v101 offset:37760
	ds_read_b64 v[36:37], v117 offset:38136
	v_pk_mul_f32 v[78:79], v[38:39], v[106:107] op_sel:[0,0] op_sel_hi:[0,1]
	v_pk_mul_f32 v[80:81], v[38:39], v[106:107] op_sel:[1,0] op_sel_hi:[1,1]
	v_pk_mul_f32 v[82:83], v[40:41], v[106:107] op_sel:[0,0] op_sel_hi:[0,1]
	v_pk_mul_f32 v[84:85], v[40:41], v[106:107] op_sel:[1,0] op_sel_hi:[1,1]
	v_pk_fma_f32 v[2:3], v[2:3], v[56:57], v[78:79] op_sel:[0,1,0] op_sel_hi:[1,1,1]
	v_pk_fma_f32 v[4:5], v[4:5], v[56:57], v[80:81] op_sel:[0,1,0] op_sel_hi:[1,1,1]
	v_pk_fma_f32 v[6:7], v[6:7], v[56:57], v[82:83] op_sel:[0,1,0] op_sel_hi:[1,1,1]
	v_pk_fma_f32 v[8:9], v[8:9], v[56:57], v[84:85] op_sel:[0,1,0] op_sel_hi:[1,1,1]
	v_pk_mul_f32 v[86:87], v[42:43], v[106:107] op_sel:[0,0] op_sel_hi:[0,1]
	v_pk_mul_f32 v[88:89], v[42:43], v[106:107] op_sel:[1,0] op_sel_hi:[1,1]
	v_pk_mul_f32 v[90:91], v[44:45], v[106:107] op_sel:[0,0] op_sel_hi:[0,1]
	v_pk_mul_f32 v[92:93], v[44:45], v[106:107] op_sel:[1,0] op_sel_hi:[1,1]
	v_pk_fma_f32 v[10:11], v[10:11], v[56:57], v[86:87] op_sel:[0,1,0] op_sel_hi:[1,1,1]
	v_pk_fma_f32 v[12:13], v[12:13], v[56:57], v[88:89] op_sel:[0,1,0] op_sel_hi:[1,1,1]
	v_pk_fma_f32 v[14:15], v[14:15], v[56:57], v[90:91] op_sel:[0,1,0] op_sel_hi:[1,1,1]
	v_pk_fma_f32 v[16:17], v[16:17], v[56:57], v[92:93] op_sel:[0,1,0] op_sel_hi:[1,1,1]
	s_waitcnt lgkmcnt(7)
	v_pk_mul_f32 v[94:95], v[58:59], v[2:3] op_sel:[0,0] op_sel_hi:[0,1]
	v_pk_mul_f32 v[96:97], v[58:59], v[4:5] op_sel:[1,0] op_sel_hi:[1,1]
	v_pk_fma_f32 v[94:95], v[60:61], v[6:7], v[94:95] op_sel:[0,0,0] op_sel_hi:[0,1,1]
	v_pk_fma_f32 v[96:97], v[60:61], v[8:9], v[96:97] op_sel:[1,0,0] op_sel_hi:[1,1,1]
	v_pk_fma_f32 v[94:95], v[62:63], v[10:11], v[94:95] op_sel:[0,0,0] op_sel_hi:[0,1,1]
	v_pk_fma_f32 v[96:97], v[62:63], v[12:13], v[96:97] op_sel:[1,0,0] op_sel_hi:[1,1,1]
	v_pk_fma_f32 v[94:95], v[64:65], v[14:15], v[94:95] op_sel:[0,0,0] op_sel_hi:[0,1,1]
	v_pk_fma_f32 v[96:97], v[64:65], v[16:17], v[96:97] op_sel:[1,0,0] op_sel_hi:[1,1,1]
	v_pk_mul_f32 v[112:113], v[46:47], v[2:3] op_sel:[0,0] op_sel_hi:[0,1]
	v_pk_add_f32 v[94:95], v[94:95], v[96:97]
	v_pk_mul_f32 v[114:115], v[46:47], v[4:5] op_sel:[1,0] op_sel_hi:[1,1]
	v_pk_fma_f32 v[112:113], v[48:49], v[6:7], v[112:113] op_sel:[0,0,0] op_sel_hi:[0,1,1]
	v_add_f32_dpp v94, v94, v94 quad_perm:[1,0,3,2] row_mask:0xf bank_mask:0xf
	v_add_f32_dpp v95, v95, v95 quad_perm:[1,0,3,2] row_mask:0xf bank_mask:0xf
	v_pk_fma_f32 v[114:115], v[48:49], v[8:9], v[114:115] op_sel:[1,0,0] op_sel_hi:[1,1,1]
	v_add_f32_dpp v94, v94, v94 quad_perm:[2,3,0,1] row_mask:0xf bank_mask:0xf
	v_add_f32_dpp v95, v95, v95 quad_perm:[2,3,0,1] row_mask:0xf bank_mask:0xf
	v_pk_fma_f32 v[112:113], v[50:51], v[10:11], v[112:113] op_sel:[0,0,0] op_sel_hi:[0,1,1]
	v_add_f32_dpp v94, v94, v94 row_half_mirror row_mask:0xf bank_mask:0xf
	v_add_f32_dpp v95, v95, v95 row_half_mirror row_mask:0xf bank_mask:0xf
	v_pk_fma_f32 v[114:115], v[50:51], v[12:13], v[114:115] op_sel:[1,0,0] op_sel_hi:[1,1,1]
	v_add_f32_dpp v94, v94, v94 row_mirror row_mask:0xf bank_mask:0xf
	v_add_f32_dpp v95, v95, v95 row_mirror row_mask:0xf bank_mask:0xf
	v_pk_fma_f32 v[112:113], v[52:53], v[14:15], v[112:113] op_sel:[0,0,0] op_sel_hi:[0,1,1]
	v_pk_fma_f32 v[114:115], v[52:53], v[16:17], v[114:115] op_sel:[1,0,0] op_sel_hi:[1,1,1]
	s_nop 0
	v_pk_add_f32 v[112:113], v[112:113], v[114:115]
	v_pk_fma_f32 v[98:99], v[76:77], v[94:95], v[74:75] op_sel:[1,0,0] op_sel_hi:[1,1,1] neg_lo:[1,0,0] neg_hi:[1,0,0]
	s_nop 0
	v_pk_mul_f32 v[106:107], v[76:77], v[98:99] op_sel:[0,0] op_sel_hi:[0,1]
	ds_write_b64 v102, v[112:113] offset:59392
	v_pk_mul_f32 v[78:79], v[58:59], v[106:107] op_sel:[0,0] op_sel_hi:[0,1]
	v_pk_mul_f32 v[80:81], v[58:59], v[106:107] op_sel:[1,0] op_sel_hi:[1,1]
	v_pk_mul_f32 v[82:83], v[60:61], v[106:107] op_sel:[0,0] op_sel_hi:[0,1]
	v_pk_mul_f32 v[84:85], v[60:61], v[106:107] op_sel:[1,0] op_sel_hi:[1,1]
	v_pk_fma_f32 v[2:3], v[2:3], v[76:77], v[78:79] op_sel:[0,1,0] op_sel_hi:[1,1,1]
	v_pk_fma_f32 v[4:5], v[4:5], v[76:77], v[80:81] op_sel:[0,1,0] op_sel_hi:[1,1,1]
	v_pk_fma_f32 v[6:7], v[6:7], v[76:77], v[82:83] op_sel:[0,1,0] op_sel_hi:[1,1,1]
	v_pk_fma_f32 v[8:9], v[8:9], v[76:77], v[84:85] op_sel:[0,1,0] op_sel_hi:[1,1,1]
	v_pk_mul_f32 v[86:87], v[62:63], v[106:107] op_sel:[0,0] op_sel_hi:[0,1]
	v_pk_mul_f32 v[88:89], v[62:63], v[106:107] op_sel:[1,0] op_sel_hi:[1,1]
	v_pk_mul_f32 v[90:91], v[64:65], v[106:107] op_sel:[0,0] op_sel_hi:[0,1]
	v_pk_mul_f32 v[92:93], v[64:65], v[106:107] op_sel:[1,0] op_sel_hi:[1,1]
	v_pk_fma_f32 v[10:11], v[10:11], v[76:77], v[86:87] op_sel:[0,1,0] op_sel_hi:[1,1,1]
	v_pk_fma_f32 v[12:13], v[12:13], v[76:77], v[88:89] op_sel:[0,1,0] op_sel_hi:[1,1,1]
	v_pk_fma_f32 v[14:15], v[14:15], v[76:77], v[90:91] op_sel:[0,1,0] op_sel_hi:[1,1,1]
	v_pk_fma_f32 v[16:17], v[16:17], v[76:77], v[92:93] op_sel:[0,1,0] op_sel_hi:[1,1,1]
	s_waitcnt lgkmcnt(1)
	v_pk_mul_f32 v[94:95], v[18:19], v[2:3] op_sel:[0,0] op_sel_hi:[0,1]
	v_pk_mul_f32 v[96:97], v[18:19], v[4:5] op_sel:[1,0] op_sel_hi:[1,1]
	v_pk_fma_f32 v[94:95], v[20:21], v[6:7], v[94:95] op_sel:[0,0,0] op_sel_hi:[0,1,1]
	v_pk_fma_f32 v[96:97], v[20:21], v[8:9], v[96:97] op_sel:[1,0,0] op_sel_hi:[1,1,1]
	v_pk_fma_f32 v[94:95], v[22:23], v[10:11], v[94:95] op_sel:[0,0,0] op_sel_hi:[0,1,1]
	v_pk_fma_f32 v[96:97], v[22:23], v[12:13], v[96:97] op_sel:[1,0,0] op_sel_hi:[1,1,1]
	v_pk_fma_f32 v[94:95], v[24:25], v[14:15], v[94:95] op_sel:[0,0,0] op_sel_hi:[0,1,1]
	v_pk_fma_f32 v[96:97], v[24:25], v[16:17], v[96:97] op_sel:[1,0,0] op_sel_hi:[1,1,1]
	v_pk_mul_f32 v[108:109], v[66:67], v[2:3] op_sel:[0,0] op_sel_hi:[0,1]
	v_pk_add_f32 v[94:95], v[94:95], v[96:97]
	v_pk_mul_f32 v[110:111], v[66:67], v[4:5] op_sel:[1,0] op_sel_hi:[1,1]
	v_pk_fma_f32 v[108:109], v[68:69], v[6:7], v[108:109] op_sel:[0,0,0] op_sel_hi:[0,1,1]
	v_add_f32_dpp v94, v94, v94 quad_perm:[1,0,3,2] row_mask:0xf bank_mask:0xf
	v_add_f32_dpp v95, v95, v95 quad_perm:[1,0,3,2] row_mask:0xf bank_mask:0xf
	v_pk_fma_f32 v[110:111], v[68:69], v[8:9], v[110:111] op_sel:[1,0,0] op_sel_hi:[1,1,1]
	v_add_f32_dpp v94, v94, v94 quad_perm:[2,3,0,1] row_mask:0xf bank_mask:0xf
	v_add_f32_dpp v95, v95, v95 quad_perm:[2,3,0,1] row_mask:0xf bank_mask:0xf
	v_pk_fma_f32 v[108:109], v[70:71], v[10:11], v[108:109] op_sel:[0,0,0] op_sel_hi:[0,1,1]
	v_add_f32_dpp v94, v94, v94 row_half_mirror row_mask:0xf bank_mask:0xf
	v_add_f32_dpp v95, v95, v95 row_half_mirror row_mask:0xf bank_mask:0xf
	v_pk_fma_f32 v[110:111], v[70:71], v[12:13], v[110:111] op_sel:[1,0,0] op_sel_hi:[1,1,1]
	v_add_f32_dpp v94, v94, v94 row_mirror row_mask:0xf bank_mask:0xf
	v_add_f32_dpp v95, v95, v95 row_mirror row_mask:0xf bank_mask:0xf
	v_pk_fma_f32 v[108:109], v[72:73], v[14:15], v[108:109] op_sel:[0,0,0] op_sel_hi:[0,1,1]
	v_pk_fma_f32 v[110:111], v[72:73], v[16:17], v[110:111] op_sel:[1,0,0] op_sel_hi:[1,1,1]
	s_nop 0
	v_pk_add_f32 v[108:109], v[108:109], v[110:111]
	v_pk_fma_f32 v[98:99], v[36:37], v[94:95], v[34:35] op_sel:[1,0,0] op_sel_hi:[1,1,1] neg_lo:[1,0,0] neg_hi:[1,0,0]
	s_nop 0
	v_pk_mul_f32 v[106:107], v[36:37], v[98:99] op_sel:[0,0] op_sel_hi:[0,1]
	ds_write_b64 v102, v[108:109] offset:61440
	v_pk_mul_f32 v[78:79], v[18:19], v[106:107] op_sel:[0,0] op_sel_hi:[0,1]
	v_pk_mul_f32 v[80:81], v[18:19], v[106:107] op_sel:[1,0] op_sel_hi:[1,1]
	v_pk_mul_f32 v[82:83], v[20:21], v[106:107] op_sel:[0,0] op_sel_hi:[0,1]
	v_pk_mul_f32 v[84:85], v[20:21], v[106:107] op_sel:[1,0] op_sel_hi:[1,1]
	v_pk_fma_f32 v[2:3], v[2:3], v[36:37], v[78:79] op_sel:[0,1,0] op_sel_hi:[1,1,1]
	v_pk_fma_f32 v[4:5], v[4:5], v[36:37], v[80:81] op_sel:[0,1,0] op_sel_hi:[1,1,1]
	v_pk_fma_f32 v[6:7], v[6:7], v[36:37], v[82:83] op_sel:[0,1,0] op_sel_hi:[1,1,1]
	v_pk_fma_f32 v[8:9], v[8:9], v[36:37], v[84:85] op_sel:[0,1,0] op_sel_hi:[1,1,1]
	v_pk_mul_f32 v[86:87], v[22:23], v[106:107] op_sel:[0,0] op_sel_hi:[0,1]
	v_pk_mul_f32 v[88:89], v[22:23], v[106:107] op_sel:[1,0] op_sel_hi:[1,1]
	v_pk_mul_f32 v[90:91], v[24:25], v[106:107] op_sel:[0,0] op_sel_hi:[0,1]
	v_pk_mul_f32 v[92:93], v[24:25], v[106:107] op_sel:[1,0] op_sel_hi:[1,1]
	v_pk_fma_f32 v[10:11], v[10:11], v[36:37], v[86:87] op_sel:[0,1,0] op_sel_hi:[1,1,1]
	v_pk_fma_f32 v[12:13], v[12:13], v[36:37], v[88:89] op_sel:[0,1,0] op_sel_hi:[1,1,1]
	v_pk_fma_f32 v[14:15], v[14:15], v[36:37], v[90:91] op_sel:[0,1,0] op_sel_hi:[1,1,1]
	v_pk_fma_f32 v[16:17], v[16:17], v[36:37], v[92:93] op_sel:[0,1,0] op_sel_hi:[1,1,1]
	v_pk_mul_f32 v[112:113], v[26:27], v[2:3] op_sel:[0,0] op_sel_hi:[0,1]
	v_pk_mul_f32 v[114:115], v[26:27], v[4:5] op_sel:[1,0] op_sel_hi:[1,1]
	v_pk_fma_f32 v[112:113], v[28:29], v[6:7], v[112:113] op_sel:[0,0,0] op_sel_hi:[0,1,1]
	v_pk_fma_f32 v[114:115], v[28:29], v[8:9], v[114:115] op_sel:[1,0,0] op_sel_hi:[1,1,1]
	v_pk_fma_f32 v[112:113], v[30:31], v[10:11], v[112:113] op_sel:[0,0,0] op_sel_hi:[0,1,1]
	v_pk_fma_f32 v[114:115], v[30:31], v[12:13], v[114:115] op_sel:[1,0,0] op_sel_hi:[1,1,1]
	v_pk_fma_f32 v[112:113], v[32:33], v[14:15], v[112:113] op_sel:[0,0,0] op_sel_hi:[0,1,1]
	v_pk_fma_f32 v[114:115], v[32:33], v[16:17], v[114:115] op_sel:[1,0,0] op_sel_hi:[1,1,1]
	s_nop 0
	v_pk_add_f32 v[112:113], v[112:113], v[114:115]
	s_nop 0
	ds_write_b64 v102, v[112:113] offset:63488
	s_waitcnt lgkmcnt(0)
	s_barrier
	s_add_i32 s16, s16, 2
	s_cmp_lt_u32 s16, 0x100
	s_cbranch_scc1 .Lgc_loop
	ds_read_b128 v[58:61], v103 offset:32768
	v_xor_b32_e32 v116, 16, v103
	ds_read_b128 v[62:65], v116 offset:32768
	v_xor_b32_e32 v116, 32, v103
	ds_read_b128 v[66:69], v116 offset:32768
	v_xor_b32_e32 v116, 48, v103
	ds_read_b128 v[70:73], v116 offset:32768
	v_xor_b32_e32 v116, 64, v103
	ds_read_b128 v[74:77], v116 offset:32768
	v_xor_b32_e32 v116, 80, v103
	ds_read_b128 v[78:81], v116 offset:32768
	v_xor_b32_e32 v116, 96, v103
	ds_read_b128 v[82:85], v116 offset:32768
	v_xor_b32_e32 v116, 112, v103
	ds_read_b128 v[86:89], v116 offset:32768
	s_waitcnt lgkmcnt(0)
	v_pk_add_f32 v[58:59], v[58:59], v[60:61]
	v_pk_add_f32 v[62:63], v[62:63], v[64:65]
	v_pk_add_f32 v[66:67], v[66:67], v[68:69]
	v_pk_add_f32 v[70:71], v[70:71], v[72:73]
	v_pk_add_f32 v[74:75], v[74:75], v[76:77]
	v_pk_add_f32 v[78:79], v[78:79], v[80:81]
	v_pk_add_f32 v[82:83], v[82:83], v[84:85]
	v_pk_add_f32 v[86:87], v[86:87], v[88:89]
	v_pk_add_f32 v[58:59], v[58:59], v[62:63]
	v_pk_add_f32 v[66:67], v[66:67], v[70:71]
	v_pk_add_f32 v[74:75], v[74:75], v[78:79]
	v_pk_add_f32 v[82:83], v[82:83], v[86:87]
	v_pk_add_f32 v[58:59], v[58:59], v[66:67]
	v_pk_add_f32 v[74:75], v[74:75], v[82:83]
	s_nop 0
	v_pk_add_f32 v[58:59], v[58:59], v[74:75]
	s_nop 0
	v_cvt_pk_bf16_f32 v90, v58, v59
	global_store_dword v[104:105], v90, off
	v_lshl_add_u64 v[104:105], v[104:105], 0, s[52:53]
	s_waitcnt vmcnt(0) lgkmcnt(0)
	s_setprio 0
